# RG-LRU softplus hoist: -8*log1p(exp(-lambda)) chain computed once per workgroup (first unit, wave w -> sub-block w&3), parked in free LDS, read back by the 16 sub-block sections instead of recomputing
# speedup vs baseline: 1.0111x; 1.0111x over previous
.LBB0_241:
	s_and_b32 s4, s2, 1
	s_bfe_u32 s72, s2, 0x30001
	s_ashr_i32 s57, s2, 4
	s_ashr_i32 s59, s34, 4
	s_cmp_lt_i32 s57, 64
	s_cselect_b64 s[0:1], -1, 0
	v_cndmask_b32_e64 v0, 0, 1, s[0:1]
	s_mov_b32 s97, s19
	s_mov_b64 s[18:19], s[10:11]
	v_readlane_b32 s10, v250, 1
	s_cmp_eq_u32 s4, 0
	s_mov_b64 s[4:5], -1
	v_cmp_ne_u32_e64 s[0:1], 1, v0
	v_readlane_b32 s11, v250, 2
	s_cbranch_scc1 .LBB0_297
	s_and_b64 vcc, exec, s[0:1]
	s_cbranch_vccnz .LBB0_296
	s_lshl_b32 s73, s72, 7
	s_add_i32 s75, s73, 0xfffffe00
	s_or_b32 s76, s73, 0x400
	s_lshl_b32 s4, s72, 16
	s_add_u32 s4, s52, s4
	s_addc_u32 s5, s53, 0
	s_add_u32 s22, s4, 0x1c80000
	s_addc_u32 s23, s5, 0
	s_lshl_b32 s4, s72, 9
	s_add_u32 s4, s52, s4
	s_addc_u32 s5, s53, 0
	s_add_u32 s24, s4, 0x17000000
	s_addc_u32 s25, s5, 0
	s_add_u32 s30, s52, 0x1e00000
	v_mbcnt_lo_u32_b32 v0, -1, 0
	s_mov_b32 s21, 0
	s_addc_u32 s31, s53, 0
	s_mov_b32 s77, s75
	s_mov_b64 s[4:5], -1
	v_mov_b32_e32 v89, 0
	s_movk_i32 s78, 0x200
	s_movk_i32 s79, 0x280
	s_movk_i32 s80, 0x7f
	s_movk_i32 s81, 0x1ff
	s_add_i32 s82, 16, 0x2000
	s_movk_i32 s83, 0xfc00
	s_movk_i32 s84, 0x4000
	s_movk_i32 s85, 0x2400
	s_mov_b64 s[38:39], 0x6001400
	s_mov_b32 s86, 0x6001000
	v_mbcnt_hi_u32_b32 v126, -1, v0
	s_mov_b32 s87, 0x5040100
	s_mov_b32 s88, 0x3f2aaaab
	v_mov_b32_e32 v127, 0x3ecc95a3
	s_mov_b32 s89, 0x3f317218
	s_mov_b32 s90, 0x7f800000
	s_mov_b32 s91, 0x33800000
	s_add_i32 s92, 16, 0x700
	s_add_i32 s93, 16, 0xf00
	s_mov_b64 s[48:49], 0x80
	s_add_i32 s94, 16, 0x1700
	s_mov_b64 s[60:61], 0x100
	s_add_i32 s95, 16, 0x1f00
	s_mov_b64 s[62:63], 0x180
	v_mov_b32_e32 v128, 0x3f80
	v_mov_b32_e32 v129, 0x1000
	v_mov_b32_e32 v130, 0x7f800000
	v_mov_b32_e32 v131, 0x7fc00000
	v_mov_b32_e32 v132, 0xff800000
	v_mov_b32_e32 v133, 0x1080
	v_mov_b32_e32 v134, 0x1100
	v_mov_b32_e32 v135, 0x1180
	s_mov_b32 s96, s57
	v_and_b32_e32 v167, 31, v177
	v_lshrrev_b32_e32 v136, 6, v177
	v_and_b32_e32 v136, 3, v136
	v_lshlrev_b32_e32 v136, 7, v136
	v_lshl_or_b32 v136, v167, 2, v136
	v_lshlrev_b32_e32 v167, 2, v167
	v_add_u32_e32 v167, 0x14100, v167
	v_lshl_add_u32 v137, s73, 2, v136
	v_or_b32_e32 v137, 0x1000, v137
	global_load_dword v149, v137, s[42:43]
	v_add_u32_e32 v136, 0x14100, v136
	s_branch .LBB0_245

.LBB0_245:
	v_mov_b32_e32 v90, v177
	s_andn2_b64 vcc, exec, s[4:5]
	v_readfirstlane_b32 s20, v90
	s_waitcnt vmcnt(4)
	v_lshlrev_b32_e32 v8, 4, v90
	s_barrier
	s_cbranch_vccnz .LBB0_264
	s_waitcnt vmcnt(0)
	v_mul_f32_e32 v149, 0xbfb8aa3b, v149
	v_exp_f32_e32 v149, v149
	s_nop 0
	v_add_f32_e32 v152, 1.0, v149
	v_add_f32_e32 v153, -1.0, v152
	v_frexp_mant_f32_e32 v154, v152
	v_cvt_f64_f32_e32 v[16:17], v152
	v_sub_f32_e32 v155, v153, v152
	v_frexp_exp_i32_f64_e32 v16, v[16:17]
	v_cmp_gt_f32_e32 vcc, s88, v154
	v_sub_f32_e32 v153, v149, v153
	v_add_f32_e32 v150, 1.0, v155
	v_subbrev_co_u32_e32 v16, vcc, 0, v16, vcc
	v_add_f32_e32 v150, v153, v150
	v_sub_u32_e32 v153, 0, v16
	v_cvt_f32_i32_e32 v16, v16
	v_ldexp_f32 v152, v152, v153
	v_ldexp_f32 v150, v150, v153
	v_add_f32_e32 v153, -1.0, v152
	v_add_f32_e32 v154, 1.0, v152
	v_add_f32_e32 v155, 1.0, v153
	v_add_f32_e32 v156, -1.0, v154
	v_sub_f32_e32 v155, v152, v155
	v_sub_f32_e32 v152, v152, v156
	v_mul_f32_e32 v156, 0x3f317218, v16
	v_add_f32_e32 v155, v150, v155
	v_add_f32_e32 v150, v150, v152
	v_fma_f32 v152, v16, s89, -v156
	v_add_f32_e32 v157, v153, v155
	v_add_f32_e32 v158, v154, v150
	v_fmac_f32_e32 v152, 0xb102e308, v16
	v_sub_f32_e32 v16, v157, v153
	v_sub_f32_e32 v153, v158, v154
	v_rcp_f32_e32 v154, v158
	v_add_f32_e32 v159, v156, v152
	v_sub_f32_e32 v150, v150, v153
	v_sub_f32_e32 v153, v159, v156
	v_sub_f32_e32 v152, v152, v153
	v_mul_f32_e32 v153, v157, v154
	v_sub_f32_e32 v16, v155, v16
	v_mul_f32_e32 v155, v158, v153
	v_fma_f32 v156, v153, v158, -v155
	v_fmac_f32_e32 v156, v153, v150
	v_add_f32_e32 v160, v155, v156
	v_sub_f32_e32 v161, v157, v160
	v_sub_f32_e32 v155, v160, v155
	v_sub_f32_e32 v157, v157, v161
	v_sub_f32_e32 v155, v155, v156
	v_sub_f32_e32 v156, v157, v160
	v_add_f32_e32 v16, v16, v156
	v_add_f32_e32 v16, v155, v16
	v_add_f32_e32 v155, v161, v16
	v_mul_f32_e32 v156, v154, v155
	v_sub_f32_e32 v157, v161, v155
	v_mul_f32_e32 v160, v158, v156
	v_add_f32_e32 v16, v16, v157
	v_add_f32_e32 v157, v153, v156
	v_fma_f32 v158, v156, v158, -v160
	v_sub_f32_e32 v153, v157, v153
	v_fmac_f32_e32 v158, v156, v150
	v_sub_f32_e32 v150, v156, v153
	v_add_f32_e32 v153, v160, v158
	v_sub_f32_e32 v156, v153, v160
	v_sub_f32_e32 v160, v155, v153
	v_sub_f32_e32 v155, v155, v160
	v_sub_f32_e32 v153, v155, v153
	v_sub_f32_e32 v156, v156, v158
	v_add_f32_e32 v16, v16, v153
	v_add_f32_e32 v16, v156, v16
	v_add_f32_e32 v16, v160, v16
	v_mul_f32_e32 v16, v154, v16
	v_add_f32_e32 v16, v150, v16
	v_add_f32_e32 v150, v157, v16
	v_mul_f32_e32 v153, v150, v150
	v_fmamk_f32 v156, v153, 0x3e9b6dac, v127
	v_sub_f32_e32 v154, v150, v157
	v_ldexp_f32 v155, v150, 1
	v_mul_f32_e32 v150, v150, v153
	v_fmaak_f32 v153, v153, v156, 0x3f2aaada
	v_mul_f32_e32 v150, v150, v153
	v_add_f32_e32 v153, v155, v150
	v_sub_f32_e32 v16, v16, v154
	v_sub_f32_e32 v154, v153, v155
	v_ldexp_f32 v16, v16, 1
	v_sub_f32_e32 v150, v150, v154
	v_add_f32_e32 v16, v16, v150
	v_add_f32_e32 v150, v153, v16
	v_sub_f32_e32 v153, v150, v153
	v_add_f32_e32 v154, v159, v150
	v_sub_f32_e32 v16, v16, v153
	v_sub_f32_e32 v153, v154, v159
	v_sub_f32_e32 v155, v154, v153
	v_sub_f32_e32 v150, v150, v153
	v_add_f32_e32 v153, v152, v16
	v_sub_f32_e32 v155, v159, v155
	v_sub_f32_e32 v156, v153, v152
	v_add_f32_e32 v150, v150, v155
	v_sub_f32_e32 v155, v153, v156
	v_sub_f32_e32 v16, v16, v156
	v_sub_f32_e32 v152, v152, v155
	v_add_f32_e32 v150, v153, v150
	v_add_f32_e32 v16, v16, v152
	v_add_f32_e32 v152, v154, v150
	v_sub_f32_e32 v153, v152, v154
	v_sub_f32_e32 v150, v150, v153
	v_add_f32_e32 v16, v16, v150
	v_add_f32_e32 v16, v152, v16
	v_cmp_neq_f32_e32 vcc, s90, v149
	v_cndmask_b32_e32 v16, v130, v16, vcc
	v_cmp_ngt_f32_e32 vcc, -1.0, v149
	v_cndmask_b32_e32 v16, v131, v16, vcc
	v_cmp_neq_f32_e32 vcc, -1.0, v149
	v_cndmask_b32_e32 v16, v132, v16, vcc
	v_cmp_lt_f32_e64 vcc, |v149|, s91
	v_cndmask_b32_e32 v16, v16, v149, vcc
	v_mul_f32_e32 v149, 0xc1000000, v16
	ds_write_b32 v136, v149
	v_add_u32_e32 v91, 0x200, v90
	v_add_u32_e32 v10, 0x400, v90
	v_add_u32_e32 v12, 0x600, v90
	v_add_u32_e32 v18, 0x800, v90
	v_add_u32_e32 v20, 0xa00, v90
	v_add_u32_e32 v28, 0xc00, v90
	v_add_u32_e32 v30, 0xe00, v90
	v_ashrrev_i32_e32 v9, 4, v90
	s_waitcnt vmcnt(3)
	v_ashrrev_i32_e32 v34, 4, v91
	v_ashrrev_i32_e32 v35, 4, v10
	v_ashrrev_i32_e32 v36, 4, v12
	v_ashrrev_i32_e32 v37, 4, v18
	v_ashrrev_i32_e32 v38, 4, v20
	v_ashrrev_i32_e32 v39, 4, v28
	v_ashrrev_i32_e32 v40, 4, v30
	v_and_b32_e32 v88, 0xf0, v8
	v_lshlrev_b32_e32 v0, 7, v9
	v_lshlrev_b32_e32 v2, 7, v34
	v_lshlrev_b32_e32 v10, 7, v35
	v_lshlrev_b32_e32 v12, 7, v36
	v_lshlrev_b32_e32 v18, 7, v37
	v_lshlrev_b32_e32 v20, 7, v38
	v_lshlrev_b32_e32 v28, 7, v39
	v_lshlrev_b32_e32 v30, 7, v40
	v_lshl_add_u64 v[26:27], s[22:23], 0, v[88:89]
	v_ashrrev_i32_e32 v1, 31, v0
	v_ashrrev_i32_e32 v3, 31, v2
	v_ashrrev_i32_e32 v11, 31, v10
	v_ashrrev_i32_e32 v13, 31, v12
	v_ashrrev_i32_e32 v19, 31, v18
	v_ashrrev_i32_e32 v21, 31, v20
	v_ashrrev_i32_e32 v29, 31, v28
	v_ashrrev_i32_e32 v31, 31, v30
	v_lshl_add_u64 v[0:1], v[0:1], 1, v[26:27]
	v_lshl_add_u64 v[4:5], v[2:3], 1, v[26:27]
	v_lshl_add_u64 v[10:11], v[10:11], 1, v[26:27]
	v_lshl_add_u64 v[14:15], v[12:13], 1, v[26:27]
	v_lshl_add_u64 v[18:19], v[18:19], 1, v[26:27]
	v_lshl_add_u64 v[22:23], v[20:21], 1, v[26:27]
	v_lshl_add_u64 v[28:29], v[28:29], 1, v[26:27]
	v_lshl_add_u64 v[30:31], v[30:31], 1, v[26:27]
	global_load_dwordx4 v[0:3], v[0:1], off
	s_nop 0
	global_load_dwordx4 v[4:7], v[4:5], off
	s_nop 0
	global_load_dwordx4 v[10:13], v[10:11], off
	s_nop 0
	global_load_dwordx4 v[14:17], v[14:15], off
	s_nop 0
	global_load_dwordx4 v[18:21], v[18:19], off
	s_nop 0
	global_load_dwordx4 v[22:25], v[22:23], off
	s_nop 0
	global_load_dwordx4 v[26:29], v[28:29], off
	s_nop 0
	global_load_dwordx4 v[30:33], v[30:31], off
	v_and_b32_e32 v41, 0x70, v90
	v_xad_u32 v41, v88, v41, 16
	v_lshl_add_u32 v9, v9, 8, v41
	v_cmp_gt_i32_e32 vcc, s79, v90
	v_lshl_add_u32 v34, v34, 8, v41
	v_lshl_add_u32 v35, v35, 8, v41
	v_lshl_add_u32 v36, v36, 8, v41
	v_lshl_add_u32 v37, v37, 8, v41
	v_lshl_add_u32 v38, v38, 8, v41
	v_lshl_add_u32 v39, v39, 8, v41
	v_lshl_add_u32 v40, v40, 8, v41
	s_waitcnt vmcnt(7)
	ds_write_b128 v9, v[0:3] offset:16384
	s_waitcnt vmcnt(6)
	ds_write_b128 v34, v[4:7] offset:16384
	s_waitcnt vmcnt(5)
	ds_write_b128 v35, v[10:13] offset:16384
	s_waitcnt vmcnt(4)
	ds_write_b128 v36, v[14:17] offset:16384
	s_waitcnt vmcnt(3)
	ds_write_b128 v37, v[18:21] offset:16384
	s_waitcnt vmcnt(2)
	ds_write_b128 v38, v[22:25] offset:16384
	s_waitcnt vmcnt(1)
	ds_write_b128 v39, v[26:29] offset:16384
	s_waitcnt vmcnt(0)
	ds_write_b128 v40, v[30:33] offset:16384
	s_and_saveexec_b64 s[64:65], vcc
	s_cbranch_execz .LBB0_263
	v_max_i32_e32 v0, 0x80, v90
	v_sub_u32_e32 v0, v0, v90
	v_add_u32_e32 v1, 0x1ff, v0
	v_and_b32_e32 v4, 0x7f, v90
	v_cmp_lt_u32_e32 vcc, s81, v1
	s_mov_b64 s[4:5], -1
	v_mov_b32_e32 v0, v90
	s_and_saveexec_b64 s[66:67], vcc
	s_cbranch_execz .LBB0_256
	v_lshrrev_b32_e32 v5, 9, v1
	v_add_u32_e32 v0, -1, v5
	v_lshrrev_b32_e32 v1, 1, v0
	v_add_u32_e32 v6, 1, v1
	v_cmp_lt_u32_e32 vcc, 5, v0
	v_mov_b32_e32 v10, 0
	v_or_b32_e32 v0, s73, v4
	v_mov_b64_e32 v[2:3], v[90:91]
	s_and_saveexec_b64 s[68:69], vcc
	s_cbranch_execz .LBB0_252
	v_and_b32_e32 v7, -4, v6
	v_mov_b32_e32 v1, v0
	v_lshl_add_u32 v9, v90, 2, s82
	s_mov_b32 s33, 0
	s_mov_b64 s[70:71], 0
	v_mov_b64_e32 v[2:3], v[90:91]

.LBB0_264:
	s_and_b32 s65, s96, 63
	s_ashr_i32 s64, s20, 6
	s_lshl_b32 s4, s65, 8
	s_lshl_b32 s5, s64, 5
	v_and_b32_e32 v93, 31, v90
	s_add_i32 s12, s5, s4
	v_or_b32_e32 v9, s12, v93
	v_add_u32_e32 v0, -2, v9
	v_cmp_gt_u32_e32 vcc, s84, v0
	v_bfe_u32 v92, v90, 5, 1
	s_lshl_b32 s20, s73, 1
	v_cndmask_b32_e32 v2, v9, v0, vcc
	v_mov_b64_e32 v[0:1], s[52:53]
	v_mad_i64_i32 v[2:3], s[4:5], v2, s85, v[0:1]
	v_lshl_add_u64 v[2:3], v[2:3], 0, s[20:21]
	v_lshlrev_b32_e32 v88, 4, v92
	v_lshl_add_u64 v[4:5], v[2:3], 0, v[88:89]
	v_add_co_u32_e64 v2, s[4:5], s86, v4
	s_waitcnt lgkmcnt(0)
	s_nop 0
	v_addc_co_u32_e64 v3, s[4:5], 0, v5, s[4:5]
	s_barrier
	global_load_dwordx4 v[10:13], v[2:3], off offset:1024
	global_load_dwordx4 v[178:181], v[2:3], off offset:1056
	global_load_dwordx4 v[194:197], v[2:3], off offset:1088
	global_load_dwordx4 v[210:213], v[2:3], off offset:1120
	global_load_dwordx4 v[226:229], v[2:3], off offset:1152
	global_load_dwordx4 v[242:245], v[2:3], off offset:1184
	v_add_u32_e32 v2, -1, v9
	v_cmp_gt_u32_e64 s[4:5], s84, v2
	v_add_u32_e32 v18, 1, v9
	s_cmpk_lt_u32 s12, 0x4000
	v_cndmask_b32_e64 v2, v9, v2, s[4:5]
	v_mad_i64_i32 v[2:3], s[6:7], v2, s85, v[0:1]
	v_lshl_add_u64 v[2:3], v[2:3], 0, s[20:21]
	v_lshl_add_u64 v[2:3], v[2:3], 0, v[88:89]
	v_add_co_u32_e64 v6, s[6:7], s86, v2
	v_lshlrev_b32_e32 v91, 8, v93
	s_nop 0
	v_addc_co_u32_e64 v7, s[6:7], 0, v3, s[6:7]
	global_load_dwordx4 v[14:17], v[6:7], off offset:1024
	global_load_dwordx4 v[182:185], v[6:7], off offset:1056
	global_load_dwordx4 v[198:201], v[6:7], off offset:1088
	global_load_dwordx4 v[214:217], v[6:7], off offset:1120
	global_load_dwordx4 v[230:233], v[6:7], off offset:1152
	global_load_dwordx4 v[246:249], v[6:7], off offset:1184
	v_mad_i64_i32 v[6:7], s[6:7], v9, s85, v[0:1]
	v_cmp_gt_u32_e64 s[6:7], s84, v18
	v_lshl_add_u64 v[6:7], v[6:7], 0, s[20:21]
	v_lshl_add_u64 v[52:53], v[6:7], 0, v[88:89]
	v_cndmask_b32_e64 v9, v9, v18, s[6:7]
	v_mad_i64_i32 v[0:1], s[8:9], v9, s85, v[0:1]
	v_add_co_u32_e64 v6, s[8:9], s86, v52
	v_lshl_add_u64 v[0:1], v[0:1], 0, s[20:21]
	s_nop 0
	v_addc_co_u32_e64 v7, s[8:9], 0, v53, s[8:9]
	global_load_dwordx4 v[18:21], v[6:7], off offset:1024
	global_load_dwordx4 v[186:189], v[6:7], off offset:1056
	global_load_dwordx4 v[202:205], v[6:7], off offset:1088
	global_load_dwordx4 v[218:221], v[6:7], off offset:1120
	global_load_dwordx4 v[234:237], v[6:7], off offset:1152
	global_load_dwordx4 v[252:255], v[6:7], off offset:1184
	v_lshl_add_u64 v[6:7], v[0:1], 0, v[88:89]
	v_add_co_u32_e64 v0, s[8:9], s86, v6
	v_lshl_add_u32 v9, v92, 5, 16
	s_nop 0
	v_addc_co_u32_e64 v1, s[8:9], 0, v7, s[8:9]
	global_load_dwordx4 v[22:25], v[0:1], off offset:1024
	global_load_dwordx4 v[190:193], v[0:1], off offset:1056
	global_load_dwordx4 v[206:209], v[0:1], off offset:1088
	global_load_dwordx4 v[222:225], v[0:1], off offset:1120
	global_load_dwordx4 v[238:241], v[0:1], off offset:1152
	global_load_dwordx4 v[168:171], v[0:1], off offset:1184
	ds_read_b128 v[26:29], v9 offset:8192
	s_waitcnt vmcnt(26)
	ds_read_b128 v[30:33], v9 offset:8704
	ds_read_b128 v[34:37], v9 offset:10240
	ds_read_b128 v[38:41], v9 offset:10256
	ds_read_b128 v[42:45], v9 offset:8208
	ds_read_b128 v[46:49], v9 offset:8720
	s_waitcnt lgkmcnt(4)
	v_mov_b32_e32 v51, v30
	v_mov_b32_e32 v30, v27
	v_mov_b32_e32 v27, v32
	v_mov_b32_e32 v50, v26
	v_lshl_add_u64 v[0:1], v[4:5], 0, s[38:39]
	v_mov_b32_e32 v26, v28
	s_cselect_b64 s[8:9], -1, 0
	v_lshl_add_u64 v[6:7], v[6:7], 0, s[38:39]
	v_or_b32_e32 v138, s73, v93
	v_and_b32_e32 v8, 0x70, v8
	v_add_u32_e32 v94, 16, v91
	s_waitcnt vmcnt(23)
	v_cndmask_b32_e32 v32, 0, v11, vcc
	v_cndmask_b32_e32 v10, 0, v10, vcc
	v_lshlrev_b32_e32 v4, 16, v10
	v_and_b32_e32 v10, 0xffff0000, v10
	v_cndmask_b32_e32 v54, 0, v12, vcc
	v_lshlrev_b32_e32 v12, 16, v32
	v_cndmask_b32_e32 v28, 0, v13, vcc
	s_waitcnt vmcnt(17)
	v_cndmask_b32_e64 v11, 0, v14, s[4:5]
	v_lshlrev_b32_e32 v5, 16, v11
	v_pk_mul_f32 v[4:5], v[50:51], v[4:5]
	v_cndmask_b32_e64 v15, 0, v15, s[4:5]
	v_and_b32_e32 v11, 0xffff0000, v11
	s_waitcnt lgkmcnt(3)
	v_add_f32_e32 v4, v34, v4
	v_pk_mul_f32 v[10:11], v[30:31], v[10:11]
	v_add_f32_e32 v30, v4, v5
	v_and_b32_e32 v5, 0xffff0000, v15
	v_and_b32_e32 v4, 0xffff0000, v32
	v_mov_b32_e32 v32, v29
	v_pk_mul_f32 v[4:5], v[32:33], v[4:5]
	v_cndmask_b32_e64 v16, 0, v16, s[4:5]
	v_add_f32_e32 v10, v35, v10
	v_add_f32_e32 v4, v37, v4
	v_add_f32_e32 v31, v10, v11
	v_add_f32_e32 v29, v4, v5
	v_lshlrev_b32_e32 v5, 16, v16
	v_lshlrev_b32_e32 v4, 16, v54
	s_waitcnt lgkmcnt(1)
	v_mov_b32_e32 v10, v42
	s_waitcnt lgkmcnt(0)
	v_mov_b32_e32 v11, v46
	v_pk_mul_f32 v[4:5], v[10:11], v[4:5]
	v_mov_b32_e32 v46, v43
	v_add_f32_e32 v4, v38, v4
	v_add_f32_e32 v32, v4, v5
	v_and_b32_e32 v5, 0xffff0000, v16
	v_and_b32_e32 v4, 0xffff0000, v54
	v_pk_mul_f32 v[4:5], v[46:47], v[4:5]
	v_cndmask_b32_e64 v17, 0, v17, s[4:5]
	v_add_f32_e32 v4, v39, v4
	v_add_f32_e32 v33, v4, v5
	v_lshlrev_b32_e32 v5, 16, v17
	v_lshlrev_b32_e32 v4, 16, v28
	v_mov_b32_e32 v10, v44
	v_mov_b32_e32 v11, v48
	v_pk_mul_f32 v[4:5], v[10:11], v[4:5]
	v_lshlrev_b32_e32 v13, 16, v15
	v_add_f32_e32 v4, v40, v4
	v_pk_mul_f32 v[12:13], v[26:27], v[12:13]
	v_add_f32_e32 v35, v4, v5
	v_and_b32_e32 v5, 0xffff0000, v17
	v_and_b32_e32 v4, 0xffff0000, v28
	v_mov_b32_e32 v48, v45
	v_add_f32_e32 v12, v36, v12
	v_pk_mul_f32 v[4:5], v[48:49], v[4:5]
	v_add_f32_e32 v34, v12, v13
	v_add_f32_e32 v4, v41, v4
	s_waitcnt vmcnt(11)
	v_cndmask_b32_e64 v36, 0, v21, s[8:9]
	v_cndmask_b32_e64 v37, 0, v20, s[8:9]
	v_cndmask_b32_e64 v38, 0, v19, s[8:9]
	v_cndmask_b32_e64 v39, 0, v18, s[8:9]
	ds_read_b128 v[10:13], v9 offset:9216
	ds_read_b128 v[14:17], v9 offset:9232
	s_waitcnt vmcnt(5)
	v_cndmask_b32_e64 v40, 0, v25, s[6:7]
	v_cndmask_b32_e64 v41, 0, v24, s[6:7]
	v_cndmask_b32_e64 v42, 0, v23, s[6:7]
	v_cndmask_b32_e64 v43, 0, v22, s[6:7]
	ds_read_b128 v[18:21], v9 offset:9728
	ds_read_b128 v[22:25], v9 offset:9744
	v_add_f32_e32 v28, v4, v5
	v_lshlrev_b32_e32 v5, 16, v43
	v_lshlrev_b32_e32 v4, 16, v39
	s_waitcnt lgkmcnt(3)
	v_mov_b32_e32 v26, v10
	s_waitcnt lgkmcnt(1)
	v_mov_b32_e32 v27, v18
	v_pk_mul_f32 v[4:5], v[26:27], v[4:5]
	v_mov_b32_e32 v18, v11
	v_add_f32_e32 v4, v30, v4
	v_add_f32_e32 v26, v4, v5
	v_and_b32_e32 v5, 0xffff0000, v43
	v_and_b32_e32 v4, 0xffff0000, v39
	v_pk_mul_f32 v[4:5], v[18:19], v[4:5]
	v_mov_b32_e32 v10, v12
	v_add_f32_e32 v4, v31, v4
	v_add_f32_e32 v18, v4, v5
	v_lshlrev_b32_e32 v5, 16, v42
	v_lshlrev_b32_e32 v4, 16, v38
	v_mov_b32_e32 v11, v20
	v_pk_mul_f32 v[4:5], v[10:11], v[4:5]
	v_mov_b32_e32 v20, v13
	v_add_f32_e32 v4, v34, v4
	v_add_f32_e32 v12, v4, v5
	v_and_b32_e32 v5, 0xffff0000, v42
	v_and_b32_e32 v4, 0xffff0000, v38
	v_pk_mul_f32 v[4:5], v[20:21], v[4:5]
	v_mov_b32_e32 v10, v14
	v_add_f32_e32 v4, v29, v4
	v_add_f32_e32 v13, v4, v5
	v_lshlrev_b32_e32 v5, 16, v41
	v_lshlrev_b32_e32 v4, 16, v37
	s_waitcnt lgkmcnt(0)
	v_mov_b32_e32 v11, v22
	v_pk_mul_f32 v[4:5], v[10:11], v[4:5]
	v_mov_b32_e32 v22, v15
	v_add_f32_e32 v4, v32, v4
	v_add_f32_e32 v14, v4, v5
	v_and_b32_e32 v5, 0xffff0000, v41
	v_and_b32_e32 v4, 0xffff0000, v37
	v_pk_mul_f32 v[4:5], v[22:23], v[4:5]
	v_mov_b32_e32 v10, v16
	v_add_f32_e32 v4, v33, v4
	v_add_f32_e32 v15, v4, v5
	v_lshlrev_b32_e32 v5, 16, v40
	v_lshlrev_b32_e32 v4, 16, v36
	v_mov_b32_e32 v11, v24
	v_pk_mul_f32 v[4:5], v[10:11], v[4:5]
	v_mov_b32_e32 v24, v17
	v_add_f32_e32 v4, v35, v4
	v_add_f32_e32 v10, v4, v5
	v_and_b32_e32 v5, 0xffff0000, v40
	v_and_b32_e32 v4, 0xffff0000, v36
	v_pk_mul_f32 v[4:5], v[24:25], v[4:5]
	v_cvt_pk_bf16_f32 v48, v26, v18
	v_cvt_pk_bf16_f32 v49, v12, v13
	v_cvt_pk_bf16_f32 v50, v14, v15
	s_nop 0
	v_add_f32_e32 v4, v28, v4
	v_add_f32_e32 v4, v4, v5
	v_cvt_pk_bf16_f32 v51, v10, v4
	v_lshl_add_u64 v[4:5], v[2:3], 0, s[38:39]
	v_lshl_add_u64 v[2:3], v[52:53], 0, s[38:39]
	ds_read_b128 v[26:29], v9 offset:10304
	ds_read_b128 v[30:33], v9 offset:10320
	s_waitcnt vmcnt(4)
	v_cndmask_b32_e32 v46, 0, v181, vcc
	v_cndmask_b32_e32 v47, 0, v180, vcc
	v_cndmask_b32_e32 v52, 0, v179, vcc
	v_cndmask_b32_e32 v53, 0, v178, vcc
	ds_read_b128 v[10:13], v9 offset:8256
	ds_read_b128 v[34:37], v9 offset:8272
	s_waitcnt vmcnt(4)
	v_cndmask_b32_e64 v54, 0, v185, s[4:5]
	v_cndmask_b32_e64 v55, 0, v184, s[4:5]
	v_cndmask_b32_e64 v56, 0, v183, s[4:5]
	v_cndmask_b32_e64 v57, 0, v182, s[4:5]
	ds_read_b128 v[14:17], v9 offset:8768
	ds_read_b128 v[38:41], v9 offset:8784
	v_lshlrev_b32_e32 v43, 16, v57
	v_lshlrev_b32_e32 v42, 16, v53
	s_waitcnt lgkmcnt(3)
	v_mov_b32_e32 v44, v10
	s_waitcnt lgkmcnt(1)
	v_mov_b32_e32 v45, v14
	v_pk_mul_f32 v[42:43], v[44:45], v[42:43]
	v_mov_b32_e32 v14, v11
	v_add_f32_e32 v10, v26, v42
	v_add_f32_e32 v44, v10, v43
	v_and_b32_e32 v43, 0xffff0000, v57
	v_and_b32_e32 v42, 0xffff0000, v53
	v_pk_mul_f32 v[10:11], v[14:15], v[42:43]
	v_mov_b32_e32 v14, v12
	v_add_f32_e32 v10, v27, v10
	v_add_f32_e32 v42, v10, v11
	v_lshlrev_b32_e32 v11, 16, v56
	v_lshlrev_b32_e32 v10, 16, v52
	v_mov_b32_e32 v15, v16
	v_pk_mul_f32 v[10:11], v[14:15], v[10:11]
	v_mov_b32_e32 v16, v13
	v_add_f32_e32 v10, v28, v10
	v_add_f32_e32 v43, v10, v11
	v_and_b32_e32 v11, 0xffff0000, v56
	v_and_b32_e32 v10, 0xffff0000, v52
	v_pk_mul_f32 v[10:11], v[16:17], v[10:11]
	v_mov_b32_e32 v12, v34
	v_add_f32_e32 v10, v29, v10
	v_add_f32_e32 v45, v10, v11
	v_lshlrev_b32_e32 v11, 16, v55
	v_lshlrev_b32_e32 v10, 16, v47
	s_waitcnt lgkmcnt(0)
	v_mov_b32_e32 v13, v38
	v_pk_mul_f32 v[10:11], v[12:13], v[10:11]
	v_mov_b32_e32 v38, v35
	v_add_f32_e32 v10, v30, v10
	v_add_f32_e32 v30, v10, v11
	v_and_b32_e32 v11, 0xffff0000, v55
	v_and_b32_e32 v10, 0xffff0000, v47
	v_pk_mul_f32 v[10:11], v[38:39], v[10:11]
	v_mov_b32_e32 v12, v36
	v_add_f32_e32 v10, v31, v10
	v_add_f32_e32 v31, v10, v11
	v_lshlrev_b32_e32 v11, 16, v54
	v_lshlrev_b32_e32 v10, 16, v46
	v_mov_b32_e32 v13, v40
	v_pk_mul_f32 v[10:11], v[12:13], v[10:11]
	v_mov_b32_e32 v40, v37
	v_add_f32_e32 v10, v32, v10
	v_add_f32_e32 v32, v10, v11
	v_and_b32_e32 v11, 0xffff0000, v54
	v_and_b32_e32 v10, 0xffff0000, v46
	v_pk_mul_f32 v[10:11], v[40:41], v[10:11]
	s_waitcnt vmcnt(4)
	v_cndmask_b32_e64 v34, 0, v189, s[8:9]
	v_add_f32_e32 v10, v33, v10
	v_add_f32_e32 v33, v10, v11
	v_cndmask_b32_e64 v35, 0, v188, s[8:9]
	v_cndmask_b32_e64 v36, 0, v187, s[8:9]
	v_cndmask_b32_e64 v37, 0, v186, s[8:9]
	ds_read_b128 v[10:13], v9 offset:9280
	ds_read_b128 v[14:17], v9 offset:9296
	v_cndmask_b32_e64 v38, 0, v193, s[6:7]
	v_cndmask_b32_e64 v39, 0, v192, s[6:7]
	v_cndmask_b32_e64 v40, 0, v191, s[6:7]
	v_cndmask_b32_e64 v41, 0, v190, s[6:7]
	ds_read_b128 v[18:21], v9 offset:9792
	ds_read_b128 v[22:25], v9 offset:9808
	v_lshlrev_b32_e32 v27, 16, v41
	v_lshlrev_b32_e32 v26, 16, v37
	s_waitcnt lgkmcnt(3)
	v_mov_b32_e32 v28, v10
	s_waitcnt lgkmcnt(1)
	v_mov_b32_e32 v29, v18
	v_pk_mul_f32 v[26:27], v[28:29], v[26:27]
	v_mov_b32_e32 v18, v11
	v_add_f32_e32 v10, v44, v26
	v_add_f32_e32 v28, v10, v27
	v_and_b32_e32 v27, 0xffff0000, v41
	v_and_b32_e32 v26, 0xffff0000, v37
	v_pk_mul_f32 v[10:11], v[18:19], v[26:27]
	v_mov_b32_e32 v18, v12
	v_add_f32_e32 v10, v42, v10
	v_add_f32_e32 v26, v10, v11
	v_lshlrev_b32_e32 v11, 16, v40
	v_lshlrev_b32_e32 v10, 16, v36
	v_mov_b32_e32 v19, v20
	v_pk_mul_f32 v[10:11], v[18:19], v[10:11]
	v_mov_b32_e32 v20, v13
	v_add_f32_e32 v10, v43, v10
	v_add_f32_e32 v18, v10, v11
	v_and_b32_e32 v11, 0xffff0000, v40
	v_and_b32_e32 v10, 0xffff0000, v36
	v_pk_mul_f32 v[10:11], v[20:21], v[10:11]
	v_mov_b32_e32 v12, v14
	v_add_f32_e32 v10, v45, v10
	v_add_f32_e32 v19, v10, v11
	v_lshlrev_b32_e32 v11, 16, v39
	v_lshlrev_b32_e32 v10, 16, v35
	s_waitcnt lgkmcnt(0)
	v_mov_b32_e32 v13, v22
	v_pk_mul_f32 v[10:11], v[12:13], v[10:11]
	v_mov_b32_e32 v22, v15
	v_add_f32_e32 v10, v30, v10
	v_add_f32_e32 v14, v10, v11
	v_and_b32_e32 v11, 0xffff0000, v39
	v_and_b32_e32 v10, 0xffff0000, v35
	v_pk_mul_f32 v[10:11], v[22:23], v[10:11]
	v_mov_b32_e32 v12, v16
	v_add_f32_e32 v10, v31, v10
	v_add_f32_e32 v15, v10, v11
	v_lshlrev_b32_e32 v11, 16, v38
	v_lshlrev_b32_e32 v10, 16, v34
	v_mov_b32_e32 v13, v24
	v_pk_mul_f32 v[10:11], v[12:13], v[10:11]
	v_mov_b32_e32 v24, v17
	v_add_f32_e32 v10, v32, v10
	v_add_f32_e32 v12, v10, v11
	v_and_b32_e32 v11, 0xffff0000, v38
	v_and_b32_e32 v10, 0xffff0000, v34
	v_pk_mul_f32 v[10:11], v[24:25], v[10:11]
	v_cvt_pk_bf16_f32 v52, v28, v26
	v_cvt_pk_bf16_f32 v53, v18, v19
	v_cvt_pk_bf16_f32 v54, v14, v15
	s_nop 0
	v_add_f32_e32 v10, v33, v10
	v_add_f32_e32 v10, v10, v11
	v_cvt_pk_bf16_f32 v55, v12, v10
	global_load_dwordx4 v[178:181], v[0:1], off offset:192
	global_load_dwordx4 v[182:185], v[4:5], off offset:192
	global_load_dwordx4 v[186:189], v[2:3], off offset:192
	global_load_dwordx4 v[190:193], v[6:7], off offset:192
	ds_read_b128 v[26:29], v9 offset:10368
	ds_read_b128 v[30:33], v9 offset:10384
	s_waitcnt vmcnt(7)
	v_cndmask_b32_e32 v46, 0, v197, vcc
	v_cndmask_b32_e32 v47, 0, v196, vcc
	v_cndmask_b32_e32 v56, 0, v195, vcc
	v_cndmask_b32_e32 v57, 0, v194, vcc
	ds_read_b128 v[10:13], v9 offset:8320
	ds_read_b128 v[34:37], v9 offset:8336
	s_waitcnt vmcnt(7)
	v_cndmask_b32_e64 v58, 0, v201, s[4:5]
	v_cndmask_b32_e64 v59, 0, v200, s[4:5]
	v_cndmask_b32_e64 v60, 0, v199, s[4:5]
	v_cndmask_b32_e64 v61, 0, v198, s[4:5]
	ds_read_b128 v[14:17], v9 offset:8832
	ds_read_b128 v[38:41], v9 offset:8848
	v_lshlrev_b32_e32 v43, 16, v61
	v_lshlrev_b32_e32 v42, 16, v57
	s_waitcnt lgkmcnt(3)
	v_mov_b32_e32 v44, v10
	s_waitcnt lgkmcnt(1)
	v_mov_b32_e32 v45, v14
	v_pk_mul_f32 v[42:43], v[44:45], v[42:43]
	v_mov_b32_e32 v14, v11
	v_add_f32_e32 v10, v26, v42
	v_add_f32_e32 v44, v10, v43
	v_and_b32_e32 v43, 0xffff0000, v61
	v_and_b32_e32 v42, 0xffff0000, v57
	v_pk_mul_f32 v[10:11], v[14:15], v[42:43]
	v_mov_b32_e32 v14, v12
	v_add_f32_e32 v10, v27, v10
	v_add_f32_e32 v42, v10, v11
	v_lshlrev_b32_e32 v11, 16, v60
	v_lshlrev_b32_e32 v10, 16, v56
	v_mov_b32_e32 v15, v16
	v_pk_mul_f32 v[10:11], v[14:15], v[10:11]
	v_mov_b32_e32 v16, v13
	v_add_f32_e32 v10, v28, v10
	v_add_f32_e32 v43, v10, v11
	v_and_b32_e32 v11, 0xffff0000, v60
	v_and_b32_e32 v10, 0xffff0000, v56
	v_pk_mul_f32 v[10:11], v[16:17], v[10:11]
	v_mov_b32_e32 v12, v34
	v_add_f32_e32 v10, v29, v10
	v_add_f32_e32 v45, v10, v11
	v_lshlrev_b32_e32 v11, 16, v59
	v_lshlrev_b32_e32 v10, 16, v47
	s_waitcnt lgkmcnt(0)
	v_mov_b32_e32 v13, v38
	v_pk_mul_f32 v[10:11], v[12:13], v[10:11]
	v_mov_b32_e32 v38, v35
	v_add_f32_e32 v10, v30, v10
	v_add_f32_e32 v30, v10, v11
	v_and_b32_e32 v11, 0xffff0000, v59
	v_and_b32_e32 v10, 0xffff0000, v47
	v_pk_mul_f32 v[10:11], v[38:39], v[10:11]
	v_mov_b32_e32 v12, v36
	v_add_f32_e32 v10, v31, v10
	v_add_f32_e32 v31, v10, v11
	v_lshlrev_b32_e32 v11, 16, v58
	v_lshlrev_b32_e32 v10, 16, v46
	v_mov_b32_e32 v13, v40
	v_pk_mul_f32 v[10:11], v[12:13], v[10:11]
	v_mov_b32_e32 v40, v37
	v_add_f32_e32 v10, v32, v10
	v_add_f32_e32 v32, v10, v11
	v_and_b32_e32 v11, 0xffff0000, v58
	v_and_b32_e32 v10, 0xffff0000, v46
	v_pk_mul_f32 v[10:11], v[40:41], v[10:11]
	s_waitcnt vmcnt(7)
	v_cndmask_b32_e64 v34, 0, v205, s[8:9]
	v_add_f32_e32 v10, v33, v10
	v_add_f32_e32 v33, v10, v11
	v_cndmask_b32_e64 v35, 0, v204, s[8:9]
	v_cndmask_b32_e64 v36, 0, v203, s[8:9]
	v_cndmask_b32_e64 v37, 0, v202, s[8:9]
	ds_read_b128 v[10:13], v9 offset:9344
	ds_read_b128 v[14:17], v9 offset:9360
	s_waitcnt vmcnt(7)
	v_cndmask_b32_e64 v38, 0, v209, s[6:7]
	v_cndmask_b32_e64 v39, 0, v208, s[6:7]
	v_cndmask_b32_e64 v40, 0, v207, s[6:7]
	v_cndmask_b32_e64 v41, 0, v206, s[6:7]
	ds_read_b128 v[18:21], v9 offset:9856
	ds_read_b128 v[22:25], v9 offset:9872
	v_lshlrev_b32_e32 v27, 16, v41
	v_lshlrev_b32_e32 v26, 16, v37
	s_waitcnt lgkmcnt(3)
	v_mov_b32_e32 v28, v10
	s_waitcnt lgkmcnt(1)
	v_mov_b32_e32 v29, v18
	v_pk_mul_f32 v[26:27], v[28:29], v[26:27]
	v_mov_b32_e32 v18, v11
	v_add_f32_e32 v10, v44, v26
	v_add_f32_e32 v28, v10, v27
	v_and_b32_e32 v27, 0xffff0000, v41
	v_and_b32_e32 v26, 0xffff0000, v37
	v_pk_mul_f32 v[10:11], v[18:19], v[26:27]
	v_mov_b32_e32 v18, v12
	v_add_f32_e32 v10, v42, v10
	v_add_f32_e32 v26, v10, v11
	v_lshlrev_b32_e32 v11, 16, v40
	v_lshlrev_b32_e32 v10, 16, v36
	v_mov_b32_e32 v19, v20
	v_pk_mul_f32 v[10:11], v[18:19], v[10:11]
	v_mov_b32_e32 v20, v13
	v_add_f32_e32 v10, v43, v10
	v_add_f32_e32 v18, v10, v11
	v_and_b32_e32 v11, 0xffff0000, v40
	v_and_b32_e32 v10, 0xffff0000, v36
	v_pk_mul_f32 v[10:11], v[20:21], v[10:11]
	v_mov_b32_e32 v12, v14
	v_add_f32_e32 v10, v45, v10
	v_add_f32_e32 v19, v10, v11
	v_lshlrev_b32_e32 v11, 16, v39
	v_lshlrev_b32_e32 v10, 16, v35
	s_waitcnt lgkmcnt(0)
	v_mov_b32_e32 v13, v22
	v_pk_mul_f32 v[10:11], v[12:13], v[10:11]
	v_mov_b32_e32 v22, v15
	v_add_f32_e32 v10, v30, v10
	v_add_f32_e32 v14, v10, v11
	v_and_b32_e32 v11, 0xffff0000, v39
	v_and_b32_e32 v10, 0xffff0000, v35
	v_pk_mul_f32 v[10:11], v[22:23], v[10:11]
	v_mov_b32_e32 v12, v16
	v_add_f32_e32 v10, v31, v10
	v_add_f32_e32 v15, v10, v11
	v_lshlrev_b32_e32 v11, 16, v38
	v_lshlrev_b32_e32 v10, 16, v34
	v_mov_b32_e32 v13, v24
	v_pk_mul_f32 v[10:11], v[12:13], v[10:11]
	v_mov_b32_e32 v24, v17
	v_add_f32_e32 v10, v32, v10
	v_add_f32_e32 v12, v10, v11
	v_and_b32_e32 v11, 0xffff0000, v38
	v_and_b32_e32 v10, 0xffff0000, v34
	v_pk_mul_f32 v[10:11], v[24:25], v[10:11]
	v_cvt_pk_bf16_f32 v56, v28, v26
	v_cvt_pk_bf16_f32 v57, v18, v19
	v_cvt_pk_bf16_f32 v58, v14, v15
	s_nop 0
	v_add_f32_e32 v10, v33, v10
	v_add_f32_e32 v10, v10, v11
	v_cvt_pk_bf16_f32 v59, v12, v10
	global_load_dwordx4 v[194:197], v[0:1], off offset:224
	global_load_dwordx4 v[198:201], v[4:5], off offset:224
	global_load_dwordx4 v[202:205], v[2:3], off offset:224
	global_load_dwordx4 v[206:209], v[6:7], off offset:224
	ds_read_b128 v[26:29], v9 offset:10432
	ds_read_b128 v[30:33], v9 offset:10448
	s_waitcnt vmcnt(10)
	v_cndmask_b32_e32 v46, 0, v213, vcc
	v_cndmask_b32_e32 v47, 0, v212, vcc
	v_cndmask_b32_e32 v60, 0, v211, vcc
	v_cndmask_b32_e32 v61, 0, v210, vcc
	ds_read_b128 v[10:13], v9 offset:8384
	ds_read_b128 v[34:37], v9 offset:8400
	s_waitcnt vmcnt(10)
	v_cndmask_b32_e64 v62, 0, v217, s[4:5]
	v_cndmask_b32_e64 v63, 0, v216, s[4:5]
	v_cndmask_b32_e64 v64, 0, v215, s[4:5]
	v_cndmask_b32_e64 v65, 0, v214, s[4:5]
	ds_read_b128 v[14:17], v9 offset:8896
	ds_read_b128 v[38:41], v9 offset:8912
	v_lshlrev_b32_e32 v43, 16, v65
	v_lshlrev_b32_e32 v42, 16, v61
	s_waitcnt lgkmcnt(3)
	v_mov_b32_e32 v44, v10
	s_waitcnt lgkmcnt(1)
	v_mov_b32_e32 v45, v14
	v_pk_mul_f32 v[42:43], v[44:45], v[42:43]
	v_mov_b32_e32 v14, v11
	v_add_f32_e32 v10, v26, v42
	v_add_f32_e32 v44, v10, v43
	v_and_b32_e32 v43, 0xffff0000, v65
	v_and_b32_e32 v42, 0xffff0000, v61
	v_pk_mul_f32 v[10:11], v[14:15], v[42:43]
	v_mov_b32_e32 v14, v12
	v_add_f32_e32 v10, v27, v10
	v_add_f32_e32 v42, v10, v11
	v_lshlrev_b32_e32 v11, 16, v64
	v_lshlrev_b32_e32 v10, 16, v60
	v_mov_b32_e32 v15, v16
	v_pk_mul_f32 v[10:11], v[14:15], v[10:11]
	v_mov_b32_e32 v16, v13
	v_add_f32_e32 v10, v28, v10
	v_add_f32_e32 v43, v10, v11
	v_and_b32_e32 v11, 0xffff0000, v64
	v_and_b32_e32 v10, 0xffff0000, v60
	v_pk_mul_f32 v[10:11], v[16:17], v[10:11]
	v_mov_b32_e32 v12, v34
	v_add_f32_e32 v10, v29, v10
	v_add_f32_e32 v45, v10, v11
	v_lshlrev_b32_e32 v11, 16, v63
	v_lshlrev_b32_e32 v10, 16, v47
	s_waitcnt lgkmcnt(0)
	v_mov_b32_e32 v13, v38
	v_pk_mul_f32 v[10:11], v[12:13], v[10:11]
	v_mov_b32_e32 v38, v35
	v_add_f32_e32 v10, v30, v10
	v_add_f32_e32 v30, v10, v11
	v_and_b32_e32 v11, 0xffff0000, v63
	v_and_b32_e32 v10, 0xffff0000, v47
	v_pk_mul_f32 v[10:11], v[38:39], v[10:11]
	v_mov_b32_e32 v12, v36
	v_add_f32_e32 v10, v31, v10
	v_add_f32_e32 v31, v10, v11
	v_lshlrev_b32_e32 v11, 16, v62
	v_lshlrev_b32_e32 v10, 16, v46
	v_mov_b32_e32 v13, v40
	v_pk_mul_f32 v[10:11], v[12:13], v[10:11]
	v_mov_b32_e32 v40, v37
	v_add_f32_e32 v10, v32, v10
	v_add_f32_e32 v32, v10, v11
	v_and_b32_e32 v11, 0xffff0000, v62
	v_and_b32_e32 v10, 0xffff0000, v46
	v_pk_mul_f32 v[10:11], v[40:41], v[10:11]
	s_waitcnt vmcnt(10)
	v_cndmask_b32_e64 v34, 0, v221, s[8:9]
	v_add_f32_e32 v10, v33, v10
	v_add_f32_e32 v33, v10, v11
	v_cndmask_b32_e64 v35, 0, v220, s[8:9]
	v_cndmask_b32_e64 v36, 0, v219, s[8:9]
	v_cndmask_b32_e64 v37, 0, v218, s[8:9]
	ds_read_b128 v[10:13], v9 offset:9408
	ds_read_b128 v[14:17], v9 offset:9424
	s_waitcnt vmcnt(10)
	v_cndmask_b32_e64 v38, 0, v225, s[6:7]
	v_cndmask_b32_e64 v39, 0, v224, s[6:7]
	v_cndmask_b32_e64 v40, 0, v223, s[6:7]
	v_cndmask_b32_e64 v41, 0, v222, s[6:7]
	ds_read_b128 v[18:21], v9 offset:9920
	ds_read_b128 v[22:25], v9 offset:9936
	v_lshlrev_b32_e32 v27, 16, v41
	v_lshlrev_b32_e32 v26, 16, v37
	s_waitcnt lgkmcnt(3)
	v_mov_b32_e32 v28, v10
	s_waitcnt lgkmcnt(1)
	v_mov_b32_e32 v29, v18
	v_pk_mul_f32 v[26:27], v[28:29], v[26:27]
	v_mov_b32_e32 v18, v11
	v_add_f32_e32 v10, v44, v26
	v_add_f32_e32 v28, v10, v27
	v_and_b32_e32 v27, 0xffff0000, v41
	v_and_b32_e32 v26, 0xffff0000, v37
	v_pk_mul_f32 v[10:11], v[18:19], v[26:27]
	v_mov_b32_e32 v18, v12
	v_add_f32_e32 v10, v42, v10
	v_add_f32_e32 v26, v10, v11
	v_lshlrev_b32_e32 v11, 16, v40
	v_lshlrev_b32_e32 v10, 16, v36
	v_mov_b32_e32 v19, v20
	v_pk_mul_f32 v[10:11], v[18:19], v[10:11]
	v_mov_b32_e32 v20, v13
	v_add_f32_e32 v10, v43, v10
	v_add_f32_e32 v18, v10, v11
	v_and_b32_e32 v11, 0xffff0000, v40
	v_and_b32_e32 v10, 0xffff0000, v36
	v_pk_mul_f32 v[10:11], v[20:21], v[10:11]
	v_mov_b32_e32 v12, v14
	v_add_f32_e32 v10, v45, v10
	v_add_f32_e32 v19, v10, v11
	v_lshlrev_b32_e32 v11, 16, v39
	v_lshlrev_b32_e32 v10, 16, v35
	s_waitcnt lgkmcnt(0)
	v_mov_b32_e32 v13, v22
	v_pk_mul_f32 v[10:11], v[12:13], v[10:11]
	v_mov_b32_e32 v22, v15
	v_add_f32_e32 v10, v30, v10
	v_add_f32_e32 v14, v10, v11
	v_and_b32_e32 v11, 0xffff0000, v39
	v_and_b32_e32 v10, 0xffff0000, v35
	v_pk_mul_f32 v[10:11], v[22:23], v[10:11]
	v_mov_b32_e32 v12, v16
	v_add_f32_e32 v10, v31, v10
	v_add_f32_e32 v15, v10, v11
	v_lshlrev_b32_e32 v11, 16, v38
	v_lshlrev_b32_e32 v10, 16, v34
	v_mov_b32_e32 v13, v24
	v_pk_mul_f32 v[10:11], v[12:13], v[10:11]
	v_mov_b32_e32 v24, v17
	v_add_f32_e32 v10, v32, v10
	v_add_f32_e32 v12, v10, v11
	v_and_b32_e32 v11, 0xffff0000, v38
	v_and_b32_e32 v10, 0xffff0000, v34
	v_pk_mul_f32 v[10:11], v[24:25], v[10:11]
	v_cvt_pk_bf16_f32 v60, v28, v26
	v_cvt_pk_bf16_f32 v61, v18, v19
	v_cvt_pk_bf16_f32 v62, v14, v15
	s_nop 0
	v_add_f32_e32 v10, v33, v10
	v_add_f32_e32 v10, v10, v11
	v_cvt_pk_bf16_f32 v63, v12, v10
	ds_read_b128 v[26:29], v9 offset:10496
	ds_read_b128 v[30:33], v9 offset:10512
	s_waitcnt vmcnt(9)
	v_cndmask_b32_e32 v46, 0, v229, vcc
	v_cndmask_b32_e32 v47, 0, v228, vcc
	v_cndmask_b32_e32 v64, 0, v227, vcc
	v_cndmask_b32_e32 v65, 0, v226, vcc
	ds_read_b128 v[10:13], v9 offset:8448
	ds_read_b128 v[34:37], v9 offset:8464
	s_waitcnt vmcnt(9)
	v_cndmask_b32_e64 v66, 0, v233, s[4:5]
	v_cndmask_b32_e64 v67, 0, v232, s[4:5]
	v_cndmask_b32_e64 v68, 0, v231, s[4:5]
	v_cndmask_b32_e64 v69, 0, v230, s[4:5]
	ds_read_b128 v[14:17], v9 offset:8960
	ds_read_b128 v[38:41], v9 offset:8976
	v_lshlrev_b32_e32 v43, 16, v69
	v_lshlrev_b32_e32 v42, 16, v65
	s_waitcnt lgkmcnt(3)
	v_mov_b32_e32 v44, v10
	s_waitcnt lgkmcnt(1)
	v_mov_b32_e32 v45, v14
	v_pk_mul_f32 v[42:43], v[44:45], v[42:43]
	v_mov_b32_e32 v14, v11
	v_add_f32_e32 v10, v26, v42
	v_add_f32_e32 v44, v10, v43
	v_and_b32_e32 v43, 0xffff0000, v69
	v_and_b32_e32 v42, 0xffff0000, v65
	v_pk_mul_f32 v[10:11], v[14:15], v[42:43]
	v_mov_b32_e32 v14, v12
	v_add_f32_e32 v10, v27, v10
	v_add_f32_e32 v42, v10, v11
	v_lshlrev_b32_e32 v11, 16, v68
	v_lshlrev_b32_e32 v10, 16, v64
	v_mov_b32_e32 v15, v16
	v_pk_mul_f32 v[10:11], v[14:15], v[10:11]
	v_mov_b32_e32 v16, v13
	v_add_f32_e32 v10, v28, v10
	v_add_f32_e32 v43, v10, v11
	v_and_b32_e32 v11, 0xffff0000, v68
	v_and_b32_e32 v10, 0xffff0000, v64
	v_pk_mul_f32 v[10:11], v[16:17], v[10:11]
	v_mov_b32_e32 v12, v34
	v_add_f32_e32 v10, v29, v10
	v_add_f32_e32 v45, v10, v11
	v_lshlrev_b32_e32 v11, 16, v67
	v_lshlrev_b32_e32 v10, 16, v47
	s_waitcnt lgkmcnt(0)
	v_mov_b32_e32 v13, v38
	v_pk_mul_f32 v[10:11], v[12:13], v[10:11]
	v_mov_b32_e32 v38, v35
	v_add_f32_e32 v10, v30, v10
	v_add_f32_e32 v30, v10, v11
	v_and_b32_e32 v11, 0xffff0000, v67
	v_and_b32_e32 v10, 0xffff0000, v47
	v_pk_mul_f32 v[10:11], v[38:39], v[10:11]
	v_mov_b32_e32 v12, v36
	v_add_f32_e32 v10, v31, v10
	v_add_f32_e32 v31, v10, v11
	v_lshlrev_b32_e32 v11, 16, v66
	v_lshlrev_b32_e32 v10, 16, v46
	v_mov_b32_e32 v13, v40
	v_pk_mul_f32 v[10:11], v[12:13], v[10:11]
	v_mov_b32_e32 v40, v37
	v_add_f32_e32 v10, v32, v10
	v_add_f32_e32 v32, v10, v11
	v_and_b32_e32 v11, 0xffff0000, v66
	v_and_b32_e32 v10, 0xffff0000, v46
	v_pk_mul_f32 v[10:11], v[40:41], v[10:11]
	s_waitcnt vmcnt(9)
	v_cndmask_b32_e64 v34, 0, v237, s[8:9]
	v_add_f32_e32 v10, v33, v10
	v_add_f32_e32 v33, v10, v11
	v_cndmask_b32_e64 v35, 0, v236, s[8:9]
	v_cndmask_b32_e64 v36, 0, v235, s[8:9]
	v_cndmask_b32_e64 v37, 0, v234, s[8:9]
	ds_read_b128 v[10:13], v9 offset:9472
	ds_read_b128 v[14:17], v9 offset:9488
	s_waitcnt vmcnt(9)
	v_cndmask_b32_e64 v38, 0, v241, s[6:7]
	v_cndmask_b32_e64 v39, 0, v240, s[6:7]
	v_cndmask_b32_e64 v40, 0, v239, s[6:7]
	v_cndmask_b32_e64 v41, 0, v238, s[6:7]
	ds_read_b128 v[18:21], v9 offset:9984
	ds_read_b128 v[22:25], v9 offset:10000
	v_lshlrev_b32_e32 v27, 16, v41
	v_lshlrev_b32_e32 v26, 16, v37
	s_waitcnt lgkmcnt(3)
	v_mov_b32_e32 v28, v10
	s_waitcnt lgkmcnt(1)
	v_mov_b32_e32 v29, v18
	v_pk_mul_f32 v[26:27], v[28:29], v[26:27]
	v_mov_b32_e32 v18, v11
	v_add_f32_e32 v10, v44, v26
	v_add_f32_e32 v28, v10, v27
	v_and_b32_e32 v27, 0xffff0000, v41
	v_and_b32_e32 v26, 0xffff0000, v37
	v_pk_mul_f32 v[10:11], v[18:19], v[26:27]
	v_mov_b32_e32 v18, v12
	v_add_f32_e32 v10, v42, v10
	v_add_f32_e32 v26, v10, v11
	v_lshlrev_b32_e32 v11, 16, v40
	v_lshlrev_b32_e32 v10, 16, v36
	v_mov_b32_e32 v19, v20
	v_pk_mul_f32 v[10:11], v[18:19], v[10:11]
	v_mov_b32_e32 v20, v13
	v_add_f32_e32 v10, v43, v10
	v_add_f32_e32 v18, v10, v11
	v_and_b32_e32 v11, 0xffff0000, v40
	v_and_b32_e32 v10, 0xffff0000, v36
	v_pk_mul_f32 v[10:11], v[20:21], v[10:11]
	v_mov_b32_e32 v12, v14
	v_add_f32_e32 v10, v45, v10
	v_add_f32_e32 v19, v10, v11
	v_lshlrev_b32_e32 v11, 16, v39
	v_lshlrev_b32_e32 v10, 16, v35
	s_waitcnt lgkmcnt(0)
	v_mov_b32_e32 v13, v22
	v_pk_mul_f32 v[10:11], v[12:13], v[10:11]
	v_mov_b32_e32 v22, v15
	v_add_f32_e32 v10, v30, v10
	v_add_f32_e32 v14, v10, v11
	v_and_b32_e32 v11, 0xffff0000, v39
	v_and_b32_e32 v10, 0xffff0000, v35
	v_pk_mul_f32 v[10:11], v[22:23], v[10:11]
	v_mov_b32_e32 v12, v16
	v_add_f32_e32 v10, v31, v10
	v_add_f32_e32 v15, v10, v11
	v_lshlrev_b32_e32 v11, 16, v38
	v_lshlrev_b32_e32 v10, 16, v34
	v_mov_b32_e32 v13, v24
	v_pk_mul_f32 v[10:11], v[12:13], v[10:11]
	v_mov_b32_e32 v24, v17
	v_add_f32_e32 v10, v32, v10
	v_add_f32_e32 v12, v10, v11
	v_and_b32_e32 v11, 0xffff0000, v38
	v_and_b32_e32 v10, 0xffff0000, v34
	v_pk_mul_f32 v[10:11], v[24:25], v[10:11]
	v_cvt_pk_bf16_f32 v64, v28, v26
	v_cvt_pk_bf16_f32 v65, v18, v19
	v_cvt_pk_bf16_f32 v66, v14, v15
	s_nop 0
	v_add_f32_e32 v10, v33, v10
	v_add_f32_e32 v10, v10, v11
	v_cvt_pk_bf16_f32 v67, v12, v10
	ds_read_b128 v[26:29], v9 offset:10560
	ds_read_b128 v[30:33], v9 offset:10576
	s_waitcnt vmcnt(8)
	v_cndmask_b32_e32 v46, 0, v245, vcc
	v_cndmask_b32_e32 v47, 0, v244, vcc
	v_cndmask_b32_e32 v68, 0, v243, vcc
	v_cndmask_b32_e32 v69, 0, v242, vcc
	ds_read_b128 v[10:13], v9 offset:8512
	ds_read_b128 v[34:37], v9 offset:8528
	s_waitcnt vmcnt(8)
	v_cndmask_b32_e64 v70, 0, v249, s[4:5]
	v_cndmask_b32_e64 v71, 0, v248, s[4:5]
	v_cndmask_b32_e64 v72, 0, v247, s[4:5]
	v_cndmask_b32_e64 v73, 0, v246, s[4:5]
	ds_read_b128 v[14:17], v9 offset:9024
	ds_read_b128 v[38:41], v9 offset:9040
	v_lshlrev_b32_e32 v43, 16, v73
	v_lshlrev_b32_e32 v42, 16, v69
	s_waitcnt lgkmcnt(3)
	v_mov_b32_e32 v44, v10
	s_waitcnt lgkmcnt(1)
	v_mov_b32_e32 v45, v14
	v_pk_mul_f32 v[42:43], v[44:45], v[42:43]
	v_mov_b32_e32 v14, v11
	v_add_f32_e32 v10, v26, v42
	v_add_f32_e32 v44, v10, v43
	v_and_b32_e32 v43, 0xffff0000, v73
	v_and_b32_e32 v42, 0xffff0000, v69
	v_pk_mul_f32 v[10:11], v[14:15], v[42:43]
	v_mov_b32_e32 v14, v12
	v_add_f32_e32 v10, v27, v10
	v_add_f32_e32 v42, v10, v11
	v_lshlrev_b32_e32 v11, 16, v72
	v_lshlrev_b32_e32 v10, 16, v68
	v_mov_b32_e32 v15, v16
	v_pk_mul_f32 v[10:11], v[14:15], v[10:11]
	v_mov_b32_e32 v16, v13
	v_add_f32_e32 v10, v28, v10
	v_add_f32_e32 v43, v10, v11
	v_and_b32_e32 v11, 0xffff0000, v72
	v_and_b32_e32 v10, 0xffff0000, v68
	v_pk_mul_f32 v[10:11], v[16:17], v[10:11]
	v_mov_b32_e32 v12, v34
	v_add_f32_e32 v10, v29, v10
	v_add_f32_e32 v45, v10, v11
	v_lshlrev_b32_e32 v11, 16, v71
	v_lshlrev_b32_e32 v10, 16, v47
	s_waitcnt lgkmcnt(0)
	v_mov_b32_e32 v13, v38
	v_pk_mul_f32 v[10:11], v[12:13], v[10:11]
	v_mov_b32_e32 v38, v35
	v_add_f32_e32 v10, v30, v10
	v_add_f32_e32 v30, v10, v11
	v_and_b32_e32 v11, 0xffff0000, v71
	v_and_b32_e32 v10, 0xffff0000, v47
	v_pk_mul_f32 v[10:11], v[38:39], v[10:11]
	v_mov_b32_e32 v12, v36
	v_add_f32_e32 v10, v31, v10
	v_add_f32_e32 v31, v10, v11
	v_lshlrev_b32_e32 v11, 16, v70
	v_lshlrev_b32_e32 v10, 16, v46
	v_mov_b32_e32 v13, v40
	v_pk_mul_f32 v[10:11], v[12:13], v[10:11]
	v_mov_b32_e32 v40, v37
	v_add_f32_e32 v10, v32, v10
	v_add_f32_e32 v32, v10, v11
	v_and_b32_e32 v11, 0xffff0000, v70
	v_and_b32_e32 v10, 0xffff0000, v46
	v_pk_mul_f32 v[10:11], v[40:41], v[10:11]
	s_waitcnt vmcnt(8)
	v_cndmask_b32_e64 v34, 0, v255, s[8:9]
	v_add_f32_e32 v10, v33, v10
	v_add_f32_e32 v33, v10, v11
	v_cndmask_b32_e64 v35, 0, v254, s[8:9]
	v_cndmask_b32_e64 v36, 0, v253, s[8:9]
	v_cndmask_b32_e64 v37, 0, v252, s[8:9]
	ds_read_b128 v[10:13], v9 offset:9536
	ds_read_b128 v[14:17], v9 offset:9552
	s_waitcnt vmcnt(8)
	v_cndmask_b32_e64 v38, 0, v171, s[6:7]
	v_cndmask_b32_e64 v39, 0, v170, s[6:7]
	v_cndmask_b32_e64 v40, 0, v169, s[6:7]
	v_cndmask_b32_e64 v41, 0, v168, s[6:7]
	ds_read_b128 v[18:21], v9 offset:10048
	ds_read_b128 v[22:25], v9 offset:10064
	v_lshlrev_b32_e32 v27, 16, v41
	v_lshlrev_b32_e32 v26, 16, v37
	s_waitcnt lgkmcnt(3)
	v_mov_b32_e32 v28, v10
	s_waitcnt lgkmcnt(1)
	v_mov_b32_e32 v29, v18
	v_pk_mul_f32 v[26:27], v[28:29], v[26:27]
	v_mov_b32_e32 v18, v11
	v_add_f32_e32 v10, v44, v26
	v_add_f32_e32 v28, v10, v27
	v_and_b32_e32 v27, 0xffff0000, v41
	v_and_b32_e32 v26, 0xffff0000, v37
	v_pk_mul_f32 v[10:11], v[18:19], v[26:27]
	v_mov_b32_e32 v18, v12
	v_add_f32_e32 v10, v42, v10
	v_add_f32_e32 v26, v10, v11
	v_lshlrev_b32_e32 v11, 16, v40
	v_lshlrev_b32_e32 v10, 16, v36
	v_mov_b32_e32 v19, v20
	v_pk_mul_f32 v[10:11], v[18:19], v[10:11]
	v_mov_b32_e32 v20, v13
	v_add_f32_e32 v10, v43, v10
	v_add_f32_e32 v18, v10, v11
	v_and_b32_e32 v11, 0xffff0000, v40
	v_and_b32_e32 v10, 0xffff0000, v36
	v_pk_mul_f32 v[10:11], v[20:21], v[10:11]
	v_mov_b32_e32 v12, v14
	v_add_f32_e32 v10, v45, v10
	v_add_f32_e32 v19, v10, v11
	v_lshlrev_b32_e32 v11, 16, v39
	v_lshlrev_b32_e32 v10, 16, v35
	s_waitcnt lgkmcnt(0)
	v_mov_b32_e32 v13, v22
	v_pk_mul_f32 v[10:11], v[12:13], v[10:11]
	v_mov_b32_e32 v22, v15
	v_add_f32_e32 v10, v30, v10
	v_add_f32_e32 v14, v10, v11
	v_and_b32_e32 v11, 0xffff0000, v39
	v_and_b32_e32 v10, 0xffff0000, v35
	v_pk_mul_f32 v[10:11], v[22:23], v[10:11]
	v_mov_b32_e32 v12, v16
	v_add_f32_e32 v10, v31, v10
	v_add_f32_e32 v15, v10, v11
	v_lshlrev_b32_e32 v11, 16, v38
	v_lshlrev_b32_e32 v10, 16, v34
	v_mov_b32_e32 v13, v24
	v_pk_mul_f32 v[10:11], v[12:13], v[10:11]
	v_mov_b32_e32 v24, v17
	v_add_f32_e32 v10, v32, v10
	v_add_f32_e32 v12, v10, v11
	v_and_b32_e32 v11, 0xffff0000, v38
	v_and_b32_e32 v10, 0xffff0000, v34
	v_pk_mul_f32 v[10:11], v[24:25], v[10:11]
	v_cvt_pk_bf16_f32 v68, v28, v26
	v_cvt_pk_bf16_f32 v69, v18, v19
	v_cvt_pk_bf16_f32 v70, v14, v15
	s_nop 0
	v_add_f32_e32 v10, v33, v10
	v_add_f32_e32 v10, v10, v11
	v_cvt_pk_bf16_f32 v71, v12, v10
	ds_read_b128 v[26:29], v9 offset:10624
	ds_read_b128 v[30:33], v9 offset:10640
	s_waitcnt vmcnt(4)
	v_cndmask_b32_e32 v46, 0, v181, vcc
	v_cndmask_b32_e32 v47, 0, v180, vcc
	v_cndmask_b32_e32 v72, 0, v179, vcc
	v_cndmask_b32_e32 v73, 0, v178, vcc
	ds_read_b128 v[10:13], v9 offset:8576
	ds_read_b128 v[34:37], v9 offset:8592
	s_waitcnt vmcnt(4)
	v_cndmask_b32_e64 v74, 0, v185, s[4:5]
	v_cndmask_b32_e64 v75, 0, v184, s[4:5]
	v_cndmask_b32_e64 v76, 0, v183, s[4:5]
	v_cndmask_b32_e64 v77, 0, v182, s[4:5]
	ds_read_b128 v[14:17], v9 offset:9088
	ds_read_b128 v[38:41], v9 offset:9104
	v_lshlrev_b32_e32 v43, 16, v77
	v_lshlrev_b32_e32 v42, 16, v73
	s_waitcnt lgkmcnt(3)
	v_mov_b32_e32 v44, v10
	s_waitcnt lgkmcnt(1)
	v_mov_b32_e32 v45, v14
	v_pk_mul_f32 v[42:43], v[44:45], v[42:43]
	v_mov_b32_e32 v14, v11
	v_add_f32_e32 v10, v26, v42
	v_add_f32_e32 v44, v10, v43
	v_and_b32_e32 v43, 0xffff0000, v77
	v_and_b32_e32 v42, 0xffff0000, v73
	v_pk_mul_f32 v[10:11], v[14:15], v[42:43]
	v_mov_b32_e32 v14, v12
	v_add_f32_e32 v10, v27, v10
	v_add_f32_e32 v42, v10, v11
	v_lshlrev_b32_e32 v11, 16, v76
	v_lshlrev_b32_e32 v10, 16, v72
	v_mov_b32_e32 v15, v16
	v_pk_mul_f32 v[10:11], v[14:15], v[10:11]
	v_mov_b32_e32 v16, v13
	v_add_f32_e32 v10, v28, v10
	v_add_f32_e32 v43, v10, v11
	v_and_b32_e32 v11, 0xffff0000, v76
	v_and_b32_e32 v10, 0xffff0000, v72
	v_pk_mul_f32 v[10:11], v[16:17], v[10:11]
	v_mov_b32_e32 v12, v34
	v_add_f32_e32 v10, v29, v10
	v_add_f32_e32 v45, v10, v11
	v_lshlrev_b32_e32 v11, 16, v75
	v_lshlrev_b32_e32 v10, 16, v47
	s_waitcnt lgkmcnt(0)
	v_mov_b32_e32 v13, v38
	v_pk_mul_f32 v[10:11], v[12:13], v[10:11]
	v_mov_b32_e32 v38, v35
	v_add_f32_e32 v10, v30, v10
	v_add_f32_e32 v30, v10, v11
	v_and_b32_e32 v11, 0xffff0000, v75
	v_and_b32_e32 v10, 0xffff0000, v47
	v_pk_mul_f32 v[10:11], v[38:39], v[10:11]
	v_mov_b32_e32 v12, v36
	v_add_f32_e32 v10, v31, v10
	v_add_f32_e32 v31, v10, v11
	v_lshlrev_b32_e32 v11, 16, v74
	v_lshlrev_b32_e32 v10, 16, v46
	v_mov_b32_e32 v13, v40
	v_pk_mul_f32 v[10:11], v[12:13], v[10:11]
	v_mov_b32_e32 v40, v37
	v_add_f32_e32 v10, v32, v10
	v_add_f32_e32 v32, v10, v11
	v_and_b32_e32 v11, 0xffff0000, v74
	v_and_b32_e32 v10, 0xffff0000, v46
	v_pk_mul_f32 v[10:11], v[40:41], v[10:11]
	s_waitcnt vmcnt(4)
	v_cndmask_b32_e64 v34, 0, v189, s[8:9]
	v_add_f32_e32 v10, v33, v10
	v_add_f32_e32 v33, v10, v11
	v_cndmask_b32_e64 v35, 0, v188, s[8:9]
	v_cndmask_b32_e64 v36, 0, v187, s[8:9]
	v_cndmask_b32_e64 v37, 0, v186, s[8:9]
	ds_read_b128 v[10:13], v9 offset:9600
	ds_read_b128 v[14:17], v9 offset:9616
	s_waitcnt vmcnt(4)
	v_cndmask_b32_e64 v38, 0, v193, s[6:7]
	v_cndmask_b32_e64 v39, 0, v192, s[6:7]
	v_cndmask_b32_e64 v40, 0, v191, s[6:7]
	v_cndmask_b32_e64 v41, 0, v190, s[6:7]
	ds_read_b128 v[18:21], v9 offset:10112
	ds_read_b128 v[22:25], v9 offset:10128
	v_lshlrev_b32_e32 v27, 16, v41
	v_lshlrev_b32_e32 v26, 16, v37
	s_waitcnt lgkmcnt(3)
	v_mov_b32_e32 v28, v10
	s_waitcnt lgkmcnt(1)
	v_mov_b32_e32 v29, v18
	v_pk_mul_f32 v[26:27], v[28:29], v[26:27]
	v_mov_b32_e32 v18, v11
	v_add_f32_e32 v10, v44, v26
	v_add_f32_e32 v28, v10, v27
	v_and_b32_e32 v27, 0xffff0000, v41
	v_and_b32_e32 v26, 0xffff0000, v37
	v_pk_mul_f32 v[10:11], v[18:19], v[26:27]
	v_mov_b32_e32 v18, v12
	v_add_f32_e32 v10, v42, v10
	v_add_f32_e32 v26, v10, v11
	v_lshlrev_b32_e32 v11, 16, v40
	v_lshlrev_b32_e32 v10, 16, v36
	v_mov_b32_e32 v19, v20
	v_pk_mul_f32 v[10:11], v[18:19], v[10:11]
	v_mov_b32_e32 v20, v13
	v_add_f32_e32 v10, v43, v10
	v_add_f32_e32 v18, v10, v11
	v_and_b32_e32 v11, 0xffff0000, v40
	v_and_b32_e32 v10, 0xffff0000, v36
	v_pk_mul_f32 v[10:11], v[20:21], v[10:11]
	v_mov_b32_e32 v12, v14
	v_add_f32_e32 v10, v45, v10
	v_add_f32_e32 v19, v10, v11
	v_lshlrev_b32_e32 v11, 16, v39
	v_lshlrev_b32_e32 v10, 16, v35
	s_waitcnt lgkmcnt(0)
	v_mov_b32_e32 v13, v22
	v_pk_mul_f32 v[10:11], v[12:13], v[10:11]
	v_mov_b32_e32 v22, v15
	v_add_f32_e32 v10, v30, v10
	v_add_f32_e32 v14, v10, v11
	v_and_b32_e32 v11, 0xffff0000, v39
	v_and_b32_e32 v10, 0xffff0000, v35
	v_pk_mul_f32 v[10:11], v[22:23], v[10:11]
	v_mov_b32_e32 v12, v16
	v_add_f32_e32 v10, v31, v10
	v_add_f32_e32 v15, v10, v11
	v_lshlrev_b32_e32 v11, 16, v38
	v_lshlrev_b32_e32 v10, 16, v34
	v_mov_b32_e32 v13, v24
	v_pk_mul_f32 v[10:11], v[12:13], v[10:11]
	v_mov_b32_e32 v24, v17
	v_add_f32_e32 v10, v32, v10
	v_add_f32_e32 v12, v10, v11
	v_and_b32_e32 v11, 0xffff0000, v38
	v_and_b32_e32 v10, 0xffff0000, v34
	v_pk_mul_f32 v[10:11], v[24:25], v[10:11]
	v_cvt_pk_bf16_f32 v72, v28, v26
	v_cvt_pk_bf16_f32 v73, v18, v19
	v_cvt_pk_bf16_f32 v74, v14, v15
	v_lshlrev_b32_e32 v38, 3, v92
	v_add_f32_e32 v10, v33, v10
	v_add_f32_e32 v10, v10, v11
	v_cvt_pk_bf16_f32 v75, v12, v10
	s_nop 0
	s_nop 0
	ds_read_b128 v[18:21], v9 offset:10688
	ds_read_b128 v[22:25], v9 offset:10704
	v_or_b32_e32 v39, 16, v38
	s_waitcnt vmcnt(0)
	v_cndmask_b32_e32 v40, 0, v197, vcc
	v_cndmask_b32_e32 v41, 0, v196, vcc
	v_cndmask_b32_e32 v42, 0, v195, vcc
	v_cndmask_b32_e32 v43, 0, v194, vcc
	ds_read_b128 v[10:13], v9 offset:8640
	ds_read_b128 v[26:29], v9 offset:8656
	s_waitcnt vmcnt(0)
	v_cndmask_b32_e64 v44, 0, v201, s[4:5]
	v_cndmask_b32_e64 v45, 0, v200, s[4:5]
	v_cndmask_b32_e64 v46, 0, v199, s[4:5]
	v_cndmask_b32_e64 v47, 0, v198, s[4:5]
	ds_read_b128 v[14:17], v9 offset:9152
	ds_read_b128 v[30:33], v9 offset:9168
	v_lshlrev_b32_e32 v35, 16, v47
	v_lshlrev_b32_e32 v34, 16, v43
	s_waitcnt lgkmcnt(3)
	v_mov_b32_e32 v36, v10
	s_waitcnt lgkmcnt(1)
	v_mov_b32_e32 v37, v14
	v_pk_mul_f32 v[34:35], v[36:37], v[34:35]
	v_mov_b32_e32 v14, v11
	v_add_f32_e32 v10, v18, v34
	v_add_f32_e32 v36, v10, v35
	v_and_b32_e32 v35, 0xffff0000, v47
	v_and_b32_e32 v34, 0xffff0000, v43
	v_pk_mul_f32 v[10:11], v[14:15], v[34:35]
	v_mov_b32_e32 v14, v12
	v_add_f32_e32 v10, v19, v10
	v_add_f32_e32 v34, v10, v11
	v_lshlrev_b32_e32 v11, 16, v46
	v_lshlrev_b32_e32 v10, 16, v42
	v_mov_b32_e32 v15, v16
	v_pk_mul_f32 v[10:11], v[14:15], v[10:11]
	v_mov_b32_e32 v16, v13
	v_add_f32_e32 v10, v20, v10
	v_add_f32_e32 v35, v10, v11
	v_and_b32_e32 v11, 0xffff0000, v46
	v_and_b32_e32 v10, 0xffff0000, v42
	v_pk_mul_f32 v[10:11], v[16:17], v[10:11]
	v_mov_b32_e32 v12, v26
	v_add_f32_e32 v10, v21, v10
	v_add_f32_e32 v37, v10, v11
	v_lshlrev_b32_e32 v11, 16, v45
	v_lshlrev_b32_e32 v10, 16, v41
	s_waitcnt lgkmcnt(0)
	v_mov_b32_e32 v13, v30
	v_pk_mul_f32 v[10:11], v[12:13], v[10:11]
	v_mov_b32_e32 v30, v27
	v_add_f32_e32 v10, v22, v10
	v_add_f32_e32 v22, v10, v11
	v_and_b32_e32 v11, 0xffff0000, v45
	v_and_b32_e32 v10, 0xffff0000, v41
	v_pk_mul_f32 v[10:11], v[30:31], v[10:11]
	v_mov_b32_e32 v12, v28
	v_add_f32_e32 v10, v23, v10
	v_add_f32_e32 v23, v10, v11
	v_lshlrev_b32_e32 v11, 16, v44
	v_lshlrev_b32_e32 v10, 16, v40
	v_mov_b32_e32 v13, v32
	v_pk_mul_f32 v[10:11], v[12:13], v[10:11]
	v_mov_b32_e32 v32, v29
	v_add_f32_e32 v10, v24, v10
	v_add_f32_e32 v24, v10, v11
	v_and_b32_e32 v11, 0xffff0000, v44
	v_and_b32_e32 v10, 0xffff0000, v40
	v_pk_mul_f32 v[10:11], v[32:33], v[10:11]
	s_waitcnt vmcnt(0)
	v_cndmask_b32_e64 v26, 0, v205, s[8:9]
	v_add_f32_e32 v10, v25, v10
	v_add_f32_e32 v25, v10, v11
	v_cndmask_b32_e64 v27, 0, v204, s[8:9]
	v_cndmask_b32_e64 v28, 0, v203, s[8:9]
	v_cndmask_b32_e64 v29, 0, v202, s[8:9]
	ds_read_b128 v[0:3], v9 offset:9664
	ds_read_b128 v[10:13], v9 offset:9680
	s_waitcnt vmcnt(0)
	v_cndmask_b32_e64 v30, 0, v209, s[6:7]
	v_cndmask_b32_e64 v31, 0, v208, s[6:7]
	v_cndmask_b32_e64 v32, 0, v207, s[6:7]
	v_cndmask_b32_e64 v33, 0, v206, s[6:7]
	ds_read_b128 v[4:7], v9 offset:10176
	ds_read_b128 v[14:17], v9 offset:10192
	v_lshlrev_b32_e32 v19, 16, v33
	v_lshlrev_b32_e32 v18, 16, v29
	s_waitcnt lgkmcnt(3)
	v_mov_b32_e32 v20, v0
	s_waitcnt lgkmcnt(1)
	v_mov_b32_e32 v21, v4
	v_pk_mul_f32 v[18:19], v[20:21], v[18:19]
	v_mov_b32_e32 v4, v1
	v_add_f32_e32 v0, v36, v18
	v_add_f32_e32 v9, v0, v19
	v_and_b32_e32 v19, 0xffff0000, v33
	v_and_b32_e32 v18, 0xffff0000, v29
	v_pk_mul_f32 v[0:1], v[4:5], v[18:19]
	v_mov_b32_e32 v4, v2
	v_add_f32_e32 v0, v34, v0
	v_add_f32_e32 v18, v0, v1
	v_lshlrev_b32_e32 v1, 16, v32
	v_lshlrev_b32_e32 v0, 16, v28
	v_mov_b32_e32 v5, v6
	v_pk_mul_f32 v[0:1], v[4:5], v[0:1]
	v_mov_b32_e32 v6, v3
	v_add_f32_e32 v0, v35, v0
	v_add_f32_e32 v4, v0, v1
	v_and_b32_e32 v1, 0xffff0000, v32
	v_and_b32_e32 v0, 0xffff0000, v28
	v_pk_mul_f32 v[0:1], v[6:7], v[0:1]
	v_mov_b32_e32 v2, v10
	v_add_f32_e32 v0, v37, v0
	v_add_f32_e32 v5, v0, v1
	v_lshlrev_b32_e32 v1, 16, v31
	v_lshlrev_b32_e32 v0, 16, v27
	s_waitcnt lgkmcnt(0)
	v_mov_b32_e32 v3, v14
	v_pk_mul_f32 v[0:1], v[2:3], v[0:1]
	v_mov_b32_e32 v14, v11
	v_add_f32_e32 v0, v22, v0
	v_add_f32_e32 v6, v0, v1
	v_and_b32_e32 v1, 0xffff0000, v31
	v_and_b32_e32 v0, 0xffff0000, v27
	v_pk_mul_f32 v[0:1], v[14:15], v[0:1]
	v_mov_b32_e32 v2, v12
	v_add_f32_e32 v0, v23, v0
	v_add_f32_e32 v7, v0, v1
	v_lshlrev_b32_e32 v1, 16, v30
	v_lshlrev_b32_e32 v0, 16, v26
	v_mov_b32_e32 v3, v16
	v_pk_mul_f32 v[0:1], v[2:3], v[0:1]
	v_mov_b32_e32 v16, v13
	v_add_f32_e32 v0, v24, v0
	v_add_f32_e32 v2, v0, v1
	v_and_b32_e32 v1, 0xffff0000, v30
	v_and_b32_e32 v0, 0xffff0000, v26
	v_pk_mul_f32 v[0:1], v[16:17], v[0:1]
	v_cvt_pk_bf16_f32 v76, v9, v18
	v_cvt_pk_bf16_f32 v77, v4, v5
	v_cvt_pk_bf16_f32 v78, v6, v7
	v_cmp_eq_u32_e32 vcc, v38, v93
	v_add_f32_e32 v0, v25, v0
	v_add_f32_e32 v0, v0, v1
	v_cvt_pk_bf16_f32 v79, v2, v0
	v_or_b32_e32 v2, 1, v38
	v_cndmask_b32_e32 v0, 0, v128, vcc
	v_or_b32_e32 v1, 2, v38
	v_cmp_eq_u32_e32 vcc, v2, v93
	v_or_b32_e32 v4, 3, v38
	v_or_b32_e32 v3, 4, v38
	v_cndmask_b32_e32 v2, 0, v128, vcc
	v_cmp_eq_u32_e32 vcc, v1, v93
	v_or_b32_e32 v5, 6, v38
	v_or_b32_e32 v6, 5, v38
	v_cndmask_b32_e32 v1, 0, v128, vcc
	v_cmp_eq_u32_e32 vcc, v4, v93
	v_or_b32_e32 v7, 7, v38
	v_or_b32_e32 v11, 17, v38
	v_cndmask_b32_e32 v4, 0, v128, vcc
	v_cmp_eq_u32_e32 vcc, v3, v93
	v_or_b32_e32 v10, 18, v38
	v_or_b32_e32 v13, 19, v38
	v_cndmask_b32_e32 v3, 0, v128, vcc
	v_cmp_eq_u32_e32 vcc, v5, v93
	v_or_b32_e32 v12, 20, v38
	v_or_b32_e32 v14, 22, v38
	v_cndmask_b32_e32 v5, 0, v128, vcc
	v_cmp_eq_u32_e32 vcc, v6, v93
	v_or_b32_e32 v15, 21, v38
	v_or_b32_e32 v16, 23, v38
	v_cndmask_b32_e32 v6, 0, v128, vcc
	v_cmp_eq_u32_e32 vcc, v7, v93
	v_and_b32_e32 v18, 64, v126
	v_xor_b32_e32 v17, 32, v126
	v_cndmask_b32_e32 v7, 0, v128, vcc
	v_cmp_eq_u32_e32 vcc, v39, v93
	v_add_u32_e32 v18, 64, v18
	s_lshl_b32 s6, s64, 8
	v_cndmask_b32_e32 v9, 0, v128, vcc
	v_cmp_eq_u32_e32 vcc, v11, v93
	s_add_i32 s6, s6, 16
	v_cmp_eq_u32_e64 s[4:5], 0, v92
	v_cndmask_b32_e32 v11, 0, v128, vcc
	v_cmp_eq_u32_e32 vcc, v10, v93
	v_lshl_add_u32 v136, v93, 3, s6
	v_perm_b32 v82, v6, v3, s87
	v_cndmask_b32_e32 v10, 0, v128, vcc
	v_cmp_eq_u32_e32 vcc, v13, v93
	v_perm_b32 v81, v4, v1, s87
	v_perm_b32 v83, v7, v5, s87
	v_cndmask_b32_e32 v13, 0, v128, vcc
	v_cmp_eq_u32_e32 vcc, v12, v93
	v_perm_b32 v80, v2, v0, s87
	v_perm_b32 v85, v13, v10, s87
	v_cndmask_b32_e32 v12, 0, v128, vcc
	v_cmp_eq_u32_e32 vcc, v14, v93
	v_perm_b32 v84, v11, v9, s87
	s_nop 0
	v_cndmask_b32_e32 v14, 0, v128, vcc
	v_cmp_eq_u32_e32 vcc, v15, v93
	s_nop 1
	v_cndmask_b32_e32 v15, 0, v128, vcc
	v_cmp_eq_u32_e32 vcc, v16, v93
	v_perm_b32 v86, v15, v12, s87
	s_nop 0
	v_cndmask_b32_e32 v16, 0, v128, vcc
	v_cmp_lt_i32_e32 vcc, v17, v18
	v_perm_b32 v87, v16, v14, s87
	s_nop 0
	v_cndmask_b32_e32 v17, v126, v17, vcc
	v_lshlrev_b32_e32 v137, 2, v17
	v_lshl_or_b32 v175, v138, 2, v129
	global_load_dword v172, v175, s[42:43]
	global_load_dword v173, v175, s[36:37]
	global_load_dword v174, v175, s[40:41]
	s_setprio 1
	v_xad_u32 v145, v88, v8, v94
	ds_read_b128 v[0:3], v145 offset:16384
	ds_read_b128 v[4:7], v145 offset:49152
	s_waitcnt lgkmcnt(1)
	v_mfma_f32_32x32x16_bf16 v[32:47], v[48:51], v[0:3], 0
	v_or_b32_e32 v0, 32, v88
	v_xad_u32 v147, v0, v8, v94
	s_waitcnt lgkmcnt(0)
	v_mfma_f32_32x32x16_bf16 v[16:31], v[48:51], v[4:7], 0
	ds_read_b128 v[0:3], v147 offset:16384
	ds_read_b128 v[4:7], v147 offset:49152
	s_waitcnt lgkmcnt(1)
	v_mfma_f32_32x32x16_bf16 v[32:47], v[52:55], v[0:3], v[32:47]
	v_or_b32_e32 v0, 64, v88
	v_xad_u32 v142, v0, v8, v94
	s_waitcnt lgkmcnt(0)
	v_mfma_f32_32x32x16_bf16 v[16:31], v[52:55], v[4:7], v[16:31]
	ds_read_b128 v[0:3], v142 offset:16384
	ds_read_b128 v[4:7], v142 offset:49152
	s_waitcnt lgkmcnt(1)
	v_mfma_f32_32x32x16_bf16 v[32:47], v[56:59], v[0:3], v[32:47]
	v_or_b32_e32 v0, 0x60, v88
	v_xad_u32 v146, v0, v8, v94
	s_waitcnt lgkmcnt(0)
	v_mfma_f32_32x32x16_bf16 v[16:31], v[56:59], v[4:7], v[16:31]
	ds_read_b128 v[0:3], v146 offset:16384
	ds_read_b128 v[4:7], v146 offset:49152
	s_waitcnt lgkmcnt(1)
	v_mfma_f32_32x32x16_bf16 v[32:47], v[60:63], v[0:3], v[32:47]
	v_or_b32_e32 v0, 0x80, v88
	v_xad_u32 v141, v0, v8, v94
	s_waitcnt lgkmcnt(0)
	v_mfma_f32_32x32x16_bf16 v[16:31], v[60:63], v[4:7], v[16:31]
	ds_read_b128 v[0:3], v141 offset:16384
	ds_read_b128 v[4:7], v141 offset:49152
	s_waitcnt lgkmcnt(1)
	v_mfma_f32_32x32x16_bf16 v[32:47], v[64:67], v[0:3], v[32:47]
	v_or_b32_e32 v0, 0xa0, v88
	v_xad_u32 v144, v0, v8, v94
	s_waitcnt lgkmcnt(0)
	v_mfma_f32_32x32x16_bf16 v[16:31], v[64:67], v[4:7], v[16:31]
	ds_read_b128 v[0:3], v144 offset:16384
	ds_read_b128 v[4:7], v144 offset:49152
	s_waitcnt lgkmcnt(1)
	v_mfma_f32_32x32x16_bf16 v[32:47], v[68:71], v[0:3], v[32:47]
	v_or_b32_e32 v0, 0xc0, v88
	v_xad_u32 v139, v0, v8, v94
	s_waitcnt lgkmcnt(0)
	v_mfma_f32_32x32x16_bf16 v[16:31], v[68:71], v[4:7], v[16:31]
	ds_read_b128 v[0:3], v139 offset:16384
	ds_read_b128 v[4:7], v139 offset:49152
	s_waitcnt lgkmcnt(1)
	v_mfma_f32_32x32x16_bf16 v[32:47], v[72:75], v[0:3], v[32:47]
	v_or_b32_e32 v0, 0xe0, v88
	v_xad_u32 v143, v0, v8, v94
	s_waitcnt lgkmcnt(0)
	v_mfma_f32_32x32x16_bf16 v[16:31], v[72:75], v[4:7], v[16:31]
	ds_read_b128 v[0:3], v143 offset:16384
	ds_read_b128 v[4:7], v143 offset:49152
	s_waitcnt lgkmcnt(1)
	v_mfma_f32_32x32x16_bf16 v[32:47], v[76:79], v[0:3], v[32:47]
	s_waitcnt lgkmcnt(0)
	v_mfma_f32_32x32x16_bf16 v[16:31], v[76:79], v[4:7], v[16:31]
	v_mfma_f32_32x32x16_bf16 v[0:15], v[48:51], v[80:83], 0
	v_mfma_f32_32x32x16_bf16 v[0:15], v[52:55], v[84:87], v[0:15]
	s_setprio 0
	v_lshl_or_b32 v88, v138, 2, v129
	s_waitcnt vmcnt(0)
	ds_read_b32 v251, v167
	v_mov_b32_e32 v94, v173
	v_mov_b32_e32 v88, v174
	v_add_f32_e32 v32, v32, v94
	v_add_f32_e32 v16, v16, v88
	v_mul_f32_e32 v32, 0xbfb8aa3b, v32
	v_mul_f32_e32 v16, 0xbfb8aa3b, v16
	v_exp_f32_e32 v32, v32
	v_exp_f32_e32 v96, v16
	v_add_f32_e32 v17, v17, v88
	v_mul_f32_e32 v17, 0xbfb8aa3b, v17
	v_exp_f32_e32 v97, v17
	v_add_f32_e32 v32, 1.0, v32
	v_add_f32_e32 v96, 1.0, v96
	v_rcp_f32_e32 v17, v32
	v_rcp_f32_e32 v32, v96
	v_add_f32_e32 v33, v33, v94
	v_add_f32_e32 v34, v34, v94
	v_mul_f32_e32 v33, 0xbfb8aa3b, v33
	v_mul_f32_e32 v34, 0xbfb8aa3b, v34
	v_exp_f32_e32 v33, v33
	v_exp_f32_e32 v34, v34
	v_add_f32_e32 v33, 1.0, v33
	v_add_f32_e32 v34, 1.0, v34
	v_rcp_f32_e32 v33, v33
	v_rcp_f32_e32 v34, v34
	v_add_f32_e32 v18, v18, v88
	v_mul_f32_e32 v18, 0xbfb8aa3b, v18
	v_add_f32_e32 v19, v19, v88
	v_exp_f32_e32 v18, v18
	s_waitcnt lgkmcnt(0)
	v_mov_b32_e32 v95, v251
	v_mul_f32_e32 v16, v17, v95
	v_mul_f32_e32 v16, 0x3fb8aa3b, v16
	v_mul_f32_e32 v17, v33, v95
	v_exp_f32_e32 v33, v16
	v_mul_f32_e32 v16, v34, v95
	v_mul_f32_e32 v16, 0x3fb8aa3b, v16
	v_exp_f32_e32 v98, v16
	v_add_f32_e32 v16, v35, v94
	v_mul_f32_e32 v16, 0xbfb8aa3b, v16
	v_exp_f32_e32 v16, v16
	v_mul_f32_e32 v17, 0x3fb8aa3b, v17
	v_mul_f32_e32 v19, 0xbfb8aa3b, v19
	v_exp_f32_e32 v96, v17
	v_add_f32_e32 v16, 1.0, v16
	v_rcp_f32_e32 v16, v16
	v_exp_f32_e32 v19, v19
	v_add_f32_e32 v97, 1.0, v97
	v_add_f32_e32 v18, 1.0, v18
	v_mul_f32_e32 v16, v16, v95
	v_mul_f32_e32 v16, 0x3fb8aa3b, v16
	v_exp_f32_e32 v16, v16
	v_fma_f32 v35, -v98, v98, 1.0
	v_rcp_f32_e32 v17, v97
	v_fma_f32 v34, -v33, v33, 1.0
	v_fma_f32 v97, -v96, v96, 1.0
	v_rcp_f32_e32 v18, v18
	v_sqrt_f32_e32 v35, v35
	v_add_f32_e32 v19, 1.0, v19
	v_fma_f32 v99, -v16, v16, 1.0
	v_sqrt_f32_e32 v34, v34
	v_sqrt_f32_e32 v97, v97
	v_rcp_f32_e32 v19, v19
	v_sqrt_f32_e32 v99, v99
	v_mul_f32_e32 v35, v18, v35
	v_add_f32_e32 v18, v36, v94
	v_mul_f32_e32 v32, v32, v34
	v_mul_f32_e32 v34, v17, v97
	v_mul_f32_e32 v17, v19, v99
	v_mul_f32_e32 v18, 0xbfb8aa3b, v18
	v_add_f32_e32 v19, v20, v88
	v_exp_f32_e32 v18, v18
	v_mul_f32_e32 v19, 0xbfb8aa3b, v19
	v_exp_f32_e32 v19, v19
	v_mul_f32_e32 v3, v3, v17
	v_add_f32_e32 v17, 1.0, v18
	v_rcp_f32_e32 v17, v17
	v_add_f32_e32 v18, 1.0, v19
	v_add_f32_e32 v19, v37, v94
	v_mul_f32_e32 v19, 0xbfb8aa3b, v19
	v_exp_f32_e32 v19, v19
	v_mul_f32_e32 v17, v17, v95
	v_mul_f32_e32 v17, 0x3fb8aa3b, v17
	v_exp_f32_e32 v36, v17
	v_add_f32_e32 v17, 1.0, v19
	v_rcp_f32_e32 v17, v17
	v_add_f32_e32 v19, v21, v88
	v_mul_f32_e32 v19, 0xbfb8aa3b, v19
	v_exp_f32_e32 v19, v19
	v_mul_f32_e32 v17, v17, v95
	v_mul_f32_e32 v17, 0x3fb8aa3b, v17
	v_exp_f32_e32 v37, v17
	v_add_f32_e32 v17, v38, v94
	v_mul_f32_e32 v17, 0xbfb8aa3b, v17
	v_exp_f32_e32 v17, v17
	v_add_f32_e32 v23, v23, v88
	v_add_f32_e32 v19, 1.0, v19
	v_fma_f32 v21, -v37, v37, 1.0
	v_add_f32_e32 v17, 1.0, v17
	v_rcp_f32_e32 v17, v17
	v_mul_f32_e32 v23, 0xbfb8aa3b, v23
	v_rcp_f32_e32 v19, v19
	v_sqrt_f32_e32 v21, v21
	v_mul_f32_e32 v17, v17, v95
	v_mul_f32_e32 v17, 0x3fb8aa3b, v17
	v_exp_f32_e32 v38, v17
	v_add_f32_e32 v17, v39, v94
	v_mul_f32_e32 v17, 0xbfb8aa3b, v17
	v_exp_f32_e32 v17, v17
	v_exp_f32_e32 v23, v23
	v_fma_f32 v20, -v36, v36, 1.0
	v_mul_f32_e32 v100, v19, v21
	v_add_f32_e32 v17, 1.0, v17
	v_rcp_f32_e32 v17, v17
	v_add_f32_e32 v23, 1.0, v23
	v_add_f32_e32 v19, v40, v94
	v_rcp_f32_e32 v18, v18
	v_mul_f32_e32 v17, v17, v95
	v_mul_f32_e32 v17, 0x3fb8aa3b, v17
	v_exp_f32_e32 v17, v17
	v_sqrt_f32_e32 v20, v20
	v_rcp_f32_e32 v23, v23
	v_mul_f32_e32 v19, 0xbfb8aa3b, v19
	v_fma_f32 v97, -v17, v17, 1.0
	v_sqrt_f32_e32 v97, v97
	v_add_f32_e32 v21, v24, v88
	v_add_f32_e32 v22, v22, v88
	v_exp_f32_e32 v19, v19
	v_mul_f32_e32 v21, 0xbfb8aa3b, v21
	v_mul_f32_e32 v22, 0xbfb8aa3b, v22
	v_exp_f32_e32 v21, v21
	v_exp_f32_e32 v22, v22
	v_mul_f32_e32 v99, v18, v20
	v_mul_f32_e32 v18, v23, v97
	v_mul_f32_e32 v7, v7, v18
	v_add_f32_e32 v18, 1.0, v19
	v_rcp_f32_e32 v18, v18
	v_add_f32_e32 v19, 1.0, v21
	v_add_f32_e32 v21, v41, v94
	v_add_f32_e32 v22, 1.0, v22
	v_fma_f32 v39, -v38, v38, 1.0
	v_mul_f32_e32 v21, 0xbfb8aa3b, v21
	v_rcp_f32_e32 v22, v22
	v_sqrt_f32_e32 v39, v39
	v_exp_f32_e32 v21, v21
	v_mul_f32_e32 v18, v18, v95
	v_mul_f32_e32 v18, 0x3fb8aa3b, v18
	v_mul_f32_e32 v20, v22, v39
	v_exp_f32_e32 v39, v18
	v_add_f32_e32 v18, 1.0, v21
	v_rcp_f32_e32 v18, v18
	v_add_f32_e32 v21, v25, v88
	v_mul_f32_e32 v21, 0xbfb8aa3b, v21
	v_exp_f32_e32 v21, v21
	v_mul_f32_e32 v18, v18, v95
	v_mul_f32_e32 v18, 0x3fb8aa3b, v18
	v_exp_f32_e32 v40, v18
	v_add_f32_e32 v18, v42, v94
	v_mul_f32_e32 v18, 0xbfb8aa3b, v18
	v_exp_f32_e32 v18, v18
	v_add_f32_e32 v24, v26, v88
	v_add_f32_e32 v26, v27, v88
	v_add_f32_e32 v21, 1.0, v21
	v_add_f32_e32 v18, 1.0, v18
	v_rcp_f32_e32 v18, v18
	v_fma_f32 v23, -v40, v40, 1.0
	v_mul_f32_e32 v26, 0xbfb8aa3b, v26
	v_fma_f32 v22, -v39, v39, 1.0
	v_mul_f32_e32 v18, v18, v95
	v_mul_f32_e32 v18, 0x3fb8aa3b, v18
	v_exp_f32_e32 v41, v18
	v_add_f32_e32 v18, v43, v94
	v_mul_f32_e32 v18, 0xbfb8aa3b, v18
	v_exp_f32_e32 v18, v18
	v_rcp_f32_e32 v21, v21
	v_sqrt_f32_e32 v23, v23
	v_exp_f32_e32 v26, v26
	v_add_f32_e32 v18, 1.0, v18
	v_rcp_f32_e32 v18, v18
	v_rcp_f32_e32 v19, v19
	v_sqrt_f32_e32 v22, v22
	v_add_f32_e32 v26, 1.0, v26
	v_mul_f32_e32 v18, v18, v95
	v_mul_f32_e32 v18, 0x3fb8aa3b, v18
	v_exp_f32_e32 v18, v18
	v_mul_f32_e32 v43, v21, v23
	v_add_f32_e32 v21, v44, v94
	v_rcp_f32_e32 v26, v26
	v_fma_f32 v27, -v18, v18, 1.0
	v_sqrt_f32_e32 v27, v27
	v_mul_f32_e32 v42, v19, v22
	v_mul_f32_e32 v21, 0xbfb8aa3b, v21
	v_add_f32_e32 v22, v28, v88
	v_exp_f32_e32 v21, v21
	v_mul_f32_e32 v22, 0xbfb8aa3b, v22
	v_exp_f32_e32 v22, v22
	v_mul_f32_e32 v19, v26, v27
	v_mul_f32_e32 v11, v11, v19
	v_add_f32_e32 v19, 1.0, v21
	v_rcp_f32_e32 v19, v19
	v_add_f32_e32 v21, 1.0, v22
	v_add_f32_e32 v22, v45, v94
	v_mul_f32_e32 v22, 0xbfb8aa3b, v22
	v_exp_f32_e32 v22, v22
	v_mul_f32_e32 v19, v19, v95
	v_mul_f32_e32 v19, 0x3fb8aa3b, v19
	v_exp_f32_e32 v44, v19
	v_add_f32_e32 v19, 1.0, v22
	v_rcp_f32_e32 v19, v19
	v_mul_f32_e32 v24, 0xbfb8aa3b, v24
	v_exp_f32_e32 v24, v24
	v_fma_f32 v25, -v41, v41, 1.0
	v_mul_f32_e32 v19, v19, v95
	v_mul_f32_e32 v19, 0x3fb8aa3b, v19
	v_exp_f32_e32 v45, v19
	v_add_f32_e32 v19, v46, v94
	v_mul_f32_e32 v19, 0xbfb8aa3b, v19
	v_exp_f32_e32 v19, v19
	v_add_f32_e32 v24, 1.0, v24
	v_rcp_f32_e32 v24, v24
	v_sqrt_f32_e32 v25, v25
	v_add_f32_e32 v19, 1.0, v19
	v_rcp_f32_e32 v19, v19
	v_add_f32_e32 v22, v29, v88
	v_mul_f32_e32 v97, v24, v25
	v_fma_f32 v24, -v45, v45, 1.0
	v_mul_f32_e32 v19, v19, v95
	v_mul_f32_e32 v19, 0x3fb8aa3b, v19
	v_exp_f32_e32 v46, v19
	v_add_f32_e32 v19, v47, v94
	v_mul_f32_e32 v19, 0xbfb8aa3b, v19
	v_exp_f32_e32 v19, v19
	v_sqrt_f32_e32 v25, v24
	v_add_f32_e32 v24, v30, v88
	v_mul_f32_e32 v24, 0xbfb8aa3b, v24
	v_exp_f32_e32 v24, v24
	v_add_f32_e32 v19, 1.0, v19
	v_rcp_f32_e32 v19, v19
	v_fma_f32 v27, -v46, v46, 1.0
	v_add_f32_e32 v24, 1.0, v24
	v_rcp_f32_e32 v26, v24
	v_add_f32_e32 v24, v31, v88
	v_mul_f32_e32 v19, v19, v95
	v_mul_f32_e32 v24, 0xbfb8aa3b, v24
	v_mul_f32_e32 v19, 0x3fb8aa3b, v19
	v_exp_f32_e32 v28, v24
	v_exp_f32_e32 v24, v19
	v_mul_f32_e32 v22, 0xbfb8aa3b, v22
	v_sqrt_f32_e32 v19, v27
	v_add_f32_e32 v27, 1.0, v28
	v_fma_f32 v28, -v24, v24, 1.0
	v_exp_f32_e32 v22, v22
	v_rcp_f32_e32 v27, v27
	v_sqrt_f32_e32 v28, v28
	v_fma_f32 v23, -v44, v44, 1.0
	v_rcp_f32_e32 v21, v21
	v_sqrt_f32_e32 v23, v23
	v_add_f32_e32 v22, 1.0, v22
	v_mul_f32_e32 v94, v26, v19
	v_mul_f32_e32 v19, v27, v28
	v_fmac_f32_e32 v7, 0, v17
	v_rcp_f32_e32 v22, v22
	v_mul_f32_e32 v15, v15, v19
	v_mul_f32_e32 v19, v38, v7
	v_fmac_f32_e32 v3, 0, v16
	v_fmac_f32_e32 v19, v6, v20
	v_mul_f32_e32 v47, v21, v23
	v_mul_f32_e32 v21, v98, v3
	v_mul_f32_e32 v20, v37, v19
	v_fmac_f32_e32 v15, 0, v24
	v_fmac_f32_e32 v21, v2, v35
	v_fmac_f32_e32 v20, v5, v100
	v_mul_f32_e32 v2, v46, v15
	v_mul_f32_e32 v88, v22, v25
	v_mul_f32_e32 v22, v36, v20
	v_fmac_f32_e32 v2, v14, v94
	v_fmac_f32_e32 v22, v4, v99
	v_mul_f32_e32 v4, v45, v2
	v_mul_f32_e32 v23, v96, v21
	v_fmac_f32_e32 v4, v13, v88
	v_fmac_f32_e32 v23, v1, v34
	v_fmac_f32_e32 v11, 0, v18
	v_mul_f32_e32 v14, v24, v46
	v_mul_f32_e32 v6, v44, v4
	v_mul_f32_e32 v25, v33, v23
	v_mul_f32_e32 v5, v41, v11
	v_mul_f32_e32 v13, v45, v14
	v_fmac_f32_e32 v6, v12, v47
	v_fmac_f32_e32 v25, v0, v32
	v_fmac_f32_e32 v5, v10, v97
	v_mul_f32_e32 v12, v44, v13
	ds_bpermute_b32 v0, v137, v6
	v_mul_f32_e32 v10, v40, v5
	ds_bpermute_b32 v35, v137, v12
	v_mul_f32_e32 v28, v18, v41
	v_fmac_f32_e32 v10, v9, v43
	v_mul_f32_e32 v26, v16, v98
	v_mul_f32_e32 v27, v17, v38
	v_mul_f32_e32 v31, v40, v28
	v_mul_f32_e32 v9, v39, v10
	v_mul_f32_e32 v29, v96, v26
	v_mul_f32_e32 v30, v37, v27
	v_fmac_f32_e32 v9, v8, v42
	v_mul_f32_e32 v34, v39, v31
	v_mul_f32_e32 v32, v33, v29
	v_mul_f32_e32 v33, v36, v30
	s_waitcnt lgkmcnt(1)
	v_cndmask_b32_e64 v36, v0, v6, s[4:5]
	v_cndmask_b32_e64 v37, v6, v0, s[4:5]
	ds_bpermute_b32 v0, v137, v34
	ds_bpermute_b32 v40, v137, v9
	s_waitcnt lgkmcnt(2)
	v_cndmask_b32_e64 v8, v12, v35, s[4:5]
	v_fmac_f32_e32 v37, 0, v8
	ds_bpermute_b32 v8, v137, v33
	v_cndmask_b32_e64 v1, v35, v12, s[4:5]
	v_mul_f32_e32 v38, v12, v35
	v_fmac_f32_e32 v36, v1, v37
	s_waitcnt lgkmcnt(2)
	v_cndmask_b32_e64 v1, v0, v34, s[4:5]
	s_waitcnt lgkmcnt(1)
	v_cndmask_b32_e64 v39, v40, v9, s[4:5]
	v_cndmask_b32_e64 v0, v34, v0, s[4:5]
	v_cndmask_b32_e64 v40, v9, v40, s[4:5]
	ds_bpermute_b32 v44, v137, v22
	v_mul_f32_e32 v41, v38, v0
	v_fmac_f32_e32 v40, v0, v36
	v_mul_f32_e32 v42, v1, v41
	v_fmac_f32_e32 v39, v1, v40
	s_waitcnt lgkmcnt(1)
	v_cndmask_b32_e64 v0, v8, v33, s[4:5]
	v_cndmask_b32_e64 v1, v33, v8, s[4:5]
	ds_bpermute_b32 v8, v137, v32
	ds_bpermute_b32 v47, v137, v25
	s_waitcnt lgkmcnt(2)
	v_cndmask_b32_e64 v43, v44, v22, s[4:5]
	v_cndmask_b32_e64 v44, v22, v44, s[4:5]
	v_mul_f32_e32 v45, v1, v42
	v_fmac_f32_e32 v44, v1, v39
	v_mul_f32_e32 v46, v0, v45
	v_fmac_f32_e32 v43, v0, v44
	s_waitcnt lgkmcnt(1)
	v_cndmask_b32_e64 v0, v32, v8, s[4:5]
	s_waitcnt lgkmcnt(0)
	v_cndmask_b32_e64 v47, v25, v47, s[4:5]
	v_mul_f32_e32 v88, v0, v46
	v_fmac_f32_e32 v47, v0, v43
	s_and_saveexec_b64 s[6:7], s[4:5]
	v_mul_f32_e32 v0, v32, v88
	v_fma_f32 v1, v32, v47, v25
	ds_write_b64 v136, v[0:1]
	s_or_b64 exec, exec, s[6:7]
	s_cmp_lt_i32 s64, 7
	s_cselect_b64 s[14:15], -1, 0
	s_cmp_gt_i32 s64, 6
	v_mul_i32_i24_e32 v140, 0xffffff08, v93
	s_waitcnt lgkmcnt(0)
	s_barrier
	s_cbranch_scc1 .LBB0_269
	v_add3_u32 v94, v140, v91, s92
	v_mov_b32_e32 v8, 1.0
	v_mov_b32_e32 v1, 0
	s_mov_b32 s6, 7

.LBB0_272:
	s_or_b64 exec, exec, s[8:9]
	s_setprio 1
	ds_read_b128 v[0:3], v145 offset:24576
	ds_read_b128 v[4:7], v145 offset:57344
	s_waitcnt lgkmcnt(1)
	v_mfma_f32_32x32x16_bf16 v[32:47], v[48:51], v[0:3], 0
	s_waitcnt lgkmcnt(0)
	v_mfma_f32_32x32x16_bf16 v[16:31], v[48:51], v[4:7], 0
	ds_read_b128 v[0:3], v147 offset:24576
	ds_read_b128 v[4:7], v147 offset:57344
	s_waitcnt lgkmcnt(1)
	v_mfma_f32_32x32x16_bf16 v[32:47], v[52:55], v[0:3], v[32:47]
	s_waitcnt lgkmcnt(0)
	v_mfma_f32_32x32x16_bf16 v[16:31], v[52:55], v[4:7], v[16:31]
	ds_read_b128 v[0:3], v142 offset:24576
	ds_read_b128 v[4:7], v142 offset:57344
	s_waitcnt lgkmcnt(1)
	v_mfma_f32_32x32x16_bf16 v[32:47], v[56:59], v[0:3], v[32:47]
	s_waitcnt lgkmcnt(0)
	v_mfma_f32_32x32x16_bf16 v[16:31], v[56:59], v[4:7], v[16:31]
	ds_read_b128 v[0:3], v146 offset:24576
	ds_read_b128 v[4:7], v146 offset:57344
	s_waitcnt lgkmcnt(1)
	v_mfma_f32_32x32x16_bf16 v[32:47], v[60:63], v[0:3], v[32:47]
	s_waitcnt lgkmcnt(0)
	v_mfma_f32_32x32x16_bf16 v[16:31], v[60:63], v[4:7], v[16:31]
	ds_read_b128 v[0:3], v141 offset:24576
	ds_read_b128 v[4:7], v141 offset:57344
	s_waitcnt lgkmcnt(1)
	v_mfma_f32_32x32x16_bf16 v[32:47], v[64:67], v[0:3], v[32:47]
	s_waitcnt lgkmcnt(0)
	v_mfma_f32_32x32x16_bf16 v[16:31], v[64:67], v[4:7], v[16:31]
	ds_read_b128 v[0:3], v144 offset:24576
	ds_read_b128 v[4:7], v144 offset:57344
	s_waitcnt lgkmcnt(1)
	v_mfma_f32_32x32x16_bf16 v[32:47], v[68:71], v[0:3], v[32:47]
	s_waitcnt lgkmcnt(0)
	v_mfma_f32_32x32x16_bf16 v[16:31], v[68:71], v[4:7], v[16:31]
	ds_read_b128 v[0:3], v139 offset:24576
	ds_read_b128 v[4:7], v139 offset:57344
	s_waitcnt lgkmcnt(1)
	v_mfma_f32_32x32x16_bf16 v[32:47], v[72:75], v[0:3], v[32:47]
	s_waitcnt lgkmcnt(0)
	v_mfma_f32_32x32x16_bf16 v[16:31], v[72:75], v[4:7], v[16:31]
	ds_read_b128 v[0:3], v143 offset:24576
	ds_read_b128 v[4:7], v143 offset:57344
	s_waitcnt lgkmcnt(1)
	v_mfma_f32_32x32x16_bf16 v[32:47], v[76:79], v[0:3], v[32:47]
	s_waitcnt lgkmcnt(0)
	v_mfma_f32_32x32x16_bf16 v[16:31], v[76:79], v[4:7], v[16:31]
	v_mfma_f32_32x32x16_bf16 v[0:15], v[56:59], v[80:83], 0
	v_mfma_f32_32x32x16_bf16 v[0:15], v[60:63], v[84:87], v[0:15]
	s_setprio 0
	v_lshl_or_b32 v93, v138, 2, v133
	s_waitcnt vmcnt(16)
	ds_read_b32 v251, v167 offset:128
	v_mov_b32_e32 v148, v173
	v_mov_b32_e32 v93, v174
	v_add_f32_e32 v32, v32, v148
	v_add_f32_e32 v16, v16, v93
	v_mul_f32_e32 v32, 0xbfb8aa3b, v32
	v_mul_f32_e32 v16, 0xbfb8aa3b, v16
	v_exp_f32_e32 v32, v32
	v_exp_f32_e32 v150, v16
	v_add_f32_e32 v17, v17, v93
	v_mul_f32_e32 v17, 0xbfb8aa3b, v17
	v_exp_f32_e32 v151, v17
	v_add_f32_e32 v32, 1.0, v32
	v_add_f32_e32 v150, 1.0, v150
	v_rcp_f32_e32 v17, v32
	v_rcp_f32_e32 v32, v150
	v_add_f32_e32 v33, v33, v148
	v_add_f32_e32 v34, v34, v148
	v_mul_f32_e32 v33, 0xbfb8aa3b, v33
	v_mul_f32_e32 v34, 0xbfb8aa3b, v34
	v_exp_f32_e32 v33, v33
	v_exp_f32_e32 v34, v34
	v_add_f32_e32 v33, 1.0, v33
	v_add_f32_e32 v34, 1.0, v34
	v_rcp_f32_e32 v33, v33
	v_rcp_f32_e32 v34, v34
	v_add_f32_e32 v18, v18, v93
	v_mul_f32_e32 v18, 0xbfb8aa3b, v18
	v_add_f32_e32 v19, v19, v93
	v_exp_f32_e32 v18, v18
	s_waitcnt lgkmcnt(0)
	v_mov_b32_e32 v149, v251
	v_mul_f32_e32 v16, v17, v149
	v_mul_f32_e32 v16, 0x3fb8aa3b, v16
	v_mul_f32_e32 v17, v33, v149
	v_exp_f32_e32 v33, v16
	v_mul_f32_e32 v16, v34, v149
	v_mul_f32_e32 v16, 0x3fb8aa3b, v16
	v_exp_f32_e32 v152, v16
	v_add_f32_e32 v16, v35, v148
	v_mul_f32_e32 v16, 0xbfb8aa3b, v16
	v_exp_f32_e32 v16, v16
	v_mul_f32_e32 v17, 0x3fb8aa3b, v17
	v_mul_f32_e32 v19, 0xbfb8aa3b, v19
	v_exp_f32_e32 v150, v17
	v_add_f32_e32 v16, 1.0, v16
	v_rcp_f32_e32 v16, v16
	v_exp_f32_e32 v19, v19
	v_add_f32_e32 v151, 1.0, v151
	v_add_f32_e32 v18, 1.0, v18
	v_mul_f32_e32 v16, v16, v149
	v_mul_f32_e32 v16, 0x3fb8aa3b, v16
	v_exp_f32_e32 v16, v16
	v_fma_f32 v35, -v152, v152, 1.0
	v_rcp_f32_e32 v17, v151
	v_fma_f32 v34, -v33, v33, 1.0
	v_fma_f32 v151, -v150, v150, 1.0
	v_rcp_f32_e32 v18, v18
	v_sqrt_f32_e32 v35, v35
	v_add_f32_e32 v19, 1.0, v19
	v_fma_f32 v153, -v16, v16, 1.0
	v_sqrt_f32_e32 v34, v34
	v_sqrt_f32_e32 v151, v151
	v_rcp_f32_e32 v19, v19
	v_sqrt_f32_e32 v153, v153
	v_mul_f32_e32 v35, v18, v35
	v_add_f32_e32 v18, v36, v148
	v_mul_f32_e32 v32, v32, v34
	v_mul_f32_e32 v34, v17, v151
	v_mul_f32_e32 v17, v19, v153
	v_mul_f32_e32 v18, 0xbfb8aa3b, v18
	v_add_f32_e32 v19, v20, v93
	v_exp_f32_e32 v18, v18
	v_mul_f32_e32 v19, 0xbfb8aa3b, v19
	v_exp_f32_e32 v19, v19
	v_mul_f32_e32 v3, v3, v17
	v_add_f32_e32 v17, 1.0, v18
	v_rcp_f32_e32 v17, v17
	v_add_f32_e32 v18, 1.0, v19
	v_add_f32_e32 v19, v37, v148
	v_mul_f32_e32 v19, 0xbfb8aa3b, v19
	v_exp_f32_e32 v19, v19
	v_mul_f32_e32 v17, v17, v149
	v_mul_f32_e32 v17, 0x3fb8aa3b, v17
	v_exp_f32_e32 v36, v17
	v_add_f32_e32 v17, 1.0, v19
	v_rcp_f32_e32 v17, v17
	v_add_f32_e32 v19, v21, v93
	v_mul_f32_e32 v19, 0xbfb8aa3b, v19
	v_exp_f32_e32 v19, v19
	v_mul_f32_e32 v17, v17, v149
	v_mul_f32_e32 v17, 0x3fb8aa3b, v17
	v_exp_f32_e32 v37, v17
	v_add_f32_e32 v17, v38, v148
	v_mul_f32_e32 v17, 0xbfb8aa3b, v17
	v_exp_f32_e32 v17, v17
	v_add_f32_e32 v23, v23, v93
	v_add_f32_e32 v19, 1.0, v19
	v_fma_f32 v21, -v37, v37, 1.0
	v_add_f32_e32 v17, 1.0, v17
	v_rcp_f32_e32 v17, v17
	v_mul_f32_e32 v23, 0xbfb8aa3b, v23
	v_fma_f32 v20, -v36, v36, 1.0
	v_rcp_f32_e32 v19, v19
	v_mul_f32_e32 v17, v17, v149
	v_mul_f32_e32 v17, 0x3fb8aa3b, v17
	v_exp_f32_e32 v38, v17
	v_add_f32_e32 v17, v39, v148
	v_mul_f32_e32 v17, 0xbfb8aa3b, v17
	v_exp_f32_e32 v17, v17
	v_sqrt_f32_e32 v21, v21
	v_exp_f32_e32 v23, v23
	v_rcp_f32_e32 v18, v18
	v_add_f32_e32 v17, 1.0, v17
	v_rcp_f32_e32 v17, v17
	v_sqrt_f32_e32 v20, v20
	v_add_f32_e32 v23, 1.0, v23
	v_mul_f32_e32 v154, v19, v21
	v_mul_f32_e32 v17, v17, v149
	v_mul_f32_e32 v17, 0x3fb8aa3b, v17
	v_exp_f32_e32 v17, v17
	v_add_f32_e32 v19, v40, v148
	v_rcp_f32_e32 v23, v23
	v_mul_f32_e32 v153, v18, v20
	v_fma_f32 v151, -v17, v17, 1.0
	v_sqrt_f32_e32 v151, v151
	v_mul_f32_e32 v19, 0xbfb8aa3b, v19
	v_add_f32_e32 v20, v24, v93
	v_add_f32_e32 v22, v22, v93
	v_exp_f32_e32 v19, v19
	v_mul_f32_e32 v20, 0xbfb8aa3b, v20
	v_mul_f32_e32 v22, 0xbfb8aa3b, v22
	v_exp_f32_e32 v20, v20
	v_exp_f32_e32 v22, v22
	v_mul_f32_e32 v18, v23, v151
	v_mul_f32_e32 v7, v7, v18
	v_add_f32_e32 v18, 1.0, v19
	v_rcp_f32_e32 v18, v18
	v_add_f32_e32 v19, 1.0, v20
	v_add_f32_e32 v20, v41, v148
	v_add_f32_e32 v22, 1.0, v22
	v_fma_f32 v39, -v38, v38, 1.0
	v_mul_f32_e32 v20, 0xbfb8aa3b, v20
	v_rcp_f32_e32 v22, v22
	v_sqrt_f32_e32 v39, v39
	v_exp_f32_e32 v20, v20
	v_mul_f32_e32 v18, v18, v149
	v_mul_f32_e32 v18, 0x3fb8aa3b, v18
	v_mul_f32_e32 v21, v22, v39
	v_exp_f32_e32 v39, v18
	v_add_f32_e32 v18, 1.0, v20
	v_rcp_f32_e32 v18, v18
	v_add_f32_e32 v20, v25, v93
	v_mul_f32_e32 v20, 0xbfb8aa3b, v20
	v_exp_f32_e32 v20, v20
	v_mul_f32_e32 v18, v18, v149
	v_mul_f32_e32 v18, 0x3fb8aa3b, v18
	v_exp_f32_e32 v40, v18
	v_add_f32_e32 v18, v42, v148
	v_mul_f32_e32 v18, 0xbfb8aa3b, v18
	v_exp_f32_e32 v18, v18
	v_add_f32_e32 v24, v26, v93
	v_add_f32_e32 v26, v27, v93
	v_add_f32_e32 v20, 1.0, v20
	v_add_f32_e32 v18, 1.0, v18
	v_rcp_f32_e32 v18, v18
	v_fma_f32 v23, -v40, v40, 1.0
	v_mul_f32_e32 v26, 0xbfb8aa3b, v26
	v_fma_f32 v22, -v39, v39, 1.0
	v_mul_f32_e32 v18, v18, v149
	v_mul_f32_e32 v18, 0x3fb8aa3b, v18
	v_exp_f32_e32 v41, v18
	v_add_f32_e32 v18, v43, v148
	v_mul_f32_e32 v18, 0xbfb8aa3b, v18
	v_exp_f32_e32 v18, v18
	v_rcp_f32_e32 v20, v20
	v_sqrt_f32_e32 v23, v23
	v_exp_f32_e32 v26, v26
	v_add_f32_e32 v18, 1.0, v18
	v_rcp_f32_e32 v18, v18
	v_rcp_f32_e32 v19, v19
	v_sqrt_f32_e32 v22, v22
	v_add_f32_e32 v26, 1.0, v26
	v_mul_f32_e32 v18, v18, v149
	v_mul_f32_e32 v18, 0x3fb8aa3b, v18
	v_exp_f32_e32 v18, v18
	v_mul_f32_e32 v43, v20, v23
	v_add_f32_e32 v20, v44, v148
	v_rcp_f32_e32 v26, v26
	v_fma_f32 v27, -v18, v18, 1.0
	v_sqrt_f32_e32 v27, v27
	v_mul_f32_e32 v42, v19, v22
	v_mul_f32_e32 v20, 0xbfb8aa3b, v20
	v_add_f32_e32 v22, v28, v93
	v_exp_f32_e32 v20, v20
	v_mul_f32_e32 v22, 0xbfb8aa3b, v22
	v_exp_f32_e32 v22, v22
	v_mul_f32_e32 v19, v26, v27
	v_mul_f32_e32 v11, v11, v19
	v_add_f32_e32 v19, 1.0, v20
	v_rcp_f32_e32 v19, v19
	v_add_f32_e32 v20, 1.0, v22
	v_add_f32_e32 v22, v45, v148
	v_mul_f32_e32 v22, 0xbfb8aa3b, v22
	v_exp_f32_e32 v22, v22
	v_mul_f32_e32 v19, v19, v149
	v_mul_f32_e32 v19, 0x3fb8aa3b, v19
	v_exp_f32_e32 v44, v19
	v_add_f32_e32 v19, 1.0, v22
	v_rcp_f32_e32 v19, v19
	v_mul_f32_e32 v24, 0xbfb8aa3b, v24
	v_exp_f32_e32 v24, v24
	v_add_f32_e32 v22, v29, v93
	v_mul_f32_e32 v19, v19, v149
	v_mul_f32_e32 v19, 0x3fb8aa3b, v19
	v_exp_f32_e32 v45, v19
	v_add_f32_e32 v19, v46, v148
	v_mul_f32_e32 v19, 0xbfb8aa3b, v19
	v_exp_f32_e32 v19, v19
	v_mul_f32_e32 v22, 0xbfb8aa3b, v22
	v_add_f32_e32 v24, 1.0, v24
	v_fma_f32 v25, -v41, v41, 1.0
	v_add_f32_e32 v19, 1.0, v19
	v_rcp_f32_e32 v19, v19
	v_exp_f32_e32 v22, v22
	v_rcp_f32_e32 v24, v24
	v_sqrt_f32_e32 v25, v25
	v_mul_f32_e32 v19, v19, v149
	v_mul_f32_e32 v19, 0x3fb8aa3b, v19
	v_exp_f32_e32 v46, v19
	v_add_f32_e32 v19, v47, v148
	v_mul_f32_e32 v19, 0xbfb8aa3b, v19
	v_add_f32_e32 v22, 1.0, v22
	v_exp_f32_e32 v19, v19
	v_mul_f32_e32 v151, v24, v25
	v_rcp_f32_e32 v24, v22
	v_fma_f32 v22, -v45, v45, 1.0
	v_sqrt_f32_e32 v25, v22
	v_add_f32_e32 v22, v30, v93
	v_mul_f32_e32 v22, 0xbfb8aa3b, v22
	v_exp_f32_e32 v22, v22
	v_add_f32_e32 v19, 1.0, v19
	v_rcp_f32_e32 v19, v19
	v_fma_f32 v27, -v46, v46, 1.0
	v_add_f32_e32 v22, 1.0, v22
	v_rcp_f32_e32 v26, v22
	v_add_f32_e32 v22, v31, v93
	v_mul_f32_e32 v19, v19, v149
	v_mul_f32_e32 v22, 0xbfb8aa3b, v22
	v_mul_f32_e32 v19, 0x3fb8aa3b, v19
	v_exp_f32_e32 v28, v22
	v_exp_f32_e32 v22, v19
	v_sqrt_f32_e32 v19, v27
	v_fma_f32 v23, -v44, v44, 1.0
	v_add_f32_e32 v27, 1.0, v28
	v_fma_f32 v28, -v22, v22, 1.0
	v_rcp_f32_e32 v27, v27
	v_sqrt_f32_e32 v28, v28
	v_rcp_f32_e32 v20, v20
	v_sqrt_f32_e32 v23, v23
	v_mul_f32_e32 v148, v26, v19
	v_mul_f32_e32 v19, v27, v28
	v_fmac_f32_e32 v7, 0, v17
	v_mul_f32_e32 v15, v15, v19
	v_mul_f32_e32 v19, v38, v7
	v_fmac_f32_e32 v19, v6, v21
	v_fmac_f32_e32 v3, 0, v16
	v_mul_f32_e32 v21, v37, v19
	v_mul_f32_e32 v47, v20, v23
	v_mul_f32_e32 v20, v152, v3
	v_fmac_f32_e32 v21, v5, v154
	v_fmac_f32_e32 v15, 0, v22
	v_mul_f32_e32 v93, v24, v25
	v_fmac_f32_e32 v20, v2, v35
	v_mul_f32_e32 v24, v36, v21
	v_fmac_f32_e32 v11, 0, v18
	v_mul_f32_e32 v2, v46, v15
	v_fmac_f32_e32 v24, v4, v153
	v_mul_f32_e32 v4, v41, v11
	v_fmac_f32_e32 v2, v14, v148
	v_fmac_f32_e32 v4, v10, v151
	v_mul_f32_e32 v5, v45, v2
	v_mul_f32_e32 v23, v150, v20
	v_mul_f32_e32 v6, v40, v4
	v_fmac_f32_e32 v5, v13, v93
	v_fmac_f32_e32 v23, v1, v34
	v_fmac_f32_e32 v6, v9, v43
	v_mul_f32_e32 v14, v22, v46
	v_mul_f32_e32 v9, v44, v5
	v_mul_f32_e32 v25, v33, v23
	v_mul_f32_e32 v13, v45, v14
	v_fmac_f32_e32 v9, v12, v47
	v_fmac_f32_e32 v25, v0, v32
	v_mul_f32_e32 v12, v44, v13
	ds_bpermute_b32 v0, v137, v9
	ds_bpermute_b32 v35, v137, v12
	v_mul_f32_e32 v28, v18, v41
	v_mul_f32_e32 v26, v16, v152
	v_mul_f32_e32 v27, v17, v38
	v_mul_f32_e32 v31, v40, v28
	v_mul_f32_e32 v10, v39, v6
	v_mul_f32_e32 v29, v150, v26
	v_mul_f32_e32 v30, v37, v27
	v_fmac_f32_e32 v10, v8, v42
	v_mul_f32_e32 v34, v39, v31
	v_mul_f32_e32 v32, v33, v29
	v_mul_f32_e32 v33, v36, v30
	s_waitcnt lgkmcnt(1)
	v_cndmask_b32_e64 v36, v0, v9, s[4:5]
	v_cndmask_b32_e64 v37, v9, v0, s[4:5]
	ds_bpermute_b32 v0, v137, v34
	ds_bpermute_b32 v40, v137, v10
	s_waitcnt lgkmcnt(2)
	v_cndmask_b32_e64 v8, v12, v35, s[4:5]
	v_fmac_f32_e32 v37, 0, v8
	ds_bpermute_b32 v8, v137, v33
	v_cndmask_b32_e64 v1, v35, v12, s[4:5]
	v_mul_f32_e32 v38, v12, v35
	v_fmac_f32_e32 v36, v1, v37
	s_waitcnt lgkmcnt(2)
	v_cndmask_b32_e64 v1, v0, v34, s[4:5]
	s_waitcnt lgkmcnt(1)
	v_cndmask_b32_e64 v39, v40, v10, s[4:5]
	v_cndmask_b32_e64 v0, v34, v0, s[4:5]
	v_cndmask_b32_e64 v40, v10, v40, s[4:5]
	ds_bpermute_b32 v44, v137, v24
	v_mul_f32_e32 v41, v38, v0
	v_fmac_f32_e32 v40, v0, v36
	v_mul_f32_e32 v42, v1, v41
	v_fmac_f32_e32 v39, v1, v40
	s_waitcnt lgkmcnt(1)
	v_cndmask_b32_e64 v0, v8, v33, s[4:5]
	v_cndmask_b32_e64 v1, v33, v8, s[4:5]
	ds_bpermute_b32 v8, v137, v32
	ds_bpermute_b32 v47, v137, v25
	s_waitcnt lgkmcnt(2)
	v_cndmask_b32_e64 v43, v44, v24, s[4:5]
	v_cndmask_b32_e64 v44, v24, v44, s[4:5]
	v_mul_f32_e32 v45, v1, v42
	v_fmac_f32_e32 v44, v1, v39
	v_mul_f32_e32 v46, v0, v45
	v_fmac_f32_e32 v43, v0, v44
	s_waitcnt lgkmcnt(1)
	v_cndmask_b32_e64 v0, v32, v8, s[4:5]
	s_waitcnt lgkmcnt(0)
	v_cndmask_b32_e64 v47, v25, v47, s[4:5]
	v_mul_f32_e32 v93, v0, v46
	v_fmac_f32_e32 v47, v0, v43
	s_and_saveexec_b64 s[8:9], s[4:5]
	v_mul_f32_e32 v0, v32, v93
	v_fma_f32 v1, v32, v47, v25
	ds_write_b64 v136, v[0:1] offset:2048
	s_or_b64 exec, exec, s[8:9]
	v_cndmask_b32_e64 v0, 0, 1, s[14:15]
	v_cmp_ne_u32_e64 s[8:9], 1, v0
	s_andn2_b64 vcc, exec, s[14:15]
	s_waitcnt lgkmcnt(0)
	s_barrier
	s_cbranch_vccnz .LBB0_277
	v_add3_u32 v148, v140, v91, s93
	v_mov_b32_e32 v8, 1.0
	v_mov_b32_e32 v1, 0
	s_mov_b32 s12, 7

.LBB0_280:
	s_or_b64 exec, exec, s[12:13]
	s_setprio 1
	ds_read_b128 v[0:3], v145 offset:32768
	ds_read_b128 v[4:7], v147 offset:32768
	v_add_u32_e32 v8, 0x8000, v147
	s_waitcnt lgkmcnt(1)
	v_mfma_f32_32x32x16_bf16 v[32:47], v[48:51], v[0:3], 0
	v_add_u32_e32 v0, 0x8000, v145
	ds_read_b128 v[0:3], v0 offset:32768
	ds_read_b128 v[8:11], v8 offset:32768
	s_waitcnt lgkmcnt(1)
	v_mfma_f32_32x32x16_bf16 v[16:31], v[48:51], v[0:3], 0
	v_mfma_f32_32x32x16_bf16 v[32:47], v[52:55], v[4:7], v[32:47]
	ds_read_b128 v[0:3], v142 offset:32768
	ds_read_b128 v[4:7], v146 offset:32768
	s_waitcnt lgkmcnt(2)
	v_mfma_f32_32x32x16_bf16 v[16:31], v[52:55], v[8:11], v[16:31]
	v_add_u32_e32 v8, 0x8000, v146
	ds_read_b128 v[8:11], v8 offset:32768
	s_waitcnt lgkmcnt(2)
	v_mfma_f32_32x32x16_bf16 v[32:47], v[56:59], v[0:3], v[32:47]
	v_add_u32_e32 v0, 0x8000, v142
	ds_read_b128 v[0:3], v0 offset:32768
	s_waitcnt lgkmcnt(0)
	v_mfma_f32_32x32x16_bf16 v[16:31], v[56:59], v[0:3], v[16:31]
	v_mfma_f32_32x32x16_bf16 v[32:47], v[60:63], v[4:7], v[32:47]
	ds_read_b128 v[0:3], v141 offset:32768
	ds_read_b128 v[4:7], v144 offset:32768
	v_mfma_f32_32x32x16_bf16 v[16:31], v[60:63], v[8:11], v[16:31]
	v_add_u32_e32 v8, 0x8000, v144
	ds_read_b128 v[8:11], v8 offset:32768
	s_waitcnt lgkmcnt(2)
	v_mfma_f32_32x32x16_bf16 v[32:47], v[64:67], v[0:3], v[32:47]
	v_add_u32_e32 v0, 0x8000, v141
	ds_read_b128 v[0:3], v0 offset:32768
	s_waitcnt lgkmcnt(0)
	v_mfma_f32_32x32x16_bf16 v[16:31], v[64:67], v[0:3], v[16:31]
	v_mfma_f32_32x32x16_bf16 v[32:47], v[68:71], v[4:7], v[32:47]
	ds_read_b128 v[0:3], v139 offset:32768
	ds_read_b128 v[4:7], v143 offset:32768
	v_mfma_f32_32x32x16_bf16 v[16:31], v[68:71], v[8:11], v[16:31]
	v_add_u32_e32 v8, 0x8000, v143
	ds_read_b128 v[8:11], v8 offset:32768
	s_waitcnt lgkmcnt(2)
	v_mfma_f32_32x32x16_bf16 v[32:47], v[72:75], v[0:3], v[32:47]
	v_add_u32_e32 v0, 0x8000, v139
	ds_read_b128 v[0:3], v0 offset:32768
	s_waitcnt lgkmcnt(0)
	v_mfma_f32_32x32x16_bf16 v[16:31], v[72:75], v[0:3], v[16:31]
	v_mfma_f32_32x32x16_bf16 v[32:47], v[76:79], v[4:7], v[32:47]
	v_mfma_f32_32x32x16_bf16 v[16:31], v[76:79], v[8:11], v[16:31]
	v_mfma_f32_32x32x16_bf16 v[0:15], v[64:67], v[80:83], 0
	v_mfma_f32_32x32x16_bf16 v[0:15], v[68:71], v[84:87], v[0:15]
	s_setprio 0
	v_lshl_or_b32 v93, v138, 2, v134
	s_waitcnt vmcnt(16)
	ds_read_b32 v251, v167 offset:256
	v_mov_b32_e32 v148, v173
	v_mov_b32_e32 v93, v174
	v_add_f32_e32 v32, v32, v148
	v_add_f32_e32 v16, v16, v93
	v_mul_f32_e32 v32, 0xbfb8aa3b, v32
	v_mul_f32_e32 v16, 0xbfb8aa3b, v16
	v_exp_f32_e32 v32, v32
	v_exp_f32_e32 v150, v16
	v_add_f32_e32 v17, v17, v93
	v_mul_f32_e32 v17, 0xbfb8aa3b, v17
	v_exp_f32_e32 v151, v17
	v_add_f32_e32 v32, 1.0, v32
	v_add_f32_e32 v150, 1.0, v150
	v_rcp_f32_e32 v17, v32
	v_rcp_f32_e32 v32, v150
	v_add_f32_e32 v33, v33, v148
	v_add_f32_e32 v34, v34, v148
	v_mul_f32_e32 v33, 0xbfb8aa3b, v33
	v_mul_f32_e32 v34, 0xbfb8aa3b, v34
	v_exp_f32_e32 v33, v33
	v_exp_f32_e32 v34, v34
	v_add_f32_e32 v33, 1.0, v33
	v_add_f32_e32 v34, 1.0, v34
	v_rcp_f32_e32 v33, v33
	v_rcp_f32_e32 v34, v34
	v_add_f32_e32 v18, v18, v93
	v_mul_f32_e32 v18, 0xbfb8aa3b, v18
	v_add_f32_e32 v19, v19, v93
	v_exp_f32_e32 v18, v18
	s_waitcnt lgkmcnt(0)
	v_mov_b32_e32 v149, v251
	v_mul_f32_e32 v16, v17, v149
	v_mul_f32_e32 v16, 0x3fb8aa3b, v16
	v_mul_f32_e32 v17, v33, v149
	v_exp_f32_e32 v33, v16
	v_mul_f32_e32 v16, v34, v149
	v_mul_f32_e32 v16, 0x3fb8aa3b, v16
	v_exp_f32_e32 v152, v16
	v_add_f32_e32 v16, v35, v148
	v_mul_f32_e32 v16, 0xbfb8aa3b, v16
	v_exp_f32_e32 v16, v16
	v_mul_f32_e32 v17, 0x3fb8aa3b, v17
	v_mul_f32_e32 v19, 0xbfb8aa3b, v19
	v_exp_f32_e32 v150, v17
	v_add_f32_e32 v16, 1.0, v16
	v_rcp_f32_e32 v16, v16
	v_exp_f32_e32 v19, v19
	v_add_f32_e32 v151, 1.0, v151
	v_add_f32_e32 v18, 1.0, v18
	v_mul_f32_e32 v16, v16, v149
	v_mul_f32_e32 v16, 0x3fb8aa3b, v16
	v_exp_f32_e32 v16, v16
	v_fma_f32 v35, -v152, v152, 1.0
	v_rcp_f32_e32 v17, v151
	v_fma_f32 v34, -v33, v33, 1.0
	v_fma_f32 v151, -v150, v150, 1.0
	v_rcp_f32_e32 v18, v18
	v_sqrt_f32_e32 v35, v35
	v_add_f32_e32 v19, 1.0, v19
	v_fma_f32 v153, -v16, v16, 1.0
	v_sqrt_f32_e32 v34, v34
	v_sqrt_f32_e32 v151, v151
	v_rcp_f32_e32 v19, v19
	v_sqrt_f32_e32 v153, v153
	v_mul_f32_e32 v35, v18, v35
	v_add_f32_e32 v18, v36, v148
	v_mul_f32_e32 v32, v32, v34
	v_mul_f32_e32 v34, v17, v151
	v_mul_f32_e32 v17, v19, v153
	v_mul_f32_e32 v18, 0xbfb8aa3b, v18
	v_add_f32_e32 v19, v20, v93
	v_exp_f32_e32 v18, v18
	v_mul_f32_e32 v19, 0xbfb8aa3b, v19
	v_exp_f32_e32 v19, v19
	v_mul_f32_e32 v3, v3, v17
	v_add_f32_e32 v17, 1.0, v18
	v_rcp_f32_e32 v17, v17
	v_add_f32_e32 v18, 1.0, v19
	v_add_f32_e32 v19, v37, v148
	v_mul_f32_e32 v19, 0xbfb8aa3b, v19
	v_exp_f32_e32 v19, v19
	v_mul_f32_e32 v17, v17, v149
	v_mul_f32_e32 v17, 0x3fb8aa3b, v17
	v_exp_f32_e32 v36, v17
	v_add_f32_e32 v17, 1.0, v19
	v_rcp_f32_e32 v17, v17
	v_add_f32_e32 v19, v21, v93
	v_mul_f32_e32 v19, 0xbfb8aa3b, v19
	v_exp_f32_e32 v19, v19
	v_mul_f32_e32 v17, v17, v149
	v_mul_f32_e32 v17, 0x3fb8aa3b, v17
	v_exp_f32_e32 v37, v17
	v_add_f32_e32 v17, v38, v148
	v_mul_f32_e32 v17, 0xbfb8aa3b, v17
	v_exp_f32_e32 v17, v17
	v_add_f32_e32 v23, v23, v93
	v_add_f32_e32 v19, 1.0, v19
	v_fma_f32 v21, -v37, v37, 1.0
	v_add_f32_e32 v17, 1.0, v17
	v_rcp_f32_e32 v17, v17
	v_mul_f32_e32 v23, 0xbfb8aa3b, v23
	v_fma_f32 v20, -v36, v36, 1.0
	v_rcp_f32_e32 v19, v19
	v_mul_f32_e32 v17, v17, v149
	v_mul_f32_e32 v17, 0x3fb8aa3b, v17
	v_exp_f32_e32 v38, v17
	v_add_f32_e32 v17, v39, v148
	v_mul_f32_e32 v17, 0xbfb8aa3b, v17
	v_exp_f32_e32 v17, v17
	v_sqrt_f32_e32 v21, v21
	v_exp_f32_e32 v23, v23
	v_rcp_f32_e32 v18, v18
	v_add_f32_e32 v17, 1.0, v17
	v_rcp_f32_e32 v17, v17
	v_sqrt_f32_e32 v20, v20
	v_add_f32_e32 v23, 1.0, v23
	v_mul_f32_e32 v154, v19, v21
	v_mul_f32_e32 v17, v17, v149
	v_mul_f32_e32 v17, 0x3fb8aa3b, v17
	v_exp_f32_e32 v17, v17
	v_add_f32_e32 v19, v40, v148
	v_rcp_f32_e32 v23, v23
	v_mul_f32_e32 v153, v18, v20
	v_fma_f32 v151, -v17, v17, 1.0
	v_sqrt_f32_e32 v151, v151
	v_mul_f32_e32 v19, 0xbfb8aa3b, v19
	v_add_f32_e32 v20, v24, v93
	v_add_f32_e32 v22, v22, v93
	v_exp_f32_e32 v19, v19
	v_mul_f32_e32 v20, 0xbfb8aa3b, v20
	v_mul_f32_e32 v22, 0xbfb8aa3b, v22
	v_exp_f32_e32 v20, v20
	v_exp_f32_e32 v22, v22
	v_mul_f32_e32 v18, v23, v151
	v_mul_f32_e32 v7, v7, v18
	v_add_f32_e32 v18, 1.0, v19
	v_rcp_f32_e32 v18, v18
	v_add_f32_e32 v19, 1.0, v20
	v_add_f32_e32 v20, v41, v148
	v_add_f32_e32 v22, 1.0, v22
	v_fma_f32 v39, -v38, v38, 1.0
	v_mul_f32_e32 v20, 0xbfb8aa3b, v20
	v_rcp_f32_e32 v22, v22
	v_sqrt_f32_e32 v39, v39
	v_exp_f32_e32 v20, v20
	v_mul_f32_e32 v18, v18, v149
	v_mul_f32_e32 v18, 0x3fb8aa3b, v18
	v_mul_f32_e32 v21, v22, v39
	v_exp_f32_e32 v39, v18
	v_add_f32_e32 v18, 1.0, v20
	v_rcp_f32_e32 v18, v18
	v_add_f32_e32 v20, v25, v93
	v_mul_f32_e32 v20, 0xbfb8aa3b, v20
	v_exp_f32_e32 v20, v20
	v_mul_f32_e32 v18, v18, v149
	v_mul_f32_e32 v18, 0x3fb8aa3b, v18
	v_exp_f32_e32 v40, v18
	v_add_f32_e32 v18, v42, v148
	v_mul_f32_e32 v18, 0xbfb8aa3b, v18
	v_exp_f32_e32 v18, v18
	v_add_f32_e32 v24, v26, v93
	v_add_f32_e32 v26, v27, v93
	v_add_f32_e32 v20, 1.0, v20
	v_add_f32_e32 v18, 1.0, v18
	v_rcp_f32_e32 v18, v18
	v_fma_f32 v23, -v40, v40, 1.0
	v_mul_f32_e32 v26, 0xbfb8aa3b, v26
	v_fma_f32 v22, -v39, v39, 1.0
	v_mul_f32_e32 v18, v18, v149
	v_mul_f32_e32 v18, 0x3fb8aa3b, v18
	v_exp_f32_e32 v41, v18
	v_add_f32_e32 v18, v43, v148
	v_mul_f32_e32 v18, 0xbfb8aa3b, v18
	v_exp_f32_e32 v18, v18
	v_rcp_f32_e32 v20, v20
	v_sqrt_f32_e32 v23, v23
	v_exp_f32_e32 v26, v26
	v_add_f32_e32 v18, 1.0, v18
	v_rcp_f32_e32 v18, v18
	v_rcp_f32_e32 v19, v19
	v_sqrt_f32_e32 v22, v22
	v_add_f32_e32 v26, 1.0, v26
	v_mul_f32_e32 v18, v18, v149
	v_mul_f32_e32 v18, 0x3fb8aa3b, v18
	v_exp_f32_e32 v18, v18
	v_mul_f32_e32 v43, v20, v23
	v_add_f32_e32 v20, v44, v148
	v_rcp_f32_e32 v26, v26
	v_fma_f32 v27, -v18, v18, 1.0
	v_sqrt_f32_e32 v27, v27
	v_mul_f32_e32 v42, v19, v22
	v_mul_f32_e32 v20, 0xbfb8aa3b, v20
	v_add_f32_e32 v22, v28, v93
	v_exp_f32_e32 v20, v20
	v_mul_f32_e32 v22, 0xbfb8aa3b, v22
	v_exp_f32_e32 v22, v22
	v_mul_f32_e32 v19, v26, v27
	v_mul_f32_e32 v11, v11, v19
	v_add_f32_e32 v19, 1.0, v20
	v_rcp_f32_e32 v19, v19
	v_add_f32_e32 v20, 1.0, v22
	v_add_f32_e32 v22, v45, v148
	v_mul_f32_e32 v22, 0xbfb8aa3b, v22
	v_exp_f32_e32 v22, v22
	v_mul_f32_e32 v19, v19, v149
	v_mul_f32_e32 v19, 0x3fb8aa3b, v19
	v_exp_f32_e32 v44, v19
	v_add_f32_e32 v19, 1.0, v22
	v_rcp_f32_e32 v19, v19
	v_mul_f32_e32 v24, 0xbfb8aa3b, v24
	v_exp_f32_e32 v24, v24
	v_add_f32_e32 v22, v29, v93
	v_mul_f32_e32 v19, v19, v149
	v_mul_f32_e32 v19, 0x3fb8aa3b, v19
	v_exp_f32_e32 v45, v19
	v_add_f32_e32 v19, v46, v148
	v_mul_f32_e32 v19, 0xbfb8aa3b, v19
	v_exp_f32_e32 v19, v19
	v_mul_f32_e32 v22, 0xbfb8aa3b, v22
	v_add_f32_e32 v24, 1.0, v24
	v_fma_f32 v25, -v41, v41, 1.0
	v_add_f32_e32 v19, 1.0, v19
	v_rcp_f32_e32 v19, v19
	v_exp_f32_e32 v22, v22
	v_rcp_f32_e32 v24, v24
	v_sqrt_f32_e32 v25, v25
	v_mul_f32_e32 v19, v19, v149
	v_mul_f32_e32 v19, 0x3fb8aa3b, v19
	v_exp_f32_e32 v46, v19
	v_add_f32_e32 v19, v47, v148
	v_mul_f32_e32 v19, 0xbfb8aa3b, v19
	v_add_f32_e32 v22, 1.0, v22
	v_exp_f32_e32 v19, v19
	v_mul_f32_e32 v151, v24, v25
	v_rcp_f32_e32 v24, v22
	v_fma_f32 v22, -v45, v45, 1.0
	v_sqrt_f32_e32 v25, v22
	v_add_f32_e32 v22, v30, v93
	v_mul_f32_e32 v22, 0xbfb8aa3b, v22
	v_exp_f32_e32 v22, v22
	v_add_f32_e32 v19, 1.0, v19
	v_rcp_f32_e32 v19, v19
	v_fma_f32 v27, -v46, v46, 1.0
	v_add_f32_e32 v22, 1.0, v22
	v_rcp_f32_e32 v26, v22
	v_add_f32_e32 v22, v31, v93
	v_mul_f32_e32 v19, v19, v149
	v_mul_f32_e32 v22, 0xbfb8aa3b, v22
	v_mul_f32_e32 v19, 0x3fb8aa3b, v19
	v_exp_f32_e32 v28, v22
	v_exp_f32_e32 v22, v19
	v_sqrt_f32_e32 v19, v27
	v_fma_f32 v23, -v44, v44, 1.0
	v_add_f32_e32 v27, 1.0, v28
	v_fma_f32 v28, -v22, v22, 1.0
	v_rcp_f32_e32 v27, v27
	v_sqrt_f32_e32 v28, v28
	v_rcp_f32_e32 v20, v20
	v_sqrt_f32_e32 v23, v23
	v_mul_f32_e32 v148, v26, v19
	v_mul_f32_e32 v19, v27, v28
	v_fmac_f32_e32 v7, 0, v17
	v_mul_f32_e32 v15, v15, v19
	v_mul_f32_e32 v19, v38, v7
	v_fmac_f32_e32 v19, v6, v21
	v_fmac_f32_e32 v3, 0, v16
	v_mul_f32_e32 v21, v37, v19
	v_mul_f32_e32 v47, v20, v23
	v_mul_f32_e32 v20, v152, v3
	v_fmac_f32_e32 v21, v5, v154
	v_fmac_f32_e32 v15, 0, v22
	v_mul_f32_e32 v93, v24, v25
	v_fmac_f32_e32 v20, v2, v35
	v_mul_f32_e32 v24, v36, v21
	v_fmac_f32_e32 v11, 0, v18
	v_mul_f32_e32 v2, v46, v15
	v_fmac_f32_e32 v24, v4, v153
	v_mul_f32_e32 v4, v41, v11
	v_fmac_f32_e32 v2, v14, v148
	v_fmac_f32_e32 v4, v10, v151
	v_mul_f32_e32 v5, v45, v2
	v_mul_f32_e32 v23, v150, v20
	v_mul_f32_e32 v6, v40, v4
	v_fmac_f32_e32 v5, v13, v93
	v_fmac_f32_e32 v23, v1, v34
	v_fmac_f32_e32 v6, v9, v43
	v_mul_f32_e32 v14, v22, v46
	v_mul_f32_e32 v9, v44, v5
	v_mul_f32_e32 v25, v33, v23
	v_mul_f32_e32 v13, v45, v14
	v_fmac_f32_e32 v9, v12, v47
	v_fmac_f32_e32 v25, v0, v32
	v_mul_f32_e32 v12, v44, v13
	ds_bpermute_b32 v0, v137, v9
	ds_bpermute_b32 v35, v137, v12
	v_mul_f32_e32 v28, v18, v41
	v_mul_f32_e32 v26, v16, v152
	v_mul_f32_e32 v27, v17, v38
	v_mul_f32_e32 v31, v40, v28
	v_mul_f32_e32 v10, v39, v6
	v_mul_f32_e32 v29, v150, v26
	v_mul_f32_e32 v30, v37, v27
	v_fmac_f32_e32 v10, v8, v42
	v_mul_f32_e32 v34, v39, v31
	v_mul_f32_e32 v32, v33, v29
	v_mul_f32_e32 v33, v36, v30
	s_waitcnt lgkmcnt(1)
	v_cndmask_b32_e64 v36, v0, v9, s[4:5]
	v_cndmask_b32_e64 v37, v9, v0, s[4:5]
	ds_bpermute_b32 v0, v137, v34
	ds_bpermute_b32 v40, v137, v10
	s_waitcnt lgkmcnt(2)
	v_cndmask_b32_e64 v8, v12, v35, s[4:5]
	v_fmac_f32_e32 v37, 0, v8
	ds_bpermute_b32 v8, v137, v33
	v_cndmask_b32_e64 v1, v35, v12, s[4:5]
	v_mul_f32_e32 v38, v12, v35
	v_fmac_f32_e32 v36, v1, v37
	s_waitcnt lgkmcnt(2)
	v_cndmask_b32_e64 v1, v0, v34, s[4:5]
	s_waitcnt lgkmcnt(1)
	v_cndmask_b32_e64 v39, v40, v10, s[4:5]
	v_cndmask_b32_e64 v0, v34, v0, s[4:5]
	v_cndmask_b32_e64 v40, v10, v40, s[4:5]
	ds_bpermute_b32 v44, v137, v24
	v_mul_f32_e32 v41, v38, v0
	v_fmac_f32_e32 v40, v0, v36
	v_mul_f32_e32 v42, v1, v41
	v_fmac_f32_e32 v39, v1, v40
	s_waitcnt lgkmcnt(1)
	v_cndmask_b32_e64 v0, v8, v33, s[4:5]
	v_cndmask_b32_e64 v1, v33, v8, s[4:5]
	ds_bpermute_b32 v8, v137, v32
	ds_bpermute_b32 v47, v137, v25
	s_waitcnt lgkmcnt(2)
	v_cndmask_b32_e64 v43, v44, v24, s[4:5]
	v_cndmask_b32_e64 v44, v24, v44, s[4:5]
	v_mul_f32_e32 v45, v1, v42
	v_fmac_f32_e32 v44, v1, v39
	v_mul_f32_e32 v46, v0, v45
	v_fmac_f32_e32 v43, v0, v44
	s_waitcnt lgkmcnt(1)
	v_cndmask_b32_e64 v0, v32, v8, s[4:5]
	s_waitcnt lgkmcnt(0)
	v_cndmask_b32_e64 v47, v25, v47, s[4:5]
	v_mul_f32_e32 v93, v0, v46
	v_fmac_f32_e32 v47, v0, v43
	s_and_saveexec_b64 s[12:13], s[4:5]
	v_mul_f32_e32 v0, v32, v93
	v_fma_f32 v1, v32, v47, v25
	ds_write_b64 v136, v[0:1] offset:4096
	s_or_b64 exec, exec, s[12:13]
	s_and_b64 vcc, exec, s[8:9]
	s_waitcnt lgkmcnt(0)
	s_barrier
	s_cbranch_vccnz .LBB0_285
	v_add3_u32 v148, v140, v91, s94
	v_mov_b32_e32 v8, 1.0
	v_mov_b32_e32 v1, 0
	s_mov_b32 s12, 7

.LBB0_288:
	s_or_b64 exec, exec, s[12:13]
	s_setprio 1
	ds_read_b128 v[0:3], v145 offset:40960
	ds_read_b128 v[4:7], v147 offset:40960
	v_add_u32_e32 v8, 0xa000, v147
	s_waitcnt lgkmcnt(1)
	v_mfma_f32_32x32x16_bf16 v[32:47], v[48:51], v[0:3], 0
	v_add_u32_e32 v0, 0xa000, v145
	ds_read_b128 v[0:3], v0 offset:32768
	ds_read_b128 v[8:11], v8 offset:32768
	s_waitcnt lgkmcnt(1)
	v_mfma_f32_32x32x16_bf16 v[16:31], v[48:51], v[0:3], 0
	v_mfma_f32_32x32x16_bf16 v[32:47], v[52:55], v[4:7], v[32:47]
	ds_read_b128 v[0:3], v142 offset:40960
	ds_read_b128 v[4:7], v146 offset:40960
	s_waitcnt lgkmcnt(2)
	v_mfma_f32_32x32x16_bf16 v[16:31], v[52:55], v[8:11], v[16:31]
	v_add_u32_e32 v8, 0xa000, v146
	ds_read_b128 v[8:11], v8 offset:32768
	s_waitcnt lgkmcnt(2)
	v_mfma_f32_32x32x16_bf16 v[32:47], v[56:59], v[0:3], v[32:47]
	v_add_u32_e32 v0, 0xa000, v142
	ds_read_b128 v[0:3], v0 offset:32768
	s_waitcnt lgkmcnt(0)
	v_mfma_f32_32x32x16_bf16 v[16:31], v[56:59], v[0:3], v[16:31]
	v_mfma_f32_32x32x16_bf16 v[32:47], v[60:63], v[4:7], v[32:47]
	ds_read_b128 v[0:3], v141 offset:40960
	ds_read_b128 v[4:7], v144 offset:40960
	v_mfma_f32_32x32x16_bf16 v[16:31], v[60:63], v[8:11], v[16:31]
	v_add_u32_e32 v8, 0xa000, v144
	ds_read_b128 v[8:11], v8 offset:32768
	s_waitcnt lgkmcnt(2)
	v_mfma_f32_32x32x16_bf16 v[32:47], v[64:67], v[0:3], v[32:47]
	v_add_u32_e32 v0, 0xa000, v141
	ds_read_b128 v[0:3], v0 offset:32768
	s_waitcnt lgkmcnt(0)
	v_mfma_f32_32x32x16_bf16 v[16:31], v[64:67], v[0:3], v[16:31]
	v_mfma_f32_32x32x16_bf16 v[32:47], v[68:71], v[4:7], v[32:47]
	ds_read_b128 v[0:3], v139 offset:40960
	ds_read_b128 v[4:7], v143 offset:40960
	v_mfma_f32_32x32x16_bf16 v[16:31], v[68:71], v[8:11], v[16:31]
	v_add_u32_e32 v8, 0xa000, v143
	ds_read_b128 v[8:11], v8 offset:32768
	s_waitcnt lgkmcnt(2)
	v_mfma_f32_32x32x16_bf16 v[32:47], v[72:75], v[0:3], v[32:47]
	v_add_u32_e32 v0, 0xa000, v139
	ds_read_b128 v[0:3], v0 offset:32768
	s_waitcnt lgkmcnt(0)
	v_mfma_f32_32x32x16_bf16 v[16:31], v[72:75], v[0:3], v[16:31]
	v_mfma_f32_32x32x16_bf16 v[32:47], v[76:79], v[4:7], v[32:47]
	v_mfma_f32_32x32x16_bf16 v[16:31], v[76:79], v[8:11], v[16:31]
	v_mfma_f32_32x32x16_bf16 v[0:15], v[72:75], v[80:83], 0
	v_mfma_f32_32x32x16_bf16 v[0:15], v[76:79], v[84:87], v[0:15]
	s_setprio 0
	v_lshl_or_b32 v48, v138, 2, v135
	s_waitcnt vmcnt(16)
	ds_read_b32 v251, v167 offset:384
	v_mov_b32_e32 v49, v173
	v_mov_b32_e32 v48, v174
	v_add_f32_e32 v32, v32, v49
	v_add_f32_e32 v16, v16, v48
	v_mul_f32_e32 v32, 0xbfb8aa3b, v32
	v_mul_f32_e32 v16, 0xbfb8aa3b, v16
	v_exp_f32_e32 v32, v32
	v_exp_f32_e32 v51, v16
	v_add_f32_e32 v17, v17, v48
	v_mul_f32_e32 v17, 0xbfb8aa3b, v17
	v_exp_f32_e32 v52, v17
	v_add_f32_e32 v32, 1.0, v32
	v_add_f32_e32 v51, 1.0, v51
	v_rcp_f32_e32 v17, v32
	v_rcp_f32_e32 v32, v51
	v_add_f32_e32 v33, v33, v49
	v_add_f32_e32 v34, v34, v49
	v_mul_f32_e32 v33, 0xbfb8aa3b, v33
	v_mul_f32_e32 v34, 0xbfb8aa3b, v34
	v_exp_f32_e32 v33, v33
	v_exp_f32_e32 v34, v34
	v_add_f32_e32 v33, 1.0, v33
	v_add_f32_e32 v34, 1.0, v34
	v_rcp_f32_e32 v33, v33
	v_rcp_f32_e32 v34, v34
	v_add_f32_e32 v18, v18, v48
	v_mul_f32_e32 v18, 0xbfb8aa3b, v18
	v_add_f32_e32 v19, v19, v48
	v_exp_f32_e32 v18, v18
	s_waitcnt lgkmcnt(0)
	v_mov_b32_e32 v50, v251
	v_mul_f32_e32 v16, v17, v50
	v_mul_f32_e32 v16, 0x3fb8aa3b, v16
	v_mul_f32_e32 v17, v33, v50
	v_exp_f32_e32 v33, v16
	v_mul_f32_e32 v16, v34, v50
	v_mul_f32_e32 v16, 0x3fb8aa3b, v16
	v_exp_f32_e32 v53, v16
	v_add_f32_e32 v16, v35, v49
	v_mul_f32_e32 v16, 0xbfb8aa3b, v16
	v_exp_f32_e32 v16, v16
	v_mul_f32_e32 v17, 0x3fb8aa3b, v17
	v_mul_f32_e32 v19, 0xbfb8aa3b, v19
	v_exp_f32_e32 v51, v17
	v_add_f32_e32 v16, 1.0, v16
	v_rcp_f32_e32 v16, v16
	v_exp_f32_e32 v19, v19
	v_add_f32_e32 v52, 1.0, v52
	v_add_f32_e32 v18, 1.0, v18
	v_mul_f32_e32 v16, v16, v50
	v_mul_f32_e32 v16, 0x3fb8aa3b, v16
	v_exp_f32_e32 v16, v16
	v_fma_f32 v35, -v53, v53, 1.0
	v_rcp_f32_e32 v17, v52
	v_fma_f32 v34, -v33, v33, 1.0
	v_fma_f32 v52, -v51, v51, 1.0
	v_rcp_f32_e32 v18, v18
	v_sqrt_f32_e32 v35, v35
	v_add_f32_e32 v19, 1.0, v19
	v_fma_f32 v54, -v16, v16, 1.0
	v_sqrt_f32_e32 v34, v34
	v_sqrt_f32_e32 v52, v52
	v_rcp_f32_e32 v19, v19
	v_sqrt_f32_e32 v54, v54
	v_mul_f32_e32 v35, v18, v35
	v_add_f32_e32 v18, v36, v49
	v_mul_f32_e32 v32, v32, v34
	v_mul_f32_e32 v34, v17, v52
	v_mul_f32_e32 v17, v19, v54
	v_mul_f32_e32 v18, 0xbfb8aa3b, v18
	v_add_f32_e32 v19, v20, v48
	v_exp_f32_e32 v18, v18
	v_mul_f32_e32 v19, 0xbfb8aa3b, v19
	v_exp_f32_e32 v19, v19
	v_mul_f32_e32 v3, v3, v17
	v_add_f32_e32 v17, 1.0, v18
	v_rcp_f32_e32 v17, v17
	v_add_f32_e32 v18, 1.0, v19
	v_add_f32_e32 v19, v37, v49
	v_mul_f32_e32 v19, 0xbfb8aa3b, v19
	v_exp_f32_e32 v19, v19
	v_mul_f32_e32 v17, v17, v50
	v_mul_f32_e32 v17, 0x3fb8aa3b, v17
	v_exp_f32_e32 v36, v17
	v_add_f32_e32 v17, 1.0, v19
	v_rcp_f32_e32 v17, v17
	v_add_f32_e32 v19, v21, v48
	v_mul_f32_e32 v19, 0xbfb8aa3b, v19
	v_exp_f32_e32 v19, v19
	v_mul_f32_e32 v17, v17, v50
	v_mul_f32_e32 v17, 0x3fb8aa3b, v17
	v_exp_f32_e32 v37, v17
	v_add_f32_e32 v17, v38, v49
	v_mul_f32_e32 v17, 0xbfb8aa3b, v17
	v_exp_f32_e32 v17, v17
	v_add_f32_e32 v23, v23, v48
	v_add_f32_e32 v19, 1.0, v19
	v_fma_f32 v21, -v37, v37, 1.0
	v_add_f32_e32 v17, 1.0, v17
	v_rcp_f32_e32 v17, v17
	v_mul_f32_e32 v23, 0xbfb8aa3b, v23
	v_fma_f32 v20, -v36, v36, 1.0
	v_rcp_f32_e32 v19, v19
	v_mul_f32_e32 v17, v17, v50
	v_mul_f32_e32 v17, 0x3fb8aa3b, v17
	v_exp_f32_e32 v38, v17
	v_add_f32_e32 v17, v39, v49
	v_mul_f32_e32 v17, 0xbfb8aa3b, v17
	v_exp_f32_e32 v17, v17
	v_sqrt_f32_e32 v21, v21
	v_exp_f32_e32 v23, v23
	v_rcp_f32_e32 v18, v18
	v_add_f32_e32 v17, 1.0, v17
	v_rcp_f32_e32 v17, v17
	v_sqrt_f32_e32 v20, v20
	v_add_f32_e32 v23, 1.0, v23
	v_mul_f32_e32 v55, v19, v21
	v_mul_f32_e32 v17, v17, v50
	v_mul_f32_e32 v17, 0x3fb8aa3b, v17
	v_exp_f32_e32 v17, v17
	v_add_f32_e32 v19, v40, v49
	v_rcp_f32_e32 v23, v23
	v_mul_f32_e32 v54, v18, v20
	v_fma_f32 v52, -v17, v17, 1.0
	v_sqrt_f32_e32 v52, v52
	v_mul_f32_e32 v19, 0xbfb8aa3b, v19
	v_add_f32_e32 v20, v24, v48
	v_add_f32_e32 v22, v22, v48
	v_exp_f32_e32 v19, v19
	v_mul_f32_e32 v20, 0xbfb8aa3b, v20
	v_mul_f32_e32 v22, 0xbfb8aa3b, v22
	v_exp_f32_e32 v20, v20
	v_exp_f32_e32 v22, v22
	v_mul_f32_e32 v18, v23, v52
	v_mul_f32_e32 v7, v7, v18
	v_add_f32_e32 v18, 1.0, v19
	v_rcp_f32_e32 v18, v18
	v_add_f32_e32 v19, 1.0, v20
	v_add_f32_e32 v20, v41, v49
	v_add_f32_e32 v22, 1.0, v22
	v_fma_f32 v39, -v38, v38, 1.0
	v_mul_f32_e32 v20, 0xbfb8aa3b, v20
	v_rcp_f32_e32 v22, v22
	v_sqrt_f32_e32 v39, v39
	v_exp_f32_e32 v20, v20
	v_mul_f32_e32 v18, v18, v50
	v_mul_f32_e32 v18, 0x3fb8aa3b, v18
	v_mul_f32_e32 v21, v22, v39
	v_exp_f32_e32 v39, v18
	v_add_f32_e32 v18, 1.0, v20
	v_rcp_f32_e32 v18, v18
	v_add_f32_e32 v20, v25, v48
	v_mul_f32_e32 v20, 0xbfb8aa3b, v20
	v_exp_f32_e32 v20, v20
	v_mul_f32_e32 v18, v18, v50
	v_mul_f32_e32 v18, 0x3fb8aa3b, v18
	v_exp_f32_e32 v40, v18
	v_add_f32_e32 v18, v42, v49
	v_mul_f32_e32 v18, 0xbfb8aa3b, v18
	v_exp_f32_e32 v18, v18
	v_add_f32_e32 v24, v26, v48
	v_add_f32_e32 v26, v27, v48
	v_add_f32_e32 v20, 1.0, v20
	v_add_f32_e32 v18, 1.0, v18
	v_rcp_f32_e32 v18, v18
	v_fma_f32 v23, -v40, v40, 1.0
	v_mul_f32_e32 v26, 0xbfb8aa3b, v26
	v_fma_f32 v22, -v39, v39, 1.0
	v_mul_f32_e32 v18, v18, v50
	v_mul_f32_e32 v18, 0x3fb8aa3b, v18
	v_exp_f32_e32 v41, v18
	v_add_f32_e32 v18, v43, v49
	v_mul_f32_e32 v18, 0xbfb8aa3b, v18
	v_exp_f32_e32 v18, v18
	v_rcp_f32_e32 v20, v20
	v_sqrt_f32_e32 v23, v23
	v_exp_f32_e32 v26, v26
	v_add_f32_e32 v18, 1.0, v18
	v_rcp_f32_e32 v18, v18
	v_rcp_f32_e32 v19, v19
	v_sqrt_f32_e32 v22, v22
	v_add_f32_e32 v26, 1.0, v26
	v_mul_f32_e32 v18, v18, v50
	v_mul_f32_e32 v18, 0x3fb8aa3b, v18
	v_exp_f32_e32 v18, v18
	v_mul_f32_e32 v43, v20, v23
	v_add_f32_e32 v20, v44, v49
	v_rcp_f32_e32 v26, v26
	v_fma_f32 v27, -v18, v18, 1.0
	v_sqrt_f32_e32 v27, v27
	v_mul_f32_e32 v42, v19, v22
	v_mul_f32_e32 v20, 0xbfb8aa3b, v20
	v_add_f32_e32 v22, v28, v48
	v_exp_f32_e32 v20, v20
	v_mul_f32_e32 v22, 0xbfb8aa3b, v22
	v_exp_f32_e32 v22, v22
	v_mul_f32_e32 v19, v26, v27
	v_mul_f32_e32 v11, v11, v19
	v_add_f32_e32 v19, 1.0, v20
	v_rcp_f32_e32 v19, v19
	v_add_f32_e32 v20, 1.0, v22
	v_add_f32_e32 v22, v45, v49
	v_mul_f32_e32 v22, 0xbfb8aa3b, v22
	v_exp_f32_e32 v22, v22
	v_mul_f32_e32 v19, v19, v50
	v_mul_f32_e32 v19, 0x3fb8aa3b, v19
	v_exp_f32_e32 v44, v19
	v_add_f32_e32 v19, 1.0, v22
	v_rcp_f32_e32 v19, v19
	v_mul_f32_e32 v24, 0xbfb8aa3b, v24
	v_exp_f32_e32 v24, v24
	v_add_f32_e32 v22, v29, v48
	v_mul_f32_e32 v19, v19, v50
	v_mul_f32_e32 v19, 0x3fb8aa3b, v19
	v_exp_f32_e32 v45, v19
	v_add_f32_e32 v19, v46, v49
	v_mul_f32_e32 v19, 0xbfb8aa3b, v19
	v_exp_f32_e32 v19, v19
	v_mul_f32_e32 v22, 0xbfb8aa3b, v22
	v_add_f32_e32 v24, 1.0, v24
	v_fma_f32 v25, -v41, v41, 1.0
	v_add_f32_e32 v19, 1.0, v19
	v_rcp_f32_e32 v19, v19
	v_exp_f32_e32 v22, v22
	v_rcp_f32_e32 v24, v24
	v_sqrt_f32_e32 v25, v25
	v_mul_f32_e32 v19, v19, v50
	v_mul_f32_e32 v19, 0x3fb8aa3b, v19
	v_exp_f32_e32 v46, v19
	v_add_f32_e32 v19, v47, v49
	v_mul_f32_e32 v19, 0xbfb8aa3b, v19
	v_add_f32_e32 v22, 1.0, v22
	v_exp_f32_e32 v19, v19
	v_mul_f32_e32 v52, v24, v25
	v_rcp_f32_e32 v24, v22
	v_fma_f32 v22, -v45, v45, 1.0
	v_sqrt_f32_e32 v25, v22
	v_add_f32_e32 v22, v30, v48
	v_mul_f32_e32 v22, 0xbfb8aa3b, v22
	v_exp_f32_e32 v22, v22
	v_add_f32_e32 v19, 1.0, v19
	v_rcp_f32_e32 v19, v19
	v_fma_f32 v27, -v46, v46, 1.0
	v_add_f32_e32 v22, 1.0, v22
	v_rcp_f32_e32 v26, v22
	v_add_f32_e32 v22, v31, v48
	v_mul_f32_e32 v19, v19, v50
	v_mul_f32_e32 v22, 0xbfb8aa3b, v22
	v_mul_f32_e32 v19, 0x3fb8aa3b, v19
	v_exp_f32_e32 v28, v22
	v_exp_f32_e32 v22, v19
	v_sqrt_f32_e32 v19, v27
	v_fma_f32 v23, -v44, v44, 1.0
	v_add_f32_e32 v27, 1.0, v28
	v_fma_f32 v28, -v22, v22, 1.0
	v_rcp_f32_e32 v27, v27
	v_sqrt_f32_e32 v28, v28
	v_rcp_f32_e32 v20, v20
	v_sqrt_f32_e32 v23, v23
	v_mul_f32_e32 v49, v26, v19
	v_mul_f32_e32 v19, v27, v28
	v_fmac_f32_e32 v7, 0, v17
	v_mul_f32_e32 v15, v15, v19
	v_mul_f32_e32 v19, v38, v7
	v_fmac_f32_e32 v19, v6, v21
	v_fmac_f32_e32 v3, 0, v16
	v_mul_f32_e32 v21, v37, v19
	v_mul_f32_e32 v47, v20, v23
	v_mul_f32_e32 v20, v53, v3
	v_fmac_f32_e32 v21, v5, v55
	v_fmac_f32_e32 v15, 0, v22
	v_mul_f32_e32 v48, v24, v25
	v_fmac_f32_e32 v20, v2, v35
	v_mul_f32_e32 v24, v36, v21
	v_fmac_f32_e32 v11, 0, v18
	v_mul_f32_e32 v2, v46, v15
	v_fmac_f32_e32 v24, v4, v54
	v_mul_f32_e32 v4, v41, v11
	v_fmac_f32_e32 v2, v14, v49
	v_fmac_f32_e32 v4, v10, v52
	v_mul_f32_e32 v5, v45, v2
	v_mul_f32_e32 v23, v51, v20
	v_mul_f32_e32 v6, v40, v4
	v_fmac_f32_e32 v5, v13, v48
	v_fmac_f32_e32 v23, v1, v34
	v_fmac_f32_e32 v6, v9, v43
	v_mul_f32_e32 v14, v22, v46
	v_mul_f32_e32 v9, v44, v5
	v_mul_f32_e32 v25, v33, v23
	v_mul_f32_e32 v13, v45, v14
	v_fmac_f32_e32 v9, v12, v47
	v_fmac_f32_e32 v25, v0, v32
	v_mul_f32_e32 v12, v44, v13
	ds_bpermute_b32 v0, v137, v9
	ds_bpermute_b32 v35, v137, v12
	v_mul_f32_e32 v28, v18, v41
	v_mul_f32_e32 v26, v16, v53
	v_mul_f32_e32 v27, v17, v38
	v_mul_f32_e32 v31, v40, v28
	v_mul_f32_e32 v10, v39, v6
	v_mul_f32_e32 v29, v51, v26
	v_mul_f32_e32 v30, v37, v27
	v_fmac_f32_e32 v10, v8, v42
	v_mul_f32_e32 v34, v39, v31
	v_mul_f32_e32 v32, v33, v29
	v_mul_f32_e32 v33, v36, v30
	s_waitcnt lgkmcnt(1)
	v_cndmask_b32_e64 v36, v0, v9, s[4:5]
	v_cndmask_b32_e64 v37, v9, v0, s[4:5]
	ds_bpermute_b32 v0, v137, v34
	ds_bpermute_b32 v40, v137, v10
	s_waitcnt lgkmcnt(2)
	v_cndmask_b32_e64 v8, v12, v35, s[4:5]
	v_fmac_f32_e32 v37, 0, v8
	ds_bpermute_b32 v8, v137, v33
	v_cndmask_b32_e64 v1, v35, v12, s[4:5]
	v_mul_f32_e32 v38, v12, v35
	v_fmac_f32_e32 v36, v1, v37
	s_waitcnt lgkmcnt(2)
	v_cndmask_b32_e64 v1, v0, v34, s[4:5]
	s_waitcnt lgkmcnt(1)
	v_cndmask_b32_e64 v39, v40, v10, s[4:5]
	v_cndmask_b32_e64 v0, v34, v0, s[4:5]
	v_cndmask_b32_e64 v40, v10, v40, s[4:5]
	ds_bpermute_b32 v44, v137, v24
	v_mul_f32_e32 v41, v38, v0
	v_fmac_f32_e32 v40, v0, v36
	v_mul_f32_e32 v42, v1, v41
	v_fmac_f32_e32 v39, v1, v40
	s_waitcnt lgkmcnt(1)
	v_cndmask_b32_e64 v0, v8, v33, s[4:5]
	v_cndmask_b32_e64 v1, v33, v8, s[4:5]
	ds_bpermute_b32 v8, v137, v32
	ds_bpermute_b32 v47, v137, v25
	s_waitcnt lgkmcnt(2)
	v_cndmask_b32_e64 v43, v44, v24, s[4:5]
	v_cndmask_b32_e64 v44, v24, v44, s[4:5]
	v_mul_f32_e32 v45, v1, v42
	v_fmac_f32_e32 v44, v1, v39
	v_mul_f32_e32 v46, v0, v45
	v_fmac_f32_e32 v43, v0, v44
	s_waitcnt lgkmcnt(1)
	v_cndmask_b32_e64 v0, v32, v8, s[4:5]
	s_waitcnt lgkmcnt(0)
	v_cndmask_b32_e64 v47, v25, v47, s[4:5]
	v_mul_f32_e32 v48, v0, v46
	v_fmac_f32_e32 v47, v0, v43
	s_and_saveexec_b64 s[12:13], s[4:5]
	v_mul_f32_e32 v0, v32, v48
	v_fma_f32 v1, v32, v47, v25
	ds_write_b64 v136, v[0:1] offset:6144
	s_or_b64 exec, exec, s[12:13]
	s_and_b64 vcc, exec, s[8:9]
	s_waitcnt lgkmcnt(0)
	s_barrier
	s_cbranch_vccnz .LBB0_293
	v_add3_u32 v49, v140, v91, s95
	v_mov_b32_e32 v8, 1.0
	v_mov_b32_e32 v1, 0
	s_mov_b32 s8, 7

.LBB0_297:
	s_andn2_b64 vcc, exec, s[4:5]
	s_cbranch_vccnz .LBB0_372
	s_and_b64 vcc, exec, s[0:1]
	s_cbranch_vccnz .LBB0_372
	s_lshl_b32 s70, s72, 7
	s_add_i32 s71, s70, 0xfffffe00
	s_lshl_b32 s0, s72, 16
	s_add_u32 s0, s52, s0
	s_addc_u32 s1, s53, 0
	s_add_u32 s20, s0, 0x1c00000
	s_addc_u32 s21, s1, 0
	s_lshl_b32 s0, s72, 9
	s_add_u32 s0, s52, s0
	s_addc_u32 s1, s53, 0
	s_add_u32 s22, s0, 0x13000000
	s_addc_u32 s23, s1, 0
	s_add_u32 s24, s52, 0x1e00000
	v_mbcnt_lo_u32_b32 v0, -1, 0
	s_mov_b32 s15, 0
	s_addc_u32 s25, s53, 0
	s_mov_b32 s72, s71
	s_mov_b64 s[0:1], -1
	v_mov_b32_e32 v89, 0
	s_movk_i32 s73, 0x200
	s_movk_i32 s75, 0x280
	s_movk_i32 s76, 0x7f
	s_movk_i32 s77, 0x1ff
	s_add_i32 s78, 16, 0x2000
	s_movk_i32 s79, 0xfc00
	s_movk_i32 s80, 0x4000
	s_movk_i32 s81, 0x2400
	s_mov_b64 s[30:31], 0x6001400
	s_mov_b32 s82, 0x6001000
	v_mbcnt_hi_u32_b32 v132, -1, v0
	s_mov_b32 s83, 0x5040100
	s_mov_b32 s84, 0x3f2aaaab
	v_mov_b32_e32 v133, 0x3ecc95a3
	s_mov_b32 s85, 0x3f317218
	s_mov_b32 s86, 0x7f800000
	s_mov_b32 s87, 0x33800000
	s_mov_b64 s[38:39], 0x80
	s_mov_b64 s[48:49], 0x100
	s_add_i32 s88, 16, 0x1800
	s_mov_b64 s[60:61], 0x180
	v_mov_b32_e32 v134, 0x3f80
	v_mov_b32_e32 v90, 0x3f317218
	v_mov_b32_e32 v135, 0x7f800000
	v_mov_b32_e32 v136, 0x7fc00000
	v_mov_b32_e32 v137, 0xff800000
	v_and_b32_e32 v167, 31, v177
	v_lshrrev_b32_e32 v138, 6, v177
	v_and_b32_e32 v138, 3, v138
	v_lshlrev_b32_e32 v138, 7, v138
	v_lshl_or_b32 v138, v167, 2, v138
	v_lshlrev_b32_e32 v167, 2, v167
	v_add_u32_e32 v167, 0x14100, v167
	v_lshl_add_u32 v139, s70, 2, v138
	global_load_dword v91, v139, s[42:43]
	v_add_u32_e32 v138, 0x14100, v138
	s_branch .LBB0_301

.LBB0_301:
	v_mov_b32_e32 v92, v177
	s_andn2_b64 vcc, exec, s[0:1]
	v_readfirstlane_b32 s89, v92
	s_waitcnt vmcnt(4)
	v_lshlrev_b32_e32 v8, 4, v92
	s_barrier
	s_cbranch_vccnz .LBB0_320
	s_waitcnt vmcnt(0)
	v_mul_f32_e32 v91, 0xbfb8aa3b, v91
	v_exp_f32_e32 v160, v91
	s_nop 0
	v_add_f32_e32 v35, 1.0, v160
	v_frexp_mant_f32_e32 v154, v35
	v_cvt_f64_f32_e32 v[16:17], v35
	v_add_f32_e32 v153, -1.0, v35
	v_frexp_exp_i32_f64_e32 v16, v[16:17]
	v_cmp_gt_f32_e32 vcc, s84, v154
	v_sub_f32_e32 v34, v153, v35
	v_subbrev_co_u32_e32 v16, vcc, 0, v16, vcc
	v_sub_f32_e32 v153, v160, v153
	v_add_f32_e32 v17, 1.0, v34
	v_sub_u32_e32 v32, 0, v16
	v_add_f32_e32 v17, v153, v17
	v_ldexp_f32 v33, v35, v32
	v_ldexp_f32 v17, v17, v32
	v_add_f32_e32 v32, -1.0, v33
	v_add_f32_e32 v34, 1.0, v33
	v_add_f32_e32 v35, 1.0, v32
	v_add_f32_e32 v91, -1.0, v34
	v_sub_f32_e32 v35, v33, v35
	v_sub_f32_e32 v33, v33, v91
	v_add_f32_e32 v35, v17, v35
	v_add_f32_e32 v17, v17, v33
	v_add_f32_e32 v91, v34, v17
	v_rcp_f32_e32 v154, v91
	v_add_f32_e32 v33, v32, v35
	v_sub_f32_e32 v34, v91, v34
	v_mul_f32_e32 v156, v33, v154
	v_sub_f32_e32 v17, v17, v34
	v_mul_f32_e32 v34, v91, v156
	v_fma_f32 v152, v156, v91, -v34
	v_sub_f32_e32 v32, v33, v32
	v_fmac_f32_e32 v152, v156, v17
	v_sub_f32_e32 v155, v35, v32
	v_add_f32_e32 v32, v34, v152
	v_sub_f32_e32 v35, v33, v32
	v_mov_b32_e32 v153, v32
	v_pk_add_f32 v[32:33], v[32:33], v[34:35] neg_lo:[0,1] neg_hi:[0,1]
	v_cvt_f32_i32_e32 v16, v16
	v_pk_add_f32 v[32:33], v[32:33], v[152:153] neg_lo:[0,1] neg_hi:[0,1]
	v_cmp_neq_f32_e32 vcc, s86, v160
	v_add_f32_e32 v33, v155, v33
	v_add_f32_e32 v32, v32, v33
	v_add_f32_e32 v33, v35, v32
	v_mul_f32_e32 v153, v154, v33
	v_mul_f32_e32 v34, v91, v153
	v_sub_f32_e32 v35, v35, v33
	v_add_f32_e32 v157, v156, v153
	v_fma_f32 v152, v153, v91, -v34
	v_add_f32_e32 v155, v32, v35
	v_sub_f32_e32 v32, v157, v156
	v_fmac_f32_e32 v152, v153, v17
	v_sub_f32_e32 v17, v153, v32
	v_add_f32_e32 v32, v34, v152
	v_sub_f32_e32 v35, v33, v32
	v_mov_b32_e32 v153, v32
	v_pk_add_f32 v[32:33], v[32:33], v[34:35] neg_lo:[0,1] neg_hi:[0,1]
	v_pk_add_f32 v[32:33], v[32:33], v[152:153] neg_lo:[0,1] neg_hi:[0,1]
	v_add_f32_e32 v33, v155, v33
	v_add_f32_e32 v32, v32, v33
	v_add_f32_e32 v32, v35, v32
	v_mul_f32_e32 v32, v154, v32
	v_add_f32_e32 v17, v17, v32
	v_add_f32_e32 v32, v157, v17
	v_mul_f32_e32 v34, v32, v32
	v_sub_f32_e32 v35, v32, v157
	v_fmamk_f32 v91, v34, 0x3e9b6dac, v133
	v_sub_f32_e32 v35, v17, v35
	v_mul_f32_e32 v17, v32, v34
	v_fmaak_f32 v91, v34, v91, 0x3f2aaada
	v_ldexp_f32 v153, v35, 1
	v_pk_mul_f32 v[34:35], v[16:17], v[90:91]
	v_ldexp_f32 v33, v32, 1
	v_fma_f32 v32, v16, s85, -v34
	v_fmac_f32_e32 v32, 0xb102e308, v16
	v_pk_add_f32 v[16:17], v[34:35], v[32:33]
	v_mov_b32_e32 v152, v34
	v_sub_f32_e32 v91, v17, v33
	v_pk_add_f32 v[154:155], v[16:17], v[34:35] neg_lo:[0,1] neg_hi:[0,1]
	v_sub_f32_e32 v34, v35, v91
	v_add_f32_e32 v153, v153, v34
	v_pk_add_f32 v[34:35], v[16:17], v[152:153]
	v_mov_b32_e32 v33, v16
	v_mov_b32_e32 v155, v35
	v_pk_add_f32 v[158:159], v[32:33], v[154:155] neg_lo:[0,1] neg_hi:[0,1]
	v_pk_add_f32 v[32:33], v[32:33], v[154:155]
	v_mov_b32_e32 v157, v16
	v_pk_add_f32 v[154:155], v[32:33], v[16:17] op_sel:[1,0] op_sel_hi:[0,1] neg_lo:[0,1] neg_hi:[0,1]
	v_mov_b32_e32 v156, v153
	v_mov_b32_e32 v152, v35
	v_mov_b32_e32 v153, v33
	v_pk_mov_b32 v[16:17], v[16:17], v[154:155] op_sel:[1,0]
	v_pk_add_f32 v[34:35], v[34:35], v[154:155] op_sel_hi:[1,0] neg_lo:[0,1] neg_hi:[0,1]
	v_pk_add_f32 v[16:17], v[152:153], v[16:17] neg_lo:[0,1] neg_hi:[0,1]
	v_mov_b32_e32 v34, v158
	v_pk_add_f32 v[16:17], v[156:157], v[16:17] neg_lo:[0,1] neg_hi:[0,1]
	v_mov_b32_e32 v159, v33
	v_pk_add_f32 v[34:35], v[34:35], v[16:17]
	v_pk_add_f32 v[152:153], v[34:35], v[34:35] op_sel:[0,1] op_sel_hi:[1,0]
	v_pk_add_f32 v[32:33], v[32:33], v[152:153] op_sel:[1,0] op_sel_hi:[0,1]
	v_mov_b32_e32 v35, v32
	v_mov_b32_e32 v17, v152
	v_pk_add_f32 v[152:153], v[34:35], v[158:159] neg_lo:[0,1] neg_hi:[0,1]
	v_sub_f32_e32 v33, v34, v152
	v_pk_add_f32 v[16:17], v[16:17], v[152:153] neg_lo:[0,1] neg_hi:[0,1]
	v_sub_f32_e32 v33, v158, v33
	v_add_f32_e32 v16, v16, v33
	v_add_f32_e32 v16, v16, v17
	v_add_f32_e32 v16, v32, v16
	v_cndmask_b32_e32 v16, v135, v16, vcc
	v_cmp_ngt_f32_e32 vcc, -1.0, v160
	v_cndmask_b32_e32 v16, v136, v16, vcc
	v_cmp_neq_f32_e32 vcc, -1.0, v160
	v_cndmask_b32_e32 v16, v137, v16, vcc
	v_cmp_lt_f32_e64 vcc, |v160|, s87
	v_cndmask_b32_e32 v16, v16, v160, vcc
	v_mul_f32_e32 v33, 0xc1000000, v16
	ds_write_b32 v138, v33
	v_add_u32_e32 v93, 0x200, v92
	v_add_u32_e32 v10, 0x400, v92
	v_add_u32_e32 v12, 0x600, v92
	v_add_u32_e32 v18, 0x800, v92
	v_add_u32_e32 v20, 0xa00, v92
	v_add_u32_e32 v28, 0xc00, v92
	v_add_u32_e32 v30, 0xe00, v92
	v_ashrrev_i32_e32 v9, 4, v92
	s_waitcnt vmcnt(3)
	v_ashrrev_i32_e32 v34, 4, v93
	v_ashrrev_i32_e32 v35, 4, v10
	v_ashrrev_i32_e32 v36, 4, v12
	v_ashrrev_i32_e32 v37, 4, v18
	v_ashrrev_i32_e32 v38, 4, v20
	v_ashrrev_i32_e32 v39, 4, v28
	v_ashrrev_i32_e32 v40, 4, v30
	v_and_b32_e32 v88, 0xf0, v8
	v_lshlrev_b32_e32 v0, 7, v9
	v_lshlrev_b32_e32 v2, 7, v34
	v_lshlrev_b32_e32 v10, 7, v35
	v_lshlrev_b32_e32 v12, 7, v36
	v_lshlrev_b32_e32 v18, 7, v37
	v_lshlrev_b32_e32 v20, 7, v38
	v_lshlrev_b32_e32 v28, 7, v39
	v_lshlrev_b32_e32 v30, 7, v40
	v_lshl_add_u64 v[26:27], s[20:21], 0, v[88:89]
	v_ashrrev_i32_e32 v1, 31, v0
	v_ashrrev_i32_e32 v3, 31, v2
	v_ashrrev_i32_e32 v11, 31, v10
	v_ashrrev_i32_e32 v13, 31, v12
	v_ashrrev_i32_e32 v19, 31, v18
	v_ashrrev_i32_e32 v21, 31, v20
	v_ashrrev_i32_e32 v29, 31, v28
	v_ashrrev_i32_e32 v31, 31, v30
	v_lshl_add_u64 v[0:1], v[0:1], 1, v[26:27]
	v_lshl_add_u64 v[4:5], v[2:3], 1, v[26:27]
	v_lshl_add_u64 v[10:11], v[10:11], 1, v[26:27]
	v_lshl_add_u64 v[14:15], v[12:13], 1, v[26:27]
	v_lshl_add_u64 v[18:19], v[18:19], 1, v[26:27]
	v_lshl_add_u64 v[22:23], v[20:21], 1, v[26:27]
	v_lshl_add_u64 v[28:29], v[28:29], 1, v[26:27]
	v_lshl_add_u64 v[30:31], v[30:31], 1, v[26:27]
	global_load_dwordx4 v[0:3], v[0:1], off
	s_nop 0
	global_load_dwordx4 v[4:7], v[4:5], off
	s_nop 0
	global_load_dwordx4 v[10:13], v[10:11], off
	s_nop 0
	global_load_dwordx4 v[14:17], v[14:15], off
	s_nop 0
	global_load_dwordx4 v[18:21], v[18:19], off
	s_nop 0
	global_load_dwordx4 v[22:25], v[22:23], off
	s_nop 0
	global_load_dwordx4 v[26:29], v[28:29], off
	s_nop 0
	global_load_dwordx4 v[30:33], v[30:31], off
	v_and_b32_e32 v41, 0x70, v92
	v_xad_u32 v41, v88, v41, 16
	v_lshl_add_u32 v9, v9, 8, v41
	v_cmp_gt_i32_e32 vcc, s75, v92
	v_lshl_add_u32 v34, v34, 8, v41
	v_lshl_add_u32 v35, v35, 8, v41
	v_lshl_add_u32 v36, v36, 8, v41
	v_lshl_add_u32 v37, v37, 8, v41
	v_lshl_add_u32 v38, v38, 8, v41
	v_lshl_add_u32 v39, v39, 8, v41
	v_lshl_add_u32 v40, v40, 8, v41
	s_waitcnt vmcnt(7)
	ds_write_b128 v9, v[0:3] offset:16384
	s_waitcnt vmcnt(6)
	ds_write_b128 v34, v[4:7] offset:16384
	s_waitcnt vmcnt(5)
	ds_write_b128 v35, v[10:13] offset:16384
	s_waitcnt vmcnt(4)
	ds_write_b128 v36, v[14:17] offset:16384
	s_waitcnt vmcnt(3)
	ds_write_b128 v37, v[18:21] offset:16384
	s_waitcnt vmcnt(2)
	ds_write_b128 v38, v[22:25] offset:16384
	s_waitcnt vmcnt(1)
	ds_write_b128 v39, v[26:29] offset:16384
	s_waitcnt vmcnt(0)
	ds_write_b128 v40, v[30:33] offset:16384
	s_and_saveexec_b64 s[62:63], vcc
	s_cbranch_execz .LBB0_319
	v_max_i32_e32 v0, 0x80, v92
	v_sub_u32_e32 v0, v0, v92
	v_add_u32_e32 v1, 0x1ff, v0
	v_and_b32_e32 v4, 0x7f, v92
	v_cmp_lt_u32_e32 vcc, s77, v1
	s_mov_b64 s[0:1], -1
	v_mov_b32_e32 v0, v92
	s_and_saveexec_b64 s[64:65], vcc
	s_cbranch_execz .LBB0_312
	v_lshrrev_b32_e32 v5, 9, v1
	v_add_u32_e32 v0, -1, v5
	v_lshrrev_b32_e32 v1, 1, v0
	v_add_u32_e32 v6, 1, v1
	v_cmp_lt_u32_e32 vcc, 5, v0
	v_mov_b32_e32 v10, 0
	v_or_b32_e32 v0, s70, v4
	v_mov_b64_e32 v[2:3], v[92:93]
	s_and_saveexec_b64 s[66:67], vcc
	s_cbranch_execz .LBB0_308
	v_and_b32_e32 v7, -4, v6
	v_mov_b32_e32 v1, v0
	v_lshl_add_u32 v9, v92, 2, s78
	s_mov_b32 s14, 0
	s_mov_b64 s[68:69], 0
	v_mov_b64_e32 v[2:3], v[92:93]

.LBB0_320:
	s_and_b32 s63, s57, 63
	s_ashr_i32 s62, s89, 6
	s_lshl_b32 s0, s63, 8
	s_lshl_b32 s1, s62, 5
	v_and_b32_e32 v94, 31, v92
	s_add_i32 s8, s1, s0
	v_or_b32_e32 v9, s8, v94
	v_add_u32_e32 v0, -2, v9
	v_cmp_gt_u32_e32 vcc, s80, v0
	v_bfe_u32 v93, v92, 5, 1
	s_lshl_b32 s14, s70, 1
	v_cndmask_b32_e32 v2, v9, v0, vcc
	v_mov_b64_e32 v[0:1], s[52:53]
	v_mad_i64_i32 v[2:3], s[0:1], v2, s81, v[0:1]
	v_lshl_add_u64 v[2:3], v[2:3], 0, s[14:15]
	v_lshlrev_b32_e32 v88, 4, v93
	v_lshl_add_u64 v[4:5], v[2:3], 0, v[88:89]
	v_add_co_u32_e64 v2, s[0:1], s82, v4
	s_waitcnt lgkmcnt(0)
	s_nop 0
	v_addc_co_u32_e64 v3, s[0:1], 0, v5, s[0:1]
	s_barrier
	global_load_dwordx4 v[10:13], v[2:3], off offset:1024
	global_load_dwordx4 v[178:181], v[2:3], off offset:1056
	global_load_dwordx4 v[194:197], v[2:3], off offset:1088
	global_load_dwordx4 v[210:213], v[2:3], off offset:1120
	global_load_dwordx4 v[226:229], v[2:3], off offset:1152
	global_load_dwordx4 v[242:245], v[2:3], off offset:1184
	v_add_u32_e32 v2, -1, v9
	v_cmp_gt_u32_e64 s[0:1], s80, v2
	v_add_u32_e32 v18, 1, v9
	s_cmpk_lt_u32 s8, 0x4000
	v_cndmask_b32_e64 v2, v9, v2, s[0:1]
	v_mad_i64_i32 v[2:3], s[4:5], v2, s81, v[0:1]
	v_lshl_add_u64 v[2:3], v[2:3], 0, s[14:15]
	v_lshl_add_u64 v[2:3], v[2:3], 0, v[88:89]
	v_add_co_u32_e64 v6, s[4:5], s82, v2
	v_lshlrev_b32_e32 v138, 8, v94
	s_nop 0
	v_addc_co_u32_e64 v7, s[4:5], 0, v3, s[4:5]
	global_load_dwordx4 v[14:17], v[6:7], off offset:1024
	global_load_dwordx4 v[182:185], v[6:7], off offset:1056
	global_load_dwordx4 v[198:201], v[6:7], off offset:1088
	global_load_dwordx4 v[214:217], v[6:7], off offset:1120
	global_load_dwordx4 v[230:233], v[6:7], off offset:1152
	global_load_dwordx4 v[246:249], v[6:7], off offset:1184
	v_mad_i64_i32 v[6:7], s[4:5], v9, s81, v[0:1]
	v_cmp_gt_u32_e64 s[4:5], s80, v18
	v_lshl_add_u64 v[6:7], v[6:7], 0, s[14:15]
	v_lshl_add_u64 v[52:53], v[6:7], 0, v[88:89]
	v_cndmask_b32_e64 v9, v9, v18, s[4:5]
	v_mad_i64_i32 v[0:1], s[6:7], v9, s81, v[0:1]
	v_add_co_u32_e64 v6, s[6:7], s82, v52
	v_lshl_add_u64 v[0:1], v[0:1], 0, s[14:15]
	s_nop 0
	v_addc_co_u32_e64 v7, s[6:7], 0, v53, s[6:7]
	global_load_dwordx4 v[18:21], v[6:7], off offset:1024
	global_load_dwordx4 v[186:189], v[6:7], off offset:1056
	global_load_dwordx4 v[202:205], v[6:7], off offset:1088
	global_load_dwordx4 v[218:221], v[6:7], off offset:1120
	global_load_dwordx4 v[234:237], v[6:7], off offset:1152
	global_load_dwordx4 v[252:255], v[6:7], off offset:1184
	v_lshl_add_u64 v[6:7], v[0:1], 0, v[88:89]
	v_add_co_u32_e64 v0, s[6:7], s82, v6
	v_lshl_add_u32 v9, v93, 5, 16
	s_nop 0
	v_addc_co_u32_e64 v1, s[6:7], 0, v7, s[6:7]
	global_load_dwordx4 v[22:25], v[0:1], off offset:1024
	global_load_dwordx4 v[190:193], v[0:1], off offset:1056
	global_load_dwordx4 v[206:209], v[0:1], off offset:1088
	global_load_dwordx4 v[222:225], v[0:1], off offset:1120
	global_load_dwordx4 v[238:241], v[0:1], off offset:1152
	global_load_dwordx4 v[168:171], v[0:1], off offset:1184
	ds_read_b128 v[26:29], v9 offset:8192
	s_waitcnt vmcnt(26)
	ds_read_b128 v[30:33], v9 offset:8704
	ds_read_b128 v[34:37], v9 offset:10240
	ds_read_b128 v[38:41], v9 offset:10256
	ds_read_b128 v[42:45], v9 offset:8208
	ds_read_b128 v[46:49], v9 offset:8720
	s_waitcnt lgkmcnt(4)
	v_mov_b32_e32 v51, v30
	v_mov_b32_e32 v30, v27
	v_mov_b32_e32 v27, v32
	v_mov_b32_e32 v50, v26
	v_lshl_add_u64 v[0:1], v[4:5], 0, s[30:31]
	v_mov_b32_e32 v26, v28
	s_cselect_b64 s[6:7], -1, 0
	v_lshl_add_u64 v[6:7], v[6:7], 0, s[30:31]
	v_and_b32_e32 v8, 0x70, v8
	v_add_u32_e32 v95, 16, v138
	v_or_b32_e32 v91, s70, v94
	s_waitcnt vmcnt(23)
	v_cndmask_b32_e32 v32, 0, v11, vcc
	v_cndmask_b32_e32 v10, 0, v10, vcc
	v_lshlrev_b32_e32 v4, 16, v10
	v_and_b32_e32 v10, 0xffff0000, v10
	v_cndmask_b32_e32 v54, 0, v12, vcc
	v_lshlrev_b32_e32 v12, 16, v32
	v_cndmask_b32_e32 v28, 0, v13, vcc
	s_waitcnt vmcnt(17)
	v_cndmask_b32_e64 v11, 0, v14, s[0:1]
	v_lshlrev_b32_e32 v5, 16, v11
	v_pk_mul_f32 v[4:5], v[50:51], v[4:5]
	v_cndmask_b32_e64 v15, 0, v15, s[0:1]
	v_and_b32_e32 v11, 0xffff0000, v11
	s_waitcnt lgkmcnt(3)
	v_add_f32_e32 v4, v34, v4
	v_pk_mul_f32 v[10:11], v[30:31], v[10:11]
	v_add_f32_e32 v30, v4, v5
	v_and_b32_e32 v5, 0xffff0000, v15
	v_and_b32_e32 v4, 0xffff0000, v32
	v_mov_b32_e32 v32, v29
	v_pk_mul_f32 v[4:5], v[32:33], v[4:5]
	v_cndmask_b32_e64 v16, 0, v16, s[0:1]
	v_add_f32_e32 v10, v35, v10
	v_add_f32_e32 v4, v37, v4
	v_add_f32_e32 v31, v10, v11
	v_add_f32_e32 v29, v4, v5
	v_lshlrev_b32_e32 v5, 16, v16
	v_lshlrev_b32_e32 v4, 16, v54
	s_waitcnt lgkmcnt(1)
	v_mov_b32_e32 v10, v42
	s_waitcnt lgkmcnt(0)
	v_mov_b32_e32 v11, v46
	v_pk_mul_f32 v[4:5], v[10:11], v[4:5]
	v_mov_b32_e32 v46, v43
	v_add_f32_e32 v4, v38, v4
	v_add_f32_e32 v32, v4, v5
	v_and_b32_e32 v5, 0xffff0000, v16
	v_and_b32_e32 v4, 0xffff0000, v54
	v_pk_mul_f32 v[4:5], v[46:47], v[4:5]
	v_cndmask_b32_e64 v17, 0, v17, s[0:1]
	v_add_f32_e32 v4, v39, v4
	v_add_f32_e32 v33, v4, v5
	v_lshlrev_b32_e32 v5, 16, v17
	v_lshlrev_b32_e32 v4, 16, v28
	v_mov_b32_e32 v10, v44
	v_mov_b32_e32 v11, v48
	v_pk_mul_f32 v[4:5], v[10:11], v[4:5]
	v_lshlrev_b32_e32 v13, 16, v15
	v_add_f32_e32 v4, v40, v4
	v_pk_mul_f32 v[12:13], v[26:27], v[12:13]
	v_add_f32_e32 v35, v4, v5
	v_and_b32_e32 v5, 0xffff0000, v17
	v_and_b32_e32 v4, 0xffff0000, v28
	v_mov_b32_e32 v48, v45
	v_add_f32_e32 v12, v36, v12
	v_pk_mul_f32 v[4:5], v[48:49], v[4:5]
	v_add_f32_e32 v34, v12, v13
	v_add_f32_e32 v4, v41, v4
	s_waitcnt vmcnt(11)
	v_cndmask_b32_e64 v36, 0, v21, s[6:7]
	v_cndmask_b32_e64 v37, 0, v20, s[6:7]
	v_cndmask_b32_e64 v38, 0, v19, s[6:7]
	v_cndmask_b32_e64 v39, 0, v18, s[6:7]
	ds_read_b128 v[10:13], v9 offset:9216
	ds_read_b128 v[14:17], v9 offset:9232
	s_waitcnt vmcnt(5)
	v_cndmask_b32_e64 v40, 0, v25, s[4:5]
	v_cndmask_b32_e64 v41, 0, v24, s[4:5]
	v_cndmask_b32_e64 v42, 0, v23, s[4:5]
	v_cndmask_b32_e64 v43, 0, v22, s[4:5]
	ds_read_b128 v[18:21], v9 offset:9728
	ds_read_b128 v[22:25], v9 offset:9744
	v_add_f32_e32 v28, v4, v5
	v_lshlrev_b32_e32 v5, 16, v43
	v_lshlrev_b32_e32 v4, 16, v39
	s_waitcnt lgkmcnt(3)
	v_mov_b32_e32 v26, v10
	s_waitcnt lgkmcnt(1)
	v_mov_b32_e32 v27, v18
	v_pk_mul_f32 v[4:5], v[26:27], v[4:5]
	v_mov_b32_e32 v18, v11
	v_add_f32_e32 v4, v30, v4
	v_add_f32_e32 v26, v4, v5
	v_and_b32_e32 v5, 0xffff0000, v43
	v_and_b32_e32 v4, 0xffff0000, v39
	v_pk_mul_f32 v[4:5], v[18:19], v[4:5]
	v_mov_b32_e32 v10, v12
	v_add_f32_e32 v4, v31, v4
	v_add_f32_e32 v18, v4, v5
	v_lshlrev_b32_e32 v5, 16, v42
	v_lshlrev_b32_e32 v4, 16, v38
	v_mov_b32_e32 v11, v20
	v_pk_mul_f32 v[4:5], v[10:11], v[4:5]
	v_mov_b32_e32 v20, v13
	v_add_f32_e32 v4, v34, v4
	v_add_f32_e32 v12, v4, v5
	v_and_b32_e32 v5, 0xffff0000, v42
	v_and_b32_e32 v4, 0xffff0000, v38
	v_pk_mul_f32 v[4:5], v[20:21], v[4:5]
	v_mov_b32_e32 v10, v14
	v_add_f32_e32 v4, v29, v4
	v_add_f32_e32 v13, v4, v5
	v_lshlrev_b32_e32 v5, 16, v41
	v_lshlrev_b32_e32 v4, 16, v37
	s_waitcnt lgkmcnt(0)
	v_mov_b32_e32 v11, v22
	v_pk_mul_f32 v[4:5], v[10:11], v[4:5]
	v_mov_b32_e32 v22, v15
	v_add_f32_e32 v4, v32, v4
	v_add_f32_e32 v14, v4, v5
	v_and_b32_e32 v5, 0xffff0000, v41
	v_and_b32_e32 v4, 0xffff0000, v37
	v_pk_mul_f32 v[4:5], v[22:23], v[4:5]
	v_mov_b32_e32 v10, v16
	v_add_f32_e32 v4, v33, v4
	v_add_f32_e32 v15, v4, v5
	v_lshlrev_b32_e32 v5, 16, v40
	v_lshlrev_b32_e32 v4, 16, v36
	v_mov_b32_e32 v11, v24
	v_pk_mul_f32 v[4:5], v[10:11], v[4:5]
	v_mov_b32_e32 v24, v17
	v_add_f32_e32 v4, v35, v4
	v_add_f32_e32 v10, v4, v5
	v_and_b32_e32 v5, 0xffff0000, v40
	v_and_b32_e32 v4, 0xffff0000, v36
	v_pk_mul_f32 v[4:5], v[24:25], v[4:5]
	v_cvt_pk_bf16_f32 v48, v26, v18
	v_cvt_pk_bf16_f32 v49, v12, v13
	v_cvt_pk_bf16_f32 v50, v14, v15
	s_nop 0
	v_add_f32_e32 v4, v28, v4
	v_add_f32_e32 v4, v4, v5
	v_cvt_pk_bf16_f32 v51, v10, v4
	v_lshl_add_u64 v[4:5], v[2:3], 0, s[30:31]
	v_lshl_add_u64 v[2:3], v[52:53], 0, s[30:31]
	ds_read_b128 v[26:29], v9 offset:10304
	ds_read_b128 v[30:33], v9 offset:10320
	s_waitcnt vmcnt(4)
	v_cndmask_b32_e32 v46, 0, v181, vcc
	v_cndmask_b32_e32 v47, 0, v180, vcc
	v_cndmask_b32_e32 v52, 0, v179, vcc
	v_cndmask_b32_e32 v53, 0, v178, vcc
	ds_read_b128 v[10:13], v9 offset:8256
	ds_read_b128 v[34:37], v9 offset:8272
	s_waitcnt vmcnt(4)
	v_cndmask_b32_e64 v54, 0, v185, s[0:1]
	v_cndmask_b32_e64 v55, 0, v184, s[0:1]
	v_cndmask_b32_e64 v56, 0, v183, s[0:1]
	v_cndmask_b32_e64 v57, 0, v182, s[0:1]
	ds_read_b128 v[14:17], v9 offset:8768
	ds_read_b128 v[38:41], v9 offset:8784
	v_lshlrev_b32_e32 v43, 16, v57
	v_lshlrev_b32_e32 v42, 16, v53
	s_waitcnt lgkmcnt(3)
	v_mov_b32_e32 v44, v10
	s_waitcnt lgkmcnt(1)
	v_mov_b32_e32 v45, v14
	v_pk_mul_f32 v[42:43], v[44:45], v[42:43]
	v_mov_b32_e32 v14, v11
	v_add_f32_e32 v10, v26, v42
	v_add_f32_e32 v44, v10, v43
	v_and_b32_e32 v43, 0xffff0000, v57
	v_and_b32_e32 v42, 0xffff0000, v53
	v_pk_mul_f32 v[10:11], v[14:15], v[42:43]
	v_mov_b32_e32 v14, v12
	v_add_f32_e32 v10, v27, v10
	v_add_f32_e32 v42, v10, v11
	v_lshlrev_b32_e32 v11, 16, v56
	v_lshlrev_b32_e32 v10, 16, v52
	v_mov_b32_e32 v15, v16
	v_pk_mul_f32 v[10:11], v[14:15], v[10:11]
	v_mov_b32_e32 v16, v13
	v_add_f32_e32 v10, v28, v10
	v_add_f32_e32 v43, v10, v11
	v_and_b32_e32 v11, 0xffff0000, v56
	v_and_b32_e32 v10, 0xffff0000, v52
	v_pk_mul_f32 v[10:11], v[16:17], v[10:11]
	v_mov_b32_e32 v12, v34
	v_add_f32_e32 v10, v29, v10
	v_add_f32_e32 v45, v10, v11
	v_lshlrev_b32_e32 v11, 16, v55
	v_lshlrev_b32_e32 v10, 16, v47
	s_waitcnt lgkmcnt(0)
	v_mov_b32_e32 v13, v38
	v_pk_mul_f32 v[10:11], v[12:13], v[10:11]
	v_mov_b32_e32 v38, v35
	v_add_f32_e32 v10, v30, v10
	v_add_f32_e32 v30, v10, v11
	v_and_b32_e32 v11, 0xffff0000, v55
	v_and_b32_e32 v10, 0xffff0000, v47
	v_pk_mul_f32 v[10:11], v[38:39], v[10:11]
	v_mov_b32_e32 v12, v36
	v_add_f32_e32 v10, v31, v10
	v_add_f32_e32 v31, v10, v11
	v_lshlrev_b32_e32 v11, 16, v54
	v_lshlrev_b32_e32 v10, 16, v46
	v_mov_b32_e32 v13, v40
	v_pk_mul_f32 v[10:11], v[12:13], v[10:11]
	v_mov_b32_e32 v40, v37
	v_add_f32_e32 v10, v32, v10
	v_add_f32_e32 v32, v10, v11
	v_and_b32_e32 v11, 0xffff0000, v54
	v_and_b32_e32 v10, 0xffff0000, v46
	v_pk_mul_f32 v[10:11], v[40:41], v[10:11]
	s_waitcnt vmcnt(4)
	v_cndmask_b32_e64 v34, 0, v189, s[6:7]
	v_add_f32_e32 v10, v33, v10
	v_add_f32_e32 v33, v10, v11
	v_cndmask_b32_e64 v35, 0, v188, s[6:7]
	v_cndmask_b32_e64 v36, 0, v187, s[6:7]
	v_cndmask_b32_e64 v37, 0, v186, s[6:7]
	ds_read_b128 v[10:13], v9 offset:9280
	ds_read_b128 v[14:17], v9 offset:9296
	v_cndmask_b32_e64 v38, 0, v193, s[4:5]
	v_cndmask_b32_e64 v39, 0, v192, s[4:5]
	v_cndmask_b32_e64 v40, 0, v191, s[4:5]
	v_cndmask_b32_e64 v41, 0, v190, s[4:5]
	ds_read_b128 v[18:21], v9 offset:9792
	ds_read_b128 v[22:25], v9 offset:9808
	v_lshlrev_b32_e32 v27, 16, v41
	v_lshlrev_b32_e32 v26, 16, v37
	s_waitcnt lgkmcnt(3)
	v_mov_b32_e32 v28, v10
	s_waitcnt lgkmcnt(1)
	v_mov_b32_e32 v29, v18
	v_pk_mul_f32 v[26:27], v[28:29], v[26:27]
	v_mov_b32_e32 v18, v11
	v_add_f32_e32 v10, v44, v26
	v_add_f32_e32 v28, v10, v27
	v_and_b32_e32 v27, 0xffff0000, v41
	v_and_b32_e32 v26, 0xffff0000, v37
	v_pk_mul_f32 v[10:11], v[18:19], v[26:27]
	v_mov_b32_e32 v18, v12
	v_add_f32_e32 v10, v42, v10
	v_add_f32_e32 v26, v10, v11
	v_lshlrev_b32_e32 v11, 16, v40
	v_lshlrev_b32_e32 v10, 16, v36
	v_mov_b32_e32 v19, v20
	v_pk_mul_f32 v[10:11], v[18:19], v[10:11]
	v_mov_b32_e32 v20, v13
	v_add_f32_e32 v10, v43, v10
	v_add_f32_e32 v18, v10, v11
	v_and_b32_e32 v11, 0xffff0000, v40
	v_and_b32_e32 v10, 0xffff0000, v36
	v_pk_mul_f32 v[10:11], v[20:21], v[10:11]
	v_mov_b32_e32 v12, v14
	v_add_f32_e32 v10, v45, v10
	v_add_f32_e32 v19, v10, v11
	v_lshlrev_b32_e32 v11, 16, v39
	v_lshlrev_b32_e32 v10, 16, v35
	s_waitcnt lgkmcnt(0)
	v_mov_b32_e32 v13, v22
	v_pk_mul_f32 v[10:11], v[12:13], v[10:11]
	v_mov_b32_e32 v22, v15
	v_add_f32_e32 v10, v30, v10
	v_add_f32_e32 v14, v10, v11
	v_and_b32_e32 v11, 0xffff0000, v39
	v_and_b32_e32 v10, 0xffff0000, v35
	v_pk_mul_f32 v[10:11], v[22:23], v[10:11]
	v_mov_b32_e32 v12, v16
	v_add_f32_e32 v10, v31, v10
	v_add_f32_e32 v15, v10, v11
	v_lshlrev_b32_e32 v11, 16, v38
	v_lshlrev_b32_e32 v10, 16, v34
	v_mov_b32_e32 v13, v24
	v_pk_mul_f32 v[10:11], v[12:13], v[10:11]
	v_mov_b32_e32 v24, v17
	v_add_f32_e32 v10, v32, v10
	v_add_f32_e32 v12, v10, v11
	v_and_b32_e32 v11, 0xffff0000, v38
	v_and_b32_e32 v10, 0xffff0000, v34
	v_pk_mul_f32 v[10:11], v[24:25], v[10:11]
	v_cvt_pk_bf16_f32 v52, v28, v26
	v_cvt_pk_bf16_f32 v53, v18, v19
	v_cvt_pk_bf16_f32 v54, v14, v15
	s_nop 0
	v_add_f32_e32 v10, v33, v10
	v_add_f32_e32 v10, v10, v11
	v_cvt_pk_bf16_f32 v55, v12, v10
	global_load_dwordx4 v[178:181], v[0:1], off offset:192
	global_load_dwordx4 v[182:185], v[4:5], off offset:192
	global_load_dwordx4 v[186:189], v[2:3], off offset:192
	global_load_dwordx4 v[190:193], v[6:7], off offset:192
	ds_read_b128 v[26:29], v9 offset:10368
	ds_read_b128 v[30:33], v9 offset:10384
	s_waitcnt vmcnt(7)
	v_cndmask_b32_e32 v46, 0, v197, vcc
	v_cndmask_b32_e32 v47, 0, v196, vcc
	v_cndmask_b32_e32 v56, 0, v195, vcc
	v_cndmask_b32_e32 v57, 0, v194, vcc
	ds_read_b128 v[10:13], v9 offset:8320
	ds_read_b128 v[34:37], v9 offset:8336
	s_waitcnt vmcnt(7)
	v_cndmask_b32_e64 v58, 0, v201, s[0:1]
	v_cndmask_b32_e64 v59, 0, v200, s[0:1]
	v_cndmask_b32_e64 v60, 0, v199, s[0:1]
	v_cndmask_b32_e64 v61, 0, v198, s[0:1]
	ds_read_b128 v[14:17], v9 offset:8832
	ds_read_b128 v[38:41], v9 offset:8848
	v_lshlrev_b32_e32 v43, 16, v61
	v_lshlrev_b32_e32 v42, 16, v57
	s_waitcnt lgkmcnt(3)
	v_mov_b32_e32 v44, v10
	s_waitcnt lgkmcnt(1)
	v_mov_b32_e32 v45, v14
	v_pk_mul_f32 v[42:43], v[44:45], v[42:43]
	v_mov_b32_e32 v14, v11
	v_add_f32_e32 v10, v26, v42
	v_add_f32_e32 v44, v10, v43
	v_and_b32_e32 v43, 0xffff0000, v61
	v_and_b32_e32 v42, 0xffff0000, v57
	v_pk_mul_f32 v[10:11], v[14:15], v[42:43]
	v_mov_b32_e32 v14, v12
	v_add_f32_e32 v10, v27, v10
	v_add_f32_e32 v42, v10, v11
	v_lshlrev_b32_e32 v11, 16, v60
	v_lshlrev_b32_e32 v10, 16, v56
	v_mov_b32_e32 v15, v16
	v_pk_mul_f32 v[10:11], v[14:15], v[10:11]
	v_mov_b32_e32 v16, v13
	v_add_f32_e32 v10, v28, v10
	v_add_f32_e32 v43, v10, v11
	v_and_b32_e32 v11, 0xffff0000, v60
	v_and_b32_e32 v10, 0xffff0000, v56
	v_pk_mul_f32 v[10:11], v[16:17], v[10:11]
	v_mov_b32_e32 v12, v34
	v_add_f32_e32 v10, v29, v10
	v_add_f32_e32 v45, v10, v11
	v_lshlrev_b32_e32 v11, 16, v59
	v_lshlrev_b32_e32 v10, 16, v47
	s_waitcnt lgkmcnt(0)
	v_mov_b32_e32 v13, v38
	v_pk_mul_f32 v[10:11], v[12:13], v[10:11]
	v_mov_b32_e32 v38, v35
	v_add_f32_e32 v10, v30, v10
	v_add_f32_e32 v30, v10, v11
	v_and_b32_e32 v11, 0xffff0000, v59
	v_and_b32_e32 v10, 0xffff0000, v47
	v_pk_mul_f32 v[10:11], v[38:39], v[10:11]
	v_mov_b32_e32 v12, v36
	v_add_f32_e32 v10, v31, v10
	v_add_f32_e32 v31, v10, v11
	v_lshlrev_b32_e32 v11, 16, v58
	v_lshlrev_b32_e32 v10, 16, v46
	v_mov_b32_e32 v13, v40
	v_pk_mul_f32 v[10:11], v[12:13], v[10:11]
	v_mov_b32_e32 v40, v37
	v_add_f32_e32 v10, v32, v10
	v_add_f32_e32 v32, v10, v11
	v_and_b32_e32 v11, 0xffff0000, v58
	v_and_b32_e32 v10, 0xffff0000, v46
	v_pk_mul_f32 v[10:11], v[40:41], v[10:11]
	s_waitcnt vmcnt(7)
	v_cndmask_b32_e64 v34, 0, v205, s[6:7]
	v_add_f32_e32 v10, v33, v10
	v_add_f32_e32 v33, v10, v11
	v_cndmask_b32_e64 v35, 0, v204, s[6:7]
	v_cndmask_b32_e64 v36, 0, v203, s[6:7]
	v_cndmask_b32_e64 v37, 0, v202, s[6:7]
	ds_read_b128 v[10:13], v9 offset:9344
	ds_read_b128 v[14:17], v9 offset:9360
	s_waitcnt vmcnt(7)
	v_cndmask_b32_e64 v38, 0, v209, s[4:5]
	v_cndmask_b32_e64 v39, 0, v208, s[4:5]
	v_cndmask_b32_e64 v40, 0, v207, s[4:5]
	v_cndmask_b32_e64 v41, 0, v206, s[4:5]
	ds_read_b128 v[18:21], v9 offset:9856
	ds_read_b128 v[22:25], v9 offset:9872
	v_lshlrev_b32_e32 v27, 16, v41
	v_lshlrev_b32_e32 v26, 16, v37
	s_waitcnt lgkmcnt(3)
	v_mov_b32_e32 v28, v10
	s_waitcnt lgkmcnt(1)
	v_mov_b32_e32 v29, v18
	v_pk_mul_f32 v[26:27], v[28:29], v[26:27]
	v_mov_b32_e32 v18, v11
	v_add_f32_e32 v10, v44, v26
	v_add_f32_e32 v28, v10, v27
	v_and_b32_e32 v27, 0xffff0000, v41
	v_and_b32_e32 v26, 0xffff0000, v37
	v_pk_mul_f32 v[10:11], v[18:19], v[26:27]
	v_mov_b32_e32 v18, v12
	v_add_f32_e32 v10, v42, v10
	v_add_f32_e32 v26, v10, v11
	v_lshlrev_b32_e32 v11, 16, v40
	v_lshlrev_b32_e32 v10, 16, v36
	v_mov_b32_e32 v19, v20
	v_pk_mul_f32 v[10:11], v[18:19], v[10:11]
	v_mov_b32_e32 v20, v13
	v_add_f32_e32 v10, v43, v10
	v_add_f32_e32 v18, v10, v11
	v_and_b32_e32 v11, 0xffff0000, v40
	v_and_b32_e32 v10, 0xffff0000, v36
	v_pk_mul_f32 v[10:11], v[20:21], v[10:11]
	v_mov_b32_e32 v12, v14
	v_add_f32_e32 v10, v45, v10
	v_add_f32_e32 v19, v10, v11
	v_lshlrev_b32_e32 v11, 16, v39
	v_lshlrev_b32_e32 v10, 16, v35
	s_waitcnt lgkmcnt(0)
	v_mov_b32_e32 v13, v22
	v_pk_mul_f32 v[10:11], v[12:13], v[10:11]
	v_mov_b32_e32 v22, v15
	v_add_f32_e32 v10, v30, v10
	v_add_f32_e32 v14, v10, v11
	v_and_b32_e32 v11, 0xffff0000, v39
	v_and_b32_e32 v10, 0xffff0000, v35
	v_pk_mul_f32 v[10:11], v[22:23], v[10:11]
	v_mov_b32_e32 v12, v16
	v_add_f32_e32 v10, v31, v10
	v_add_f32_e32 v15, v10, v11
	v_lshlrev_b32_e32 v11, 16, v38
	v_lshlrev_b32_e32 v10, 16, v34
	v_mov_b32_e32 v13, v24
	v_pk_mul_f32 v[10:11], v[12:13], v[10:11]
	v_mov_b32_e32 v24, v17
	v_add_f32_e32 v10, v32, v10
	v_add_f32_e32 v12, v10, v11
	v_and_b32_e32 v11, 0xffff0000, v38
	v_and_b32_e32 v10, 0xffff0000, v34
	v_pk_mul_f32 v[10:11], v[24:25], v[10:11]
	v_cvt_pk_bf16_f32 v56, v28, v26
	v_cvt_pk_bf16_f32 v57, v18, v19
	v_cvt_pk_bf16_f32 v58, v14, v15
	s_nop 0
	v_add_f32_e32 v10, v33, v10
	v_add_f32_e32 v10, v10, v11
	v_cvt_pk_bf16_f32 v59, v12, v10
	global_load_dwordx4 v[194:197], v[0:1], off offset:224
	global_load_dwordx4 v[198:201], v[4:5], off offset:224
	global_load_dwordx4 v[202:205], v[2:3], off offset:224
	global_load_dwordx4 v[206:209], v[6:7], off offset:224
	ds_read_b128 v[26:29], v9 offset:10432
	ds_read_b128 v[30:33], v9 offset:10448
	s_waitcnt vmcnt(10)
	v_cndmask_b32_e32 v46, 0, v213, vcc
	v_cndmask_b32_e32 v47, 0, v212, vcc
	v_cndmask_b32_e32 v60, 0, v211, vcc
	v_cndmask_b32_e32 v61, 0, v210, vcc
	ds_read_b128 v[10:13], v9 offset:8384
	ds_read_b128 v[34:37], v9 offset:8400
	s_waitcnt vmcnt(10)
	v_cndmask_b32_e64 v62, 0, v217, s[0:1]
	v_cndmask_b32_e64 v63, 0, v216, s[0:1]
	v_cndmask_b32_e64 v64, 0, v215, s[0:1]
	v_cndmask_b32_e64 v65, 0, v214, s[0:1]
	ds_read_b128 v[14:17], v9 offset:8896
	ds_read_b128 v[38:41], v9 offset:8912
	v_lshlrev_b32_e32 v43, 16, v65
	v_lshlrev_b32_e32 v42, 16, v61
	s_waitcnt lgkmcnt(3)
	v_mov_b32_e32 v44, v10
	s_waitcnt lgkmcnt(1)
	v_mov_b32_e32 v45, v14
	v_pk_mul_f32 v[42:43], v[44:45], v[42:43]
	v_mov_b32_e32 v14, v11
	v_add_f32_e32 v10, v26, v42
	v_add_f32_e32 v44, v10, v43
	v_and_b32_e32 v43, 0xffff0000, v65
	v_and_b32_e32 v42, 0xffff0000, v61
	v_pk_mul_f32 v[10:11], v[14:15], v[42:43]
	v_mov_b32_e32 v14, v12
	v_add_f32_e32 v10, v27, v10
	v_add_f32_e32 v42, v10, v11
	v_lshlrev_b32_e32 v11, 16, v64
	v_lshlrev_b32_e32 v10, 16, v60
	v_mov_b32_e32 v15, v16
	v_pk_mul_f32 v[10:11], v[14:15], v[10:11]
	v_mov_b32_e32 v16, v13
	v_add_f32_e32 v10, v28, v10
	v_add_f32_e32 v43, v10, v11
	v_and_b32_e32 v11, 0xffff0000, v64
	v_and_b32_e32 v10, 0xffff0000, v60
	v_pk_mul_f32 v[10:11], v[16:17], v[10:11]
	v_mov_b32_e32 v12, v34
	v_add_f32_e32 v10, v29, v10
	v_add_f32_e32 v45, v10, v11
	v_lshlrev_b32_e32 v11, 16, v63
	v_lshlrev_b32_e32 v10, 16, v47
	s_waitcnt lgkmcnt(0)
	v_mov_b32_e32 v13, v38
	v_pk_mul_f32 v[10:11], v[12:13], v[10:11]
	v_mov_b32_e32 v38, v35
	v_add_f32_e32 v10, v30, v10
	v_add_f32_e32 v30, v10, v11
	v_and_b32_e32 v11, 0xffff0000, v63
	v_and_b32_e32 v10, 0xffff0000, v47
	v_pk_mul_f32 v[10:11], v[38:39], v[10:11]
	v_mov_b32_e32 v12, v36
	v_add_f32_e32 v10, v31, v10
	v_add_f32_e32 v31, v10, v11
	v_lshlrev_b32_e32 v11, 16, v62
	v_lshlrev_b32_e32 v10, 16, v46
	v_mov_b32_e32 v13, v40
	v_pk_mul_f32 v[10:11], v[12:13], v[10:11]
	v_mov_b32_e32 v40, v37
	v_add_f32_e32 v10, v32, v10
	v_add_f32_e32 v32, v10, v11
	v_and_b32_e32 v11, 0xffff0000, v62
	v_and_b32_e32 v10, 0xffff0000, v46
	v_pk_mul_f32 v[10:11], v[40:41], v[10:11]
	s_waitcnt vmcnt(10)
	v_cndmask_b32_e64 v34, 0, v221, s[6:7]
	v_add_f32_e32 v10, v33, v10
	v_add_f32_e32 v33, v10, v11
	v_cndmask_b32_e64 v35, 0, v220, s[6:7]
	v_cndmask_b32_e64 v36, 0, v219, s[6:7]
	v_cndmask_b32_e64 v37, 0, v218, s[6:7]
	ds_read_b128 v[10:13], v9 offset:9408
	ds_read_b128 v[14:17], v9 offset:9424
	s_waitcnt vmcnt(10)
	v_cndmask_b32_e64 v38, 0, v225, s[4:5]
	v_cndmask_b32_e64 v39, 0, v224, s[4:5]
	v_cndmask_b32_e64 v40, 0, v223, s[4:5]
	v_cndmask_b32_e64 v41, 0, v222, s[4:5]
	ds_read_b128 v[18:21], v9 offset:9920
	ds_read_b128 v[22:25], v9 offset:9936
	v_lshlrev_b32_e32 v27, 16, v41
	v_lshlrev_b32_e32 v26, 16, v37
	s_waitcnt lgkmcnt(3)
	v_mov_b32_e32 v28, v10
	s_waitcnt lgkmcnt(1)
	v_mov_b32_e32 v29, v18
	v_pk_mul_f32 v[26:27], v[28:29], v[26:27]
	v_mov_b32_e32 v18, v11
	v_add_f32_e32 v10, v44, v26
	v_add_f32_e32 v28, v10, v27
	v_and_b32_e32 v27, 0xffff0000, v41
	v_and_b32_e32 v26, 0xffff0000, v37
	v_pk_mul_f32 v[10:11], v[18:19], v[26:27]
	v_mov_b32_e32 v18, v12
	v_add_f32_e32 v10, v42, v10
	v_add_f32_e32 v26, v10, v11
	v_lshlrev_b32_e32 v11, 16, v40
	v_lshlrev_b32_e32 v10, 16, v36
	v_mov_b32_e32 v19, v20
	v_pk_mul_f32 v[10:11], v[18:19], v[10:11]
	v_mov_b32_e32 v20, v13
	v_add_f32_e32 v10, v43, v10
	v_add_f32_e32 v18, v10, v11
	v_and_b32_e32 v11, 0xffff0000, v40
	v_and_b32_e32 v10, 0xffff0000, v36
	v_pk_mul_f32 v[10:11], v[20:21], v[10:11]
	v_mov_b32_e32 v12, v14
	v_add_f32_e32 v10, v45, v10
	v_add_f32_e32 v19, v10, v11
	v_lshlrev_b32_e32 v11, 16, v39
	v_lshlrev_b32_e32 v10, 16, v35
	s_waitcnt lgkmcnt(0)
	v_mov_b32_e32 v13, v22
	v_pk_mul_f32 v[10:11], v[12:13], v[10:11]
	v_mov_b32_e32 v22, v15
	v_add_f32_e32 v10, v30, v10
	v_add_f32_e32 v14, v10, v11
	v_and_b32_e32 v11, 0xffff0000, v39
	v_and_b32_e32 v10, 0xffff0000, v35
	v_pk_mul_f32 v[10:11], v[22:23], v[10:11]
	v_mov_b32_e32 v12, v16
	v_add_f32_e32 v10, v31, v10
	v_add_f32_e32 v15, v10, v11
	v_lshlrev_b32_e32 v11, 16, v38
	v_lshlrev_b32_e32 v10, 16, v34
	v_mov_b32_e32 v13, v24
	v_pk_mul_f32 v[10:11], v[12:13], v[10:11]
	v_mov_b32_e32 v24, v17
	v_add_f32_e32 v10, v32, v10
	v_add_f32_e32 v12, v10, v11
	v_and_b32_e32 v11, 0xffff0000, v38
	v_and_b32_e32 v10, 0xffff0000, v34
	v_pk_mul_f32 v[10:11], v[24:25], v[10:11]
	v_cvt_pk_bf16_f32 v60, v28, v26
	v_cvt_pk_bf16_f32 v61, v18, v19
	v_cvt_pk_bf16_f32 v62, v14, v15
	s_nop 0
	v_add_f32_e32 v10, v33, v10
	v_add_f32_e32 v10, v10, v11
	v_cvt_pk_bf16_f32 v63, v12, v10
	ds_read_b128 v[26:29], v9 offset:10496
	ds_read_b128 v[30:33], v9 offset:10512
	s_waitcnt vmcnt(9)
	v_cndmask_b32_e32 v46, 0, v229, vcc
	v_cndmask_b32_e32 v47, 0, v228, vcc
	v_cndmask_b32_e32 v64, 0, v227, vcc
	v_cndmask_b32_e32 v65, 0, v226, vcc
	ds_read_b128 v[10:13], v9 offset:8448
	ds_read_b128 v[34:37], v9 offset:8464
	s_waitcnt vmcnt(9)
	v_cndmask_b32_e64 v66, 0, v233, s[0:1]
	v_cndmask_b32_e64 v67, 0, v232, s[0:1]
	v_cndmask_b32_e64 v68, 0, v231, s[0:1]
	v_cndmask_b32_e64 v69, 0, v230, s[0:1]
	ds_read_b128 v[14:17], v9 offset:8960
	ds_read_b128 v[38:41], v9 offset:8976
	v_lshlrev_b32_e32 v43, 16, v69
	v_lshlrev_b32_e32 v42, 16, v65
	s_waitcnt lgkmcnt(3)
	v_mov_b32_e32 v44, v10
	s_waitcnt lgkmcnt(1)
	v_mov_b32_e32 v45, v14
	v_pk_mul_f32 v[42:43], v[44:45], v[42:43]
	v_mov_b32_e32 v14, v11
	v_add_f32_e32 v10, v26, v42
	v_add_f32_e32 v44, v10, v43
	v_and_b32_e32 v43, 0xffff0000, v69
	v_and_b32_e32 v42, 0xffff0000, v65
	v_pk_mul_f32 v[10:11], v[14:15], v[42:43]
	v_mov_b32_e32 v14, v12
	v_add_f32_e32 v10, v27, v10
	v_add_f32_e32 v42, v10, v11
	v_lshlrev_b32_e32 v11, 16, v68
	v_lshlrev_b32_e32 v10, 16, v64
	v_mov_b32_e32 v15, v16
	v_pk_mul_f32 v[10:11], v[14:15], v[10:11]
	v_mov_b32_e32 v16, v13
	v_add_f32_e32 v10, v28, v10
	v_add_f32_e32 v43, v10, v11
	v_and_b32_e32 v11, 0xffff0000, v68
	v_and_b32_e32 v10, 0xffff0000, v64
	v_pk_mul_f32 v[10:11], v[16:17], v[10:11]
	v_mov_b32_e32 v12, v34
	v_add_f32_e32 v10, v29, v10
	v_add_f32_e32 v45, v10, v11
	v_lshlrev_b32_e32 v11, 16, v67
	v_lshlrev_b32_e32 v10, 16, v47
	s_waitcnt lgkmcnt(0)
	v_mov_b32_e32 v13, v38
	v_pk_mul_f32 v[10:11], v[12:13], v[10:11]
	v_mov_b32_e32 v38, v35
	v_add_f32_e32 v10, v30, v10
	v_add_f32_e32 v30, v10, v11
	v_and_b32_e32 v11, 0xffff0000, v67
	v_and_b32_e32 v10, 0xffff0000, v47
	v_pk_mul_f32 v[10:11], v[38:39], v[10:11]
	v_mov_b32_e32 v12, v36
	v_add_f32_e32 v10, v31, v10
	v_add_f32_e32 v31, v10, v11
	v_lshlrev_b32_e32 v11, 16, v66
	v_lshlrev_b32_e32 v10, 16, v46
	v_mov_b32_e32 v13, v40
	v_pk_mul_f32 v[10:11], v[12:13], v[10:11]
	v_mov_b32_e32 v40, v37
	v_add_f32_e32 v10, v32, v10
	v_add_f32_e32 v32, v10, v11
	v_and_b32_e32 v11, 0xffff0000, v66
	v_and_b32_e32 v10, 0xffff0000, v46
	v_pk_mul_f32 v[10:11], v[40:41], v[10:11]
	s_waitcnt vmcnt(9)
	v_cndmask_b32_e64 v34, 0, v237, s[6:7]
	v_add_f32_e32 v10, v33, v10
	v_add_f32_e32 v33, v10, v11
	v_cndmask_b32_e64 v35, 0, v236, s[6:7]
	v_cndmask_b32_e64 v36, 0, v235, s[6:7]
	v_cndmask_b32_e64 v37, 0, v234, s[6:7]
	ds_read_b128 v[10:13], v9 offset:9472
	ds_read_b128 v[14:17], v9 offset:9488
	s_waitcnt vmcnt(9)
	v_cndmask_b32_e64 v38, 0, v241, s[4:5]
	v_cndmask_b32_e64 v39, 0, v240, s[4:5]
	v_cndmask_b32_e64 v40, 0, v239, s[4:5]
	v_cndmask_b32_e64 v41, 0, v238, s[4:5]
	ds_read_b128 v[18:21], v9 offset:9984
	ds_read_b128 v[22:25], v9 offset:10000
	v_lshlrev_b32_e32 v27, 16, v41
	v_lshlrev_b32_e32 v26, 16, v37
	s_waitcnt lgkmcnt(3)
	v_mov_b32_e32 v28, v10
	s_waitcnt lgkmcnt(1)
	v_mov_b32_e32 v29, v18
	v_pk_mul_f32 v[26:27], v[28:29], v[26:27]
	v_mov_b32_e32 v18, v11
	v_add_f32_e32 v10, v44, v26
	v_add_f32_e32 v28, v10, v27
	v_and_b32_e32 v27, 0xffff0000, v41
	v_and_b32_e32 v26, 0xffff0000, v37
	v_pk_mul_f32 v[10:11], v[18:19], v[26:27]
	v_mov_b32_e32 v18, v12
	v_add_f32_e32 v10, v42, v10
	v_add_f32_e32 v26, v10, v11
	v_lshlrev_b32_e32 v11, 16, v40
	v_lshlrev_b32_e32 v10, 16, v36
	v_mov_b32_e32 v19, v20
	v_pk_mul_f32 v[10:11], v[18:19], v[10:11]
	v_mov_b32_e32 v20, v13
	v_add_f32_e32 v10, v43, v10
	v_add_f32_e32 v18, v10, v11
	v_and_b32_e32 v11, 0xffff0000, v40
	v_and_b32_e32 v10, 0xffff0000, v36
	v_pk_mul_f32 v[10:11], v[20:21], v[10:11]
	v_mov_b32_e32 v12, v14
	v_add_f32_e32 v10, v45, v10
	v_add_f32_e32 v19, v10, v11
	v_lshlrev_b32_e32 v11, 16, v39
	v_lshlrev_b32_e32 v10, 16, v35
	s_waitcnt lgkmcnt(0)
	v_mov_b32_e32 v13, v22
	v_pk_mul_f32 v[10:11], v[12:13], v[10:11]
	v_mov_b32_e32 v22, v15
	v_add_f32_e32 v10, v30, v10
	v_add_f32_e32 v14, v10, v11
	v_and_b32_e32 v11, 0xffff0000, v39
	v_and_b32_e32 v10, 0xffff0000, v35
	v_pk_mul_f32 v[10:11], v[22:23], v[10:11]
	v_mov_b32_e32 v12, v16
	v_add_f32_e32 v10, v31, v10
	v_add_f32_e32 v15, v10, v11
	v_lshlrev_b32_e32 v11, 16, v38
	v_lshlrev_b32_e32 v10, 16, v34
	v_mov_b32_e32 v13, v24
	v_pk_mul_f32 v[10:11], v[12:13], v[10:11]
	v_mov_b32_e32 v24, v17
	v_add_f32_e32 v10, v32, v10
	v_add_f32_e32 v12, v10, v11
	v_and_b32_e32 v11, 0xffff0000, v38
	v_and_b32_e32 v10, 0xffff0000, v34
	v_pk_mul_f32 v[10:11], v[24:25], v[10:11]
	v_cvt_pk_bf16_f32 v64, v28, v26
	v_cvt_pk_bf16_f32 v65, v18, v19
	v_cvt_pk_bf16_f32 v66, v14, v15
	s_nop 0
	v_add_f32_e32 v10, v33, v10
	v_add_f32_e32 v10, v10, v11
	v_cvt_pk_bf16_f32 v67, v12, v10
	ds_read_b128 v[26:29], v9 offset:10560
	ds_read_b128 v[30:33], v9 offset:10576
	s_waitcnt vmcnt(8)
	v_cndmask_b32_e32 v46, 0, v245, vcc
	v_cndmask_b32_e32 v47, 0, v244, vcc
	v_cndmask_b32_e32 v68, 0, v243, vcc
	v_cndmask_b32_e32 v69, 0, v242, vcc
	ds_read_b128 v[10:13], v9 offset:8512
	ds_read_b128 v[34:37], v9 offset:8528
	s_waitcnt vmcnt(8)
	v_cndmask_b32_e64 v70, 0, v249, s[0:1]
	v_cndmask_b32_e64 v71, 0, v248, s[0:1]
	v_cndmask_b32_e64 v72, 0, v247, s[0:1]
	v_cndmask_b32_e64 v73, 0, v246, s[0:1]
	ds_read_b128 v[14:17], v9 offset:9024
	ds_read_b128 v[38:41], v9 offset:9040
	v_lshlrev_b32_e32 v43, 16, v73
	v_lshlrev_b32_e32 v42, 16, v69
	s_waitcnt lgkmcnt(3)
	v_mov_b32_e32 v44, v10
	s_waitcnt lgkmcnt(1)
	v_mov_b32_e32 v45, v14
	v_pk_mul_f32 v[42:43], v[44:45], v[42:43]
	v_mov_b32_e32 v14, v11
	v_add_f32_e32 v10, v26, v42
	v_add_f32_e32 v44, v10, v43
	v_and_b32_e32 v43, 0xffff0000, v73
	v_and_b32_e32 v42, 0xffff0000, v69
	v_pk_mul_f32 v[10:11], v[14:15], v[42:43]
	v_mov_b32_e32 v14, v12
	v_add_f32_e32 v10, v27, v10
	v_add_f32_e32 v42, v10, v11
	v_lshlrev_b32_e32 v11, 16, v72
	v_lshlrev_b32_e32 v10, 16, v68
	v_mov_b32_e32 v15, v16
	v_pk_mul_f32 v[10:11], v[14:15], v[10:11]
	v_mov_b32_e32 v16, v13
	v_add_f32_e32 v10, v28, v10
	v_add_f32_e32 v43, v10, v11
	v_and_b32_e32 v11, 0xffff0000, v72
	v_and_b32_e32 v10, 0xffff0000, v68
	v_pk_mul_f32 v[10:11], v[16:17], v[10:11]
	v_mov_b32_e32 v12, v34
	v_add_f32_e32 v10, v29, v10
	v_add_f32_e32 v45, v10, v11
	v_lshlrev_b32_e32 v11, 16, v71
	v_lshlrev_b32_e32 v10, 16, v47
	s_waitcnt lgkmcnt(0)
	v_mov_b32_e32 v13, v38
	v_pk_mul_f32 v[10:11], v[12:13], v[10:11]
	v_mov_b32_e32 v38, v35
	v_add_f32_e32 v10, v30, v10
	v_add_f32_e32 v30, v10, v11
	v_and_b32_e32 v11, 0xffff0000, v71
	v_and_b32_e32 v10, 0xffff0000, v47
	v_pk_mul_f32 v[10:11], v[38:39], v[10:11]
	v_mov_b32_e32 v12, v36
	v_add_f32_e32 v10, v31, v10
	v_add_f32_e32 v31, v10, v11
	v_lshlrev_b32_e32 v11, 16, v70
	v_lshlrev_b32_e32 v10, 16, v46
	v_mov_b32_e32 v13, v40
	v_pk_mul_f32 v[10:11], v[12:13], v[10:11]
	v_mov_b32_e32 v40, v37
	v_add_f32_e32 v10, v32, v10
	v_add_f32_e32 v32, v10, v11
	v_and_b32_e32 v11, 0xffff0000, v70
	v_and_b32_e32 v10, 0xffff0000, v46
	v_pk_mul_f32 v[10:11], v[40:41], v[10:11]
	s_waitcnt vmcnt(8)
	v_cndmask_b32_e64 v34, 0, v255, s[6:7]
	v_add_f32_e32 v10, v33, v10
	v_add_f32_e32 v33, v10, v11
	v_cndmask_b32_e64 v35, 0, v254, s[6:7]
	v_cndmask_b32_e64 v36, 0, v253, s[6:7]
	v_cndmask_b32_e64 v37, 0, v252, s[6:7]
	ds_read_b128 v[10:13], v9 offset:9536
	ds_read_b128 v[14:17], v9 offset:9552
	s_waitcnt vmcnt(8)
	v_cndmask_b32_e64 v38, 0, v171, s[4:5]
	v_cndmask_b32_e64 v39, 0, v170, s[4:5]
	v_cndmask_b32_e64 v40, 0, v169, s[4:5]
	v_cndmask_b32_e64 v41, 0, v168, s[4:5]
	ds_read_b128 v[18:21], v9 offset:10048
	ds_read_b128 v[22:25], v9 offset:10064
	v_lshlrev_b32_e32 v27, 16, v41
	v_lshlrev_b32_e32 v26, 16, v37
	s_waitcnt lgkmcnt(3)
	v_mov_b32_e32 v28, v10
	s_waitcnt lgkmcnt(1)
	v_mov_b32_e32 v29, v18
	v_pk_mul_f32 v[26:27], v[28:29], v[26:27]
	v_mov_b32_e32 v18, v11
	v_add_f32_e32 v10, v44, v26
	v_add_f32_e32 v28, v10, v27
	v_and_b32_e32 v27, 0xffff0000, v41
	v_and_b32_e32 v26, 0xffff0000, v37
	v_pk_mul_f32 v[10:11], v[18:19], v[26:27]
	v_mov_b32_e32 v18, v12
	v_add_f32_e32 v10, v42, v10
	v_add_f32_e32 v26, v10, v11
	v_lshlrev_b32_e32 v11, 16, v40
	v_lshlrev_b32_e32 v10, 16, v36
	v_mov_b32_e32 v19, v20
	v_pk_mul_f32 v[10:11], v[18:19], v[10:11]
	v_mov_b32_e32 v20, v13
	v_add_f32_e32 v10, v43, v10
	v_add_f32_e32 v18, v10, v11
	v_and_b32_e32 v11, 0xffff0000, v40
	v_and_b32_e32 v10, 0xffff0000, v36
	v_pk_mul_f32 v[10:11], v[20:21], v[10:11]
	v_mov_b32_e32 v12, v14
	v_add_f32_e32 v10, v45, v10
	v_add_f32_e32 v19, v10, v11
	v_lshlrev_b32_e32 v11, 16, v39
	v_lshlrev_b32_e32 v10, 16, v35
	s_waitcnt lgkmcnt(0)
	v_mov_b32_e32 v13, v22
	v_pk_mul_f32 v[10:11], v[12:13], v[10:11]
	v_mov_b32_e32 v22, v15
	v_add_f32_e32 v10, v30, v10
	v_add_f32_e32 v14, v10, v11
	v_and_b32_e32 v11, 0xffff0000, v39
	v_and_b32_e32 v10, 0xffff0000, v35
	v_pk_mul_f32 v[10:11], v[22:23], v[10:11]
	v_mov_b32_e32 v12, v16
	v_add_f32_e32 v10, v31, v10
	v_add_f32_e32 v15, v10, v11
	v_lshlrev_b32_e32 v11, 16, v38
	v_lshlrev_b32_e32 v10, 16, v34
	v_mov_b32_e32 v13, v24
	v_pk_mul_f32 v[10:11], v[12:13], v[10:11]
	v_mov_b32_e32 v24, v17
	v_add_f32_e32 v10, v32, v10
	v_add_f32_e32 v12, v10, v11
	v_and_b32_e32 v11, 0xffff0000, v38
	v_and_b32_e32 v10, 0xffff0000, v34
	v_pk_mul_f32 v[10:11], v[24:25], v[10:11]
	v_cvt_pk_bf16_f32 v68, v28, v26
	v_cvt_pk_bf16_f32 v69, v18, v19
	v_cvt_pk_bf16_f32 v70, v14, v15
	s_nop 0
	v_add_f32_e32 v10, v33, v10
	v_add_f32_e32 v10, v10, v11
	v_cvt_pk_bf16_f32 v71, v12, v10
	ds_read_b128 v[26:29], v9 offset:10624
	ds_read_b128 v[30:33], v9 offset:10640
	s_waitcnt vmcnt(4)
	v_cndmask_b32_e32 v46, 0, v181, vcc
	v_cndmask_b32_e32 v47, 0, v180, vcc
	v_cndmask_b32_e32 v72, 0, v179, vcc
	v_cndmask_b32_e32 v73, 0, v178, vcc
	ds_read_b128 v[10:13], v9 offset:8576
	ds_read_b128 v[34:37], v9 offset:8592
	s_waitcnt vmcnt(4)
	v_cndmask_b32_e64 v74, 0, v185, s[0:1]
	v_cndmask_b32_e64 v75, 0, v184, s[0:1]
	v_cndmask_b32_e64 v76, 0, v183, s[0:1]
	v_cndmask_b32_e64 v77, 0, v182, s[0:1]
	ds_read_b128 v[14:17], v9 offset:9088
	ds_read_b128 v[38:41], v9 offset:9104
	v_lshlrev_b32_e32 v43, 16, v77
	v_lshlrev_b32_e32 v42, 16, v73
	s_waitcnt lgkmcnt(3)
	v_mov_b32_e32 v44, v10
	s_waitcnt lgkmcnt(1)
	v_mov_b32_e32 v45, v14
	v_pk_mul_f32 v[42:43], v[44:45], v[42:43]
	v_mov_b32_e32 v14, v11
	v_add_f32_e32 v10, v26, v42
	v_add_f32_e32 v44, v10, v43
	v_and_b32_e32 v43, 0xffff0000, v77
	v_and_b32_e32 v42, 0xffff0000, v73
	v_pk_mul_f32 v[10:11], v[14:15], v[42:43]
	v_mov_b32_e32 v14, v12
	v_add_f32_e32 v10, v27, v10
	v_add_f32_e32 v42, v10, v11
	v_lshlrev_b32_e32 v11, 16, v76
	v_lshlrev_b32_e32 v10, 16, v72
	v_mov_b32_e32 v15, v16
	v_pk_mul_f32 v[10:11], v[14:15], v[10:11]
	v_mov_b32_e32 v16, v13
	v_add_f32_e32 v10, v28, v10
	v_add_f32_e32 v43, v10, v11
	v_and_b32_e32 v11, 0xffff0000, v76
	v_and_b32_e32 v10, 0xffff0000, v72
	v_pk_mul_f32 v[10:11], v[16:17], v[10:11]
	v_mov_b32_e32 v12, v34
	v_add_f32_e32 v10, v29, v10
	v_add_f32_e32 v45, v10, v11
	v_lshlrev_b32_e32 v11, 16, v75
	v_lshlrev_b32_e32 v10, 16, v47
	s_waitcnt lgkmcnt(0)
	v_mov_b32_e32 v13, v38
	v_pk_mul_f32 v[10:11], v[12:13], v[10:11]
	v_mov_b32_e32 v38, v35
	v_add_f32_e32 v10, v30, v10
	v_add_f32_e32 v30, v10, v11
	v_and_b32_e32 v11, 0xffff0000, v75
	v_and_b32_e32 v10, 0xffff0000, v47
	v_pk_mul_f32 v[10:11], v[38:39], v[10:11]
	v_mov_b32_e32 v12, v36
	v_add_f32_e32 v10, v31, v10
	v_add_f32_e32 v31, v10, v11
	v_lshlrev_b32_e32 v11, 16, v74
	v_lshlrev_b32_e32 v10, 16, v46
	v_mov_b32_e32 v13, v40
	v_pk_mul_f32 v[10:11], v[12:13], v[10:11]
	v_mov_b32_e32 v40, v37
	v_add_f32_e32 v10, v32, v10
	v_add_f32_e32 v32, v10, v11
	v_and_b32_e32 v11, 0xffff0000, v74
	v_and_b32_e32 v10, 0xffff0000, v46
	v_pk_mul_f32 v[10:11], v[40:41], v[10:11]
	s_waitcnt vmcnt(4)
	v_cndmask_b32_e64 v34, 0, v189, s[6:7]
	v_add_f32_e32 v10, v33, v10
	v_add_f32_e32 v33, v10, v11
	v_cndmask_b32_e64 v35, 0, v188, s[6:7]
	v_cndmask_b32_e64 v36, 0, v187, s[6:7]
	v_cndmask_b32_e64 v37, 0, v186, s[6:7]
	ds_read_b128 v[10:13], v9 offset:9600
	ds_read_b128 v[14:17], v9 offset:9616
	s_waitcnt vmcnt(4)
	v_cndmask_b32_e64 v38, 0, v193, s[4:5]
	v_cndmask_b32_e64 v39, 0, v192, s[4:5]
	v_cndmask_b32_e64 v40, 0, v191, s[4:5]
	v_cndmask_b32_e64 v41, 0, v190, s[4:5]
	ds_read_b128 v[18:21], v9 offset:10112
	ds_read_b128 v[22:25], v9 offset:10128
	v_lshlrev_b32_e32 v27, 16, v41
	v_lshlrev_b32_e32 v26, 16, v37
	s_waitcnt lgkmcnt(3)
	v_mov_b32_e32 v28, v10
	s_waitcnt lgkmcnt(1)
	v_mov_b32_e32 v29, v18
	v_pk_mul_f32 v[26:27], v[28:29], v[26:27]
	v_mov_b32_e32 v18, v11
	v_add_f32_e32 v10, v44, v26
	v_add_f32_e32 v28, v10, v27
	v_and_b32_e32 v27, 0xffff0000, v41
	v_and_b32_e32 v26, 0xffff0000, v37
	v_pk_mul_f32 v[10:11], v[18:19], v[26:27]
	v_mov_b32_e32 v18, v12
	v_add_f32_e32 v10, v42, v10
	v_add_f32_e32 v26, v10, v11
	v_lshlrev_b32_e32 v11, 16, v40
	v_lshlrev_b32_e32 v10, 16, v36
	v_mov_b32_e32 v19, v20
	v_pk_mul_f32 v[10:11], v[18:19], v[10:11]
	v_mov_b32_e32 v20, v13
	v_add_f32_e32 v10, v43, v10
	v_add_f32_e32 v18, v10, v11
	v_and_b32_e32 v11, 0xffff0000, v40
	v_and_b32_e32 v10, 0xffff0000, v36
	v_pk_mul_f32 v[10:11], v[20:21], v[10:11]
	v_mov_b32_e32 v12, v14
	v_add_f32_e32 v10, v45, v10
	v_add_f32_e32 v19, v10, v11
	v_lshlrev_b32_e32 v11, 16, v39
	v_lshlrev_b32_e32 v10, 16, v35
	s_waitcnt lgkmcnt(0)
	v_mov_b32_e32 v13, v22
	v_pk_mul_f32 v[10:11], v[12:13], v[10:11]
	v_mov_b32_e32 v22, v15
	v_add_f32_e32 v10, v30, v10
	v_add_f32_e32 v14, v10, v11
	v_and_b32_e32 v11, 0xffff0000, v39
	v_and_b32_e32 v10, 0xffff0000, v35
	v_pk_mul_f32 v[10:11], v[22:23], v[10:11]
	v_mov_b32_e32 v12, v16
	v_add_f32_e32 v10, v31, v10
	v_add_f32_e32 v15, v10, v11
	v_lshlrev_b32_e32 v11, 16, v38
	v_lshlrev_b32_e32 v10, 16, v34
	v_mov_b32_e32 v13, v24
	v_pk_mul_f32 v[10:11], v[12:13], v[10:11]
	v_mov_b32_e32 v24, v17
	v_add_f32_e32 v10, v32, v10
	v_add_f32_e32 v12, v10, v11
	v_and_b32_e32 v11, 0xffff0000, v38
	v_and_b32_e32 v10, 0xffff0000, v34
	v_pk_mul_f32 v[10:11], v[24:25], v[10:11]
	v_cvt_pk_bf16_f32 v72, v28, v26
	v_cvt_pk_bf16_f32 v73, v18, v19
	v_cvt_pk_bf16_f32 v74, v14, v15
	v_lshlrev_b32_e32 v38, 3, v93
	v_add_f32_e32 v10, v33, v10
	v_add_f32_e32 v10, v10, v11
	v_cvt_pk_bf16_f32 v75, v12, v10
	s_nop 0
	s_nop 0
	ds_read_b128 v[18:21], v9 offset:10688
	ds_read_b128 v[22:25], v9 offset:10704
	v_or_b32_e32 v39, 16, v38
	s_waitcnt vmcnt(0)
	v_cndmask_b32_e32 v40, 0, v197, vcc
	v_cndmask_b32_e32 v41, 0, v196, vcc
	v_cndmask_b32_e32 v42, 0, v195, vcc
	v_cndmask_b32_e32 v43, 0, v194, vcc
	ds_read_b128 v[10:13], v9 offset:8640
	ds_read_b128 v[26:29], v9 offset:8656
	s_waitcnt vmcnt(0)
	v_cndmask_b32_e64 v44, 0, v201, s[0:1]
	v_cndmask_b32_e64 v45, 0, v200, s[0:1]
	v_cndmask_b32_e64 v46, 0, v199, s[0:1]
	v_cndmask_b32_e64 v47, 0, v198, s[0:1]
	ds_read_b128 v[14:17], v9 offset:9152
	ds_read_b128 v[30:33], v9 offset:9168
	v_lshlrev_b32_e32 v35, 16, v47
	v_lshlrev_b32_e32 v34, 16, v43
	s_waitcnt lgkmcnt(3)
	v_mov_b32_e32 v36, v10
	s_waitcnt lgkmcnt(1)
	v_mov_b32_e32 v37, v14
	v_pk_mul_f32 v[34:35], v[36:37], v[34:35]
	v_mov_b32_e32 v14, v11
	v_add_f32_e32 v10, v18, v34
	v_add_f32_e32 v36, v10, v35
	v_and_b32_e32 v35, 0xffff0000, v47
	v_and_b32_e32 v34, 0xffff0000, v43
	v_pk_mul_f32 v[10:11], v[14:15], v[34:35]
	v_mov_b32_e32 v14, v12
	v_add_f32_e32 v10, v19, v10
	v_add_f32_e32 v34, v10, v11
	v_lshlrev_b32_e32 v11, 16, v46
	v_lshlrev_b32_e32 v10, 16, v42
	v_mov_b32_e32 v15, v16
	v_pk_mul_f32 v[10:11], v[14:15], v[10:11]
	v_mov_b32_e32 v16, v13
	v_add_f32_e32 v10, v20, v10
	v_add_f32_e32 v35, v10, v11
	v_and_b32_e32 v11, 0xffff0000, v46
	v_and_b32_e32 v10, 0xffff0000, v42
	v_pk_mul_f32 v[10:11], v[16:17], v[10:11]
	v_mov_b32_e32 v12, v26
	v_add_f32_e32 v10, v21, v10
	v_add_f32_e32 v37, v10, v11
	v_lshlrev_b32_e32 v11, 16, v45
	v_lshlrev_b32_e32 v10, 16, v41
	s_waitcnt lgkmcnt(0)
	v_mov_b32_e32 v13, v30
	v_pk_mul_f32 v[10:11], v[12:13], v[10:11]
	v_mov_b32_e32 v30, v27
	v_add_f32_e32 v10, v22, v10
	v_add_f32_e32 v22, v10, v11
	v_and_b32_e32 v11, 0xffff0000, v45
	v_and_b32_e32 v10, 0xffff0000, v41
	v_pk_mul_f32 v[10:11], v[30:31], v[10:11]
	v_mov_b32_e32 v12, v28
	v_add_f32_e32 v10, v23, v10
	v_add_f32_e32 v23, v10, v11
	v_lshlrev_b32_e32 v11, 16, v44
	v_lshlrev_b32_e32 v10, 16, v40
	v_mov_b32_e32 v13, v32
	v_pk_mul_f32 v[10:11], v[12:13], v[10:11]
	v_mov_b32_e32 v32, v29
	v_add_f32_e32 v10, v24, v10
	v_add_f32_e32 v24, v10, v11
	v_and_b32_e32 v11, 0xffff0000, v44
	v_and_b32_e32 v10, 0xffff0000, v40
	v_pk_mul_f32 v[10:11], v[32:33], v[10:11]
	s_waitcnt vmcnt(0)
	v_cndmask_b32_e64 v26, 0, v205, s[6:7]
	v_add_f32_e32 v10, v25, v10
	v_add_f32_e32 v25, v10, v11
	v_cndmask_b32_e64 v27, 0, v204, s[6:7]
	v_cndmask_b32_e64 v28, 0, v203, s[6:7]
	v_cndmask_b32_e64 v29, 0, v202, s[6:7]
	ds_read_b128 v[0:3], v9 offset:9664
	ds_read_b128 v[10:13], v9 offset:9680
	s_waitcnt vmcnt(0)
	v_cndmask_b32_e64 v30, 0, v209, s[4:5]
	v_cndmask_b32_e64 v31, 0, v208, s[4:5]
	v_cndmask_b32_e64 v32, 0, v207, s[4:5]
	v_cndmask_b32_e64 v33, 0, v206, s[4:5]
	ds_read_b128 v[4:7], v9 offset:10176
	ds_read_b128 v[14:17], v9 offset:10192
	v_lshlrev_b32_e32 v19, 16, v33
	v_lshlrev_b32_e32 v18, 16, v29
	s_waitcnt lgkmcnt(3)
	v_mov_b32_e32 v20, v0
	s_waitcnt lgkmcnt(1)
	v_mov_b32_e32 v21, v4
	v_pk_mul_f32 v[18:19], v[20:21], v[18:19]
	v_mov_b32_e32 v4, v1
	v_add_f32_e32 v0, v36, v18
	v_add_f32_e32 v9, v0, v19
	v_and_b32_e32 v19, 0xffff0000, v33
	v_and_b32_e32 v18, 0xffff0000, v29
	v_pk_mul_f32 v[0:1], v[4:5], v[18:19]
	v_mov_b32_e32 v4, v2
	v_add_f32_e32 v0, v34, v0
	v_add_f32_e32 v18, v0, v1
	v_lshlrev_b32_e32 v1, 16, v32
	v_lshlrev_b32_e32 v0, 16, v28
	v_mov_b32_e32 v5, v6
	v_pk_mul_f32 v[0:1], v[4:5], v[0:1]
	v_mov_b32_e32 v6, v3
	v_add_f32_e32 v0, v35, v0
	v_add_f32_e32 v4, v0, v1
	v_and_b32_e32 v1, 0xffff0000, v32
	v_and_b32_e32 v0, 0xffff0000, v28
	v_pk_mul_f32 v[0:1], v[6:7], v[0:1]
	v_mov_b32_e32 v2, v10
	v_add_f32_e32 v0, v37, v0
	v_add_f32_e32 v5, v0, v1
	v_lshlrev_b32_e32 v1, 16, v31
	v_lshlrev_b32_e32 v0, 16, v27
	s_waitcnt lgkmcnt(0)
	v_mov_b32_e32 v3, v14
	v_pk_mul_f32 v[0:1], v[2:3], v[0:1]
	v_mov_b32_e32 v14, v11
	v_add_f32_e32 v0, v22, v0
	v_add_f32_e32 v6, v0, v1
	v_and_b32_e32 v1, 0xffff0000, v31
	v_and_b32_e32 v0, 0xffff0000, v27
	v_pk_mul_f32 v[0:1], v[14:15], v[0:1]
	v_mov_b32_e32 v2, v12
	v_add_f32_e32 v0, v23, v0
	v_add_f32_e32 v7, v0, v1
	v_lshlrev_b32_e32 v1, 16, v30
	v_lshlrev_b32_e32 v0, 16, v26
	v_mov_b32_e32 v3, v16
	v_pk_mul_f32 v[0:1], v[2:3], v[0:1]
	v_mov_b32_e32 v16, v13
	v_add_f32_e32 v0, v24, v0
	v_add_f32_e32 v2, v0, v1
	v_and_b32_e32 v1, 0xffff0000, v30
	v_and_b32_e32 v0, 0xffff0000, v26
	v_pk_mul_f32 v[0:1], v[16:17], v[0:1]
	v_cvt_pk_bf16_f32 v76, v9, v18
	v_cvt_pk_bf16_f32 v77, v4, v5
	v_cvt_pk_bf16_f32 v78, v6, v7
	v_cmp_eq_u32_e32 vcc, v38, v94
	v_add_f32_e32 v0, v25, v0
	v_add_f32_e32 v0, v0, v1
	v_cvt_pk_bf16_f32 v79, v2, v0
	v_or_b32_e32 v2, 1, v38
	v_cndmask_b32_e32 v0, 0, v134, vcc
	v_or_b32_e32 v1, 2, v38
	v_cmp_eq_u32_e32 vcc, v2, v94
	v_or_b32_e32 v4, 3, v38
	v_or_b32_e32 v3, 4, v38
	v_cndmask_b32_e32 v2, 0, v134, vcc
	v_cmp_eq_u32_e32 vcc, v1, v94
	v_or_b32_e32 v5, 6, v38
	v_or_b32_e32 v6, 5, v38
	v_cndmask_b32_e32 v1, 0, v134, vcc
	v_cmp_eq_u32_e32 vcc, v4, v94
	v_or_b32_e32 v7, 7, v38
	v_or_b32_e32 v11, 17, v38
	v_cndmask_b32_e32 v4, 0, v134, vcc
	v_cmp_eq_u32_e32 vcc, v3, v94
	v_or_b32_e32 v10, 18, v38
	v_or_b32_e32 v13, 19, v38
	v_cndmask_b32_e32 v3, 0, v134, vcc
	v_cmp_eq_u32_e32 vcc, v5, v94
	v_or_b32_e32 v12, 20, v38
	v_or_b32_e32 v14, 22, v38
	v_cndmask_b32_e32 v5, 0, v134, vcc
	v_cmp_eq_u32_e32 vcc, v6, v94
	v_or_b32_e32 v15, 21, v38
	v_or_b32_e32 v16, 23, v38
	v_cndmask_b32_e32 v6, 0, v134, vcc
	v_cmp_eq_u32_e32 vcc, v7, v94
	v_and_b32_e32 v18, 64, v132
	v_xor_b32_e32 v17, 32, v132
	v_cndmask_b32_e32 v7, 0, v134, vcc
	v_cmp_eq_u32_e32 vcc, v39, v94
	v_add_u32_e32 v18, 64, v18
	s_lshl_b32 s4, s62, 8
	v_cndmask_b32_e32 v9, 0, v134, vcc
	v_cmp_eq_u32_e32 vcc, v11, v94
	s_add_i32 s4, s4, 16
	v_cmp_eq_u32_e64 s[0:1], 0, v93
	v_cndmask_b32_e32 v11, 0, v134, vcc
	v_cmp_eq_u32_e32 vcc, v10, v94
	v_lshl_add_u32 v139, v94, 3, s4
	v_perm_b32 v82, v6, v3, s83
	v_cndmask_b32_e32 v10, 0, v134, vcc
	v_cmp_eq_u32_e32 vcc, v13, v94
	v_perm_b32 v81, v4, v1, s83
	v_perm_b32 v83, v7, v5, s83
	v_cndmask_b32_e32 v13, 0, v134, vcc
	v_cmp_eq_u32_e32 vcc, v12, v94
	v_perm_b32 v80, v2, v0, s83
	v_perm_b32 v85, v13, v10, s83
	v_cndmask_b32_e32 v12, 0, v134, vcc
	v_cmp_eq_u32_e32 vcc, v14, v94
	v_perm_b32 v84, v11, v9, s83
	s_nop 0
	v_cndmask_b32_e32 v14, 0, v134, vcc
	v_cmp_eq_u32_e32 vcc, v15, v94
	s_nop 1
	v_cndmask_b32_e32 v15, 0, v134, vcc
	v_cmp_eq_u32_e32 vcc, v16, v94
	v_perm_b32 v86, v15, v12, s83
	s_nop 0
	v_cndmask_b32_e32 v16, 0, v134, vcc
	v_cmp_lt_i32_e32 vcc, v17, v18
	v_perm_b32 v87, v16, v14, s83
	s_nop 0
	v_cndmask_b32_e32 v17, v132, v17, vcc
	v_lshlrev_b32_e32 v140, 2, v17
	v_lshlrev_b32_e32 v175, 2, v91
	global_load_dword v172, v175, s[42:43]
	global_load_dword v173, v175, s[36:37]
	global_load_dword v174, v175, s[40:41]
	s_setprio 1
	v_xad_u32 v148, v88, v8, v95
	ds_read_b128 v[0:3], v148 offset:16384
	ds_read_b128 v[4:7], v148 offset:49152
	s_waitcnt lgkmcnt(1)
	v_mfma_f32_32x32x16_bf16 v[32:47], v[48:51], v[0:3], 0
	v_or_b32_e32 v0, 32, v88
	v_xad_u32 v150, v0, v8, v95
	s_waitcnt lgkmcnt(0)
	v_mfma_f32_32x32x16_bf16 v[16:31], v[48:51], v[4:7], 0
	ds_read_b128 v[0:3], v150 offset:16384
	ds_read_b128 v[4:7], v150 offset:49152
	s_waitcnt lgkmcnt(1)
	v_mfma_f32_32x32x16_bf16 v[32:47], v[52:55], v[0:3], v[32:47]
	v_or_b32_e32 v0, 64, v88
	v_xad_u32 v145, v0, v8, v95
	s_waitcnt lgkmcnt(0)
	v_mfma_f32_32x32x16_bf16 v[16:31], v[52:55], v[4:7], v[16:31]
	ds_read_b128 v[0:3], v145 offset:16384
	ds_read_b128 v[4:7], v145 offset:49152
	s_waitcnt lgkmcnt(1)
	v_mfma_f32_32x32x16_bf16 v[32:47], v[56:59], v[0:3], v[32:47]
	v_or_b32_e32 v0, 0x60, v88
	v_xad_u32 v149, v0, v8, v95
	s_waitcnt lgkmcnt(0)
	v_mfma_f32_32x32x16_bf16 v[16:31], v[56:59], v[4:7], v[16:31]
	ds_read_b128 v[0:3], v149 offset:16384
	ds_read_b128 v[4:7], v149 offset:49152
	s_waitcnt lgkmcnt(1)
	v_mfma_f32_32x32x16_bf16 v[32:47], v[60:63], v[0:3], v[32:47]
	v_or_b32_e32 v0, 0x80, v88
	v_xad_u32 v144, v0, v8, v95
	s_waitcnt lgkmcnt(0)
	v_mfma_f32_32x32x16_bf16 v[16:31], v[60:63], v[4:7], v[16:31]
	ds_read_b128 v[0:3], v144 offset:16384
	ds_read_b128 v[4:7], v144 offset:49152
	s_waitcnt lgkmcnt(1)
	v_mfma_f32_32x32x16_bf16 v[32:47], v[64:67], v[0:3], v[32:47]
	v_or_b32_e32 v0, 0xa0, v88
	v_xad_u32 v147, v0, v8, v95
	s_waitcnt lgkmcnt(0)
	v_mfma_f32_32x32x16_bf16 v[16:31], v[64:67], v[4:7], v[16:31]
	ds_read_b128 v[0:3], v147 offset:16384
	ds_read_b128 v[4:7], v147 offset:49152
	s_waitcnt lgkmcnt(1)
	v_mfma_f32_32x32x16_bf16 v[32:47], v[68:71], v[0:3], v[32:47]
	v_or_b32_e32 v0, 0xc0, v88
	v_xad_u32 v143, v0, v8, v95
	s_waitcnt lgkmcnt(0)
	v_mfma_f32_32x32x16_bf16 v[16:31], v[68:71], v[4:7], v[16:31]
	ds_read_b128 v[0:3], v143 offset:16384
	ds_read_b128 v[4:7], v143 offset:49152
	s_waitcnt lgkmcnt(1)
	v_mfma_f32_32x32x16_bf16 v[32:47], v[72:75], v[0:3], v[32:47]
	v_or_b32_e32 v0, 0xe0, v88
	v_xad_u32 v146, v0, v8, v95
	s_waitcnt lgkmcnt(0)
	v_mfma_f32_32x32x16_bf16 v[16:31], v[72:75], v[4:7], v[16:31]
	ds_read_b128 v[0:3], v146 offset:16384
	ds_read_b128 v[4:7], v146 offset:49152
	s_waitcnt lgkmcnt(1)
	v_mfma_f32_32x32x16_bf16 v[32:47], v[76:79], v[0:3], v[32:47]
	s_waitcnt lgkmcnt(0)
	v_mfma_f32_32x32x16_bf16 v[16:31], v[76:79], v[4:7], v[16:31]
	v_mfma_f32_32x32x16_bf16 v[0:15], v[48:51], v[80:83], 0
	v_mfma_f32_32x32x16_bf16 v[0:15], v[52:55], v[84:87], v[0:15]
	s_setprio 0
	v_lshlrev_b32_e32 v88, 2, v91
	s_waitcnt vmcnt(0)
	ds_read_b32 v251, v167
	v_mov_b32_e32 v97, v173
	v_mov_b32_e32 v96, v174
	v_add_f32_e32 v32, v32, v97
	v_add_f32_e32 v34, v34, v97
	v_add_f32_e32 v33, v33, v97
	v_add_f32_e32 v35, v35, v97
	v_mul_f32_e32 v32, 0xbfb8aa3b, v32
	v_mul_f32_e32 v34, 0xbfb8aa3b, v34
	v_add_f32_e32 v16, v16, v96
	v_add_f32_e32 v17, v17, v96
	v_mul_f32_e32 v33, 0xbfb8aa3b, v33
	v_mul_f32_e32 v35, 0xbfb8aa3b, v35
	v_exp_f32_e32 v32, v32
	v_exp_f32_e32 v34, v34
	v_mul_f32_e32 v16, 0xbfb8aa3b, v16
	v_mul_f32_e32 v17, 0xbfb8aa3b, v17
	v_exp_f32_e32 v33, v33
	v_exp_f32_e32 v107, v35
	v_exp_f32_e32 v91, v16
	v_exp_f32_e32 v98, v17
	v_add_f32_e32 v32, 1.0, v32
	v_add_f32_e32 v108, 1.0, v34
	v_add_f32_e32 v33, 1.0, v33
	v_rcp_f32_e32 v109, v32
	v_rcp_f32_e32 v111, v33
	v_add_f32_e32 v91, 1.0, v91
	v_rcp_f32_e32 v110, v91
	v_add_f32_e32 v98, 1.0, v98
	v_rcp_f32_e32 v112, v98
	v_add_f32_e32 v18, v18, v96
	v_mul_f32_e32 v18, 0xbfb8aa3b, v18
	v_exp_f32_e32 v18, v18
	v_add_f32_e32 v20, v20, v96
	v_add_f32_e32 v18, 1.0, v18
	v_mul_f32_e32 v20, 0xbfb8aa3b, v20
	v_exp_f32_e32 v20, v20
	v_add_f32_e32 v19, v19, v96
	v_mul_f32_e32 v19, 0xbfb8aa3b, v19
	v_exp_f32_e32 v19, v19
	v_add_f32_e32 v21, v21, v96
	s_waitcnt lgkmcnt(0)
	v_mov_b32_e32 v33, v251
	v_mul_f32_e32 v16, v109, v33
	v_mul_f32_e32 v16, 0x3fb8aa3b, v16
	v_exp_f32_e32 v32, v16
	v_mul_f32_e32 v17, v111, v33
	v_mul_f32_e32 v17, 0x3fb8aa3b, v17
	v_exp_f32_e32 v34, v17
	v_rcp_f32_e32 v16, v108
	v_rcp_f32_e32 v17, v18
	v_fma_f32 v18, -v32, v32, 1.0
	v_sqrt_f32_e32 v18, v18
	v_mul_f32_e32 v16, v16, v33
	v_mul_f32_e32 v16, 0x3fb8aa3b, v16
	v_add_f32_e32 v19, 1.0, v19
	v_mul_f32_e32 v18, v110, v18
	v_mul_f32_e32 v18, v0, v18
	v_exp_f32_e32 v0, v16
	v_add_f32_e32 v16, 1.0, v107
	v_rcp_f32_e32 v16, v16
	v_rcp_f32_e32 v19, v19
	v_fma_f32 v91, -v0, v0, 1.0
	v_sqrt_f32_e32 v91, v91
	v_mul_f32_e32 v16, v16, v33
	v_mul_f32_e32 v16, 0x3fb8aa3b, v16
	v_exp_f32_e32 v98, v16
	v_add_f32_e32 v16, v36, v97
	v_mul_f32_e32 v16, 0xbfb8aa3b, v16
	v_exp_f32_e32 v16, v16
	v_mul_f32_e32 v91, v17, v91
	v_add_f32_e32 v17, 1.0, v20
	v_fma_f32 v36, -v98, v98, 1.0
	v_add_f32_e32 v16, 1.0, v16
	v_rcp_f32_e32 v16, v16
	v_sqrt_f32_e32 v36, v36
	v_rcp_f32_e32 v17, v17
	v_mul_f32_e32 v21, 0xbfb8aa3b, v21
	v_mul_f32_e32 v16, v16, v33
	v_mul_f32_e32 v16, 0x3fb8aa3b, v16
	v_exp_f32_e32 v20, v16
	v_add_f32_e32 v16, v37, v97
	v_mul_f32_e32 v16, 0xbfb8aa3b, v16
	v_exp_f32_e32 v16, v16
	v_mul_f32_e32 v36, v19, v36
	v_fma_f32 v19, -v20, v20, 1.0
	v_sqrt_f32_e32 v19, v19
	v_add_f32_e32 v16, 1.0, v16
	v_rcp_f32_e32 v16, v16
	v_exp_f32_e32 v21, v21
	v_mul_f32_e32 v17, v17, v19
	v_mul_f32_e32 v19, v4, v17
	v_mul_f32_e32 v16, v16, v33
	v_mul_f32_e32 v16, 0x3fb8aa3b, v16
	v_exp_f32_e32 v37, v16
	v_add_f32_e32 v16, v38, v97
	v_mul_f32_e32 v16, 0xbfb8aa3b, v16
	v_exp_f32_e32 v16, v16
	v_add_f32_e32 v4, 1.0, v21
	v_add_f32_e32 v21, v22, v96
	v_mul_f32_e32 v21, 0xbfb8aa3b, v21
	v_add_f32_e32 v16, 1.0, v16
	v_rcp_f32_e32 v16, v16
	v_fma_f32 v17, -v37, v37, 1.0
	v_exp_f32_e32 v21, v21
	v_rcp_f32_e32 v4, v4
	v_mul_f32_e32 v16, v16, v33
	v_mul_f32_e32 v16, 0x3fb8aa3b, v16
	v_sqrt_f32_e32 v17, v17
	v_exp_f32_e32 v38, v16
	v_add_f32_e32 v16, 1.0, v21
	v_add_f32_e32 v21, v39, v97
	v_mul_f32_e32 v4, v4, v17
	v_fma_f32 v17, -v38, v38, 1.0
	v_mul_f32_e32 v21, 0xbfb8aa3b, v21
	v_rcp_f32_e32 v16, v16
	v_sqrt_f32_e32 v17, v17
	v_exp_f32_e32 v21, v21
	v_add_f32_e32 v22, v23, v96
	v_mul_f32_e32 v22, 0xbfb8aa3b, v22
	v_mul_f32_e32 v23, v16, v17
	v_add_f32_e32 v16, 1.0, v21
	v_rcp_f32_e32 v16, v16
	v_add_f32_e32 v21, v40, v97
	v_mul_f32_e32 v21, 0xbfb8aa3b, v21
	v_exp_f32_e32 v21, v21
	v_mul_f32_e32 v16, v16, v33
	v_mul_f32_e32 v16, 0x3fb8aa3b, v16
	v_exp_f32_e32 v39, v16
	v_add_f32_e32 v16, 1.0, v21
	v_rcp_f32_e32 v16, v16
	v_exp_f32_e32 v22, v22
	v_add_f32_e32 v21, v24, v96
	v_mul_f32_e32 v21, 0xbfb8aa3b, v21
	v_mul_f32_e32 v16, v16, v33
	v_add_f32_e32 v17, 1.0, v22
	v_fma_f32 v22, -v39, v39, 1.0
	v_mul_f32_e32 v16, 0x3fb8aa3b, v16
	v_sqrt_f32_e32 v24, v22
	v_exp_f32_e32 v22, v16
	v_add_f32_e32 v16, v41, v97
	v_mul_f32_e32 v16, 0xbfb8aa3b, v16
	v_exp_f32_e32 v16, v16
	v_exp_f32_e32 v21, v21
	v_fma_f32 v40, -v22, v22, 1.0
	v_rcp_f32_e32 v17, v17
	v_add_f32_e32 v16, 1.0, v16
	v_rcp_f32_e32 v16, v16
	v_add_f32_e32 v21, 1.0, v21
	v_rcp_f32_e32 v21, v21
	v_sqrt_f32_e32 v40, v40
	v_mul_f32_e32 v16, v16, v33
	v_mul_f32_e32 v16, 0x3fb8aa3b, v16
	v_mul_f32_e32 v24, v17, v24
	v_mul_f32_e32 v17, v21, v40
	v_exp_f32_e32 v40, v16
	v_add_f32_e32 v16, v42, v97
	v_add_f32_e32 v25, v25, v96
	v_mul_f32_e32 v16, 0xbfb8aa3b, v16
	v_mul_f32_e32 v25, 0xbfb8aa3b, v25
	v_exp_f32_e32 v16, v16
	v_exp_f32_e32 v25, v25
	v_fma_f32 v35, -v34, v34, 1.0
	v_sqrt_f32_e32 v35, v35
	v_add_f32_e32 v16, 1.0, v16
	v_add_f32_e32 v21, 1.0, v25
	v_rcp_f32_e32 v16, v16
	v_rcp_f32_e32 v25, v21
	v_fma_f32 v21, -v40, v40, 1.0
	v_sqrt_f32_e32 v41, v21
	v_add_f32_e32 v21, v26, v96
	v_mul_f32_e32 v16, v16, v33
	v_mul_f32_e32 v21, 0xbfb8aa3b, v21
	v_mul_f32_e32 v16, 0x3fb8aa3b, v16
	v_exp_f32_e32 v26, v21
	v_mul_f32_e32 v21, v8, v17
	v_mul_f32_e32 v8, v25, v41
	v_exp_f32_e32 v41, v16
	v_add_f32_e32 v16, v43, v97
	v_mul_f32_e32 v16, 0xbfb8aa3b, v16
	v_exp_f32_e32 v16, v16
	v_add_f32_e32 v17, 1.0, v26
	v_fma_f32 v25, -v41, v41, 1.0
	v_add_f32_e32 v26, v27, v96
	v_add_f32_e32 v16, 1.0, v16
	v_rcp_f32_e32 v16, v16
	v_rcp_f32_e32 v17, v17
	v_sqrt_f32_e32 v25, v25
	v_mul_f32_e32 v26, 0xbfb8aa3b, v26
	v_mul_f32_e32 v16, v16, v33
	v_exp_f32_e32 v26, v26
	v_mul_f32_e32 v16, 0x3fb8aa3b, v16
	v_exp_f32_e32 v99, v16
	v_mul_f32_e32 v100, v17, v25
	v_add_f32_e32 v25, v44, v97
	v_add_f32_e32 v16, 1.0, v26
	v_mul_f32_e32 v25, 0xbfb8aa3b, v25
	v_add_f32_e32 v26, v28, v96
	v_fma_f32 v17, -v99, v99, 1.0
	v_exp_f32_e32 v25, v25
	v_mul_f32_e32 v26, 0xbfb8aa3b, v26
	v_rcp_f32_e32 v16, v16
	v_sqrt_f32_e32 v17, v17
	v_exp_f32_e32 v26, v26
	v_add_f32_e32 v25, 1.0, v25
	v_rcp_f32_e32 v25, v25
	v_mul_f32_e32 v101, v16, v17
	v_add_f32_e32 v16, 1.0, v26
	v_add_f32_e32 v26, v29, v96
	v_mul_f32_e32 v26, 0xbfb8aa3b, v26
	v_exp_f32_e32 v26, v26
	v_rcp_f32_e32 v17, v16
	v_mul_f32_e32 v16, v25, v33
	v_add_f32_e32 v25, v45, v97
	v_mul_f32_e32 v25, 0xbfb8aa3b, v25
	v_exp_f32_e32 v25, v25
	v_add_f32_e32 v26, 1.0, v26
	v_rcp_f32_e32 v42, v26
	v_add_f32_e32 v26, v46, v97
	v_mul_f32_e32 v26, 0xbfb8aa3b, v26
	v_exp_f32_e32 v26, v26
	v_add_f32_e32 v25, 1.0, v25
	v_rcp_f32_e32 v25, v25
	v_add_f32_e32 v27, v30, v96
	v_mul_f32_e32 v27, 0xbfb8aa3b, v27
	v_exp_f32_e32 v27, v27
	v_add_f32_e32 v26, 1.0, v26
	v_rcp_f32_e32 v26, v26
	v_mul_f32_e32 v25, v25, v33
	v_mul_f32_e32 v25, 0x3fb8aa3b, v25
	v_exp_f32_e32 v43, v25
	v_add_f32_e32 v25, 1.0, v27
	v_rcp_f32_e32 v44, v25
	v_mul_f32_e32 v25, v26, v33
	v_add_f32_e32 v26, v47, v97
	v_mul_f32_e32 v26, 0xbfb8aa3b, v26
	v_exp_f32_e32 v26, v26
	v_add_f32_e32 v27, v31, v96
	v_mul_f32_e32 v27, 0xbfb8aa3b, v27
	v_exp_f32_e32 v27, v27
	v_add_f32_e32 v26, 1.0, v26
	v_mul_f32_e32 v16, 0x3fb8aa3b, v16
	v_rcp_f32_e32 v26, v26
	v_exp_f32_e32 v16, v16
	v_mul_f32_e32 v25, 0x3fb8aa3b, v25
	v_fmac_f32_e32 v18, 0, v32
	v_mul_f32_e32 v35, v112, v35
	v_exp_f32_e32 v45, v25
	v_add_f32_e32 v25, 1.0, v27
	v_mul_f32_e32 v31, v34, v18
	v_rcp_f32_e32 v46, v25
	v_mul_f32_e32 v25, v26, v33
	v_fmac_f32_e32 v31, v1, v35
	v_mul_f32_e32 v33, v32, v34
	v_mul_f32_e32 v30, v0, v31
	v_mul_f32_e32 v34, v0, v33
	v_fma_f32 v0, -v16, v16, 1.0
	v_sqrt_f32_e32 v1, v0
	v_mul_f32_e32 v25, 0x3fb8aa3b, v25
	v_fmac_f32_e32 v30, v2, v91
	v_fmac_f32_e32 v21, 0, v22
	v_fma_f32 v2, -v43, v43, 1.0
	v_exp_f32_e32 v47, v25
	v_mul_f32_e32 v25, v40, v21
	v_mov_b32_e32 v0, v89
	v_sqrt_f32_e32 v2, v2
	v_fmac_f32_e32 v25, v9, v8
	v_pk_mul_f32 v[8:9], v[16:17], v[0:1]
	v_mul_f32_e32 v29, v98, v30
	v_fmac_f32_e32 v19, 0, v20
	v_fmac_f32_e32 v8, v12, v9
	v_fmac_f32_e32 v29, v3, v36
	v_mul_f32_e32 v28, v37, v19
	v_mov_b32_e32 v3, v8
	v_fmac_f32_e32 v28, v5, v4
	v_pk_mul_f32 v[4:5], v[42:43], v[2:3]
	v_fma_f32 v0, -v45, v45, 1.0
	v_fmac_f32_e32 v5, v13, v4
	v_sqrt_f32_e32 v4, v0
	v_mul_f32_e32 v27, v38, v28
	v_fmac_f32_e32 v27, v6, v23
	v_mul_f32_e32 v26, v39, v27
	v_fmac_f32_e32 v26, v7, v24
	v_pk_mul_f32 v[6:7], v[44:45], v[4:5]
	v_fma_f32 v0, -v47, v47, 1.0
	v_fmac_f32_e32 v7, v14, v6
	v_sqrt_f32_e32 v6, v0
	ds_bpermute_b32 v0, v140, v29
	v_mul_f32_e32 v24, v41, v25
	v_mul_f32_e32 v35, v98, v34
	v_mul_f32_e32 v36, v20, v37
	v_fmac_f32_e32 v24, v10, v100
	v_mul_f32_e32 v37, v38, v36
	v_mul_f32_e32 v23, v99, v24
	ds_bpermute_b32 v13, v140, v35
	v_mul_f32_e32 v38, v39, v37
	v_fmac_f32_e32 v23, v11, v101
	v_pk_mul_f32 v[10:11], v[46:47], v[6:7]
	s_waitcnt lgkmcnt(1)
	v_cndmask_b32_e64 v14, v29, v0, s[0:1]
	v_fmac_f32_e32 v11, v15, v10
	v_cndmask_b32_e64 v10, v0, v29, s[0:1]
	ds_bpermute_b32 v0, v140, v38
	ds_bpermute_b32 v3, v140, v26
	v_mul_f32_e32 v39, v22, v40
	v_mul_f32_e32 v40, v41, v39
	s_waitcnt lgkmcnt(2)
	v_cndmask_b32_e64 v1, v13, v35, s[0:1]
	v_mul_f32_e32 v12, v99, v40
	v_mul_f32_e32 v9, v16, v43
	v_cndmask_b32_e64 v2, v35, v13, s[0:1]
	v_fmac_f32_e32 v10, 0, v1
	v_mul_f32_e32 v4, v45, v9
	v_mul_f32_e32 v15, v35, v13
	v_fmac_f32_e32 v14, v2, v10
	s_waitcnt lgkmcnt(1)
	v_cndmask_b32_e64 v1, v0, v38, s[0:1]
	s_waitcnt lgkmcnt(0)
	v_cndmask_b32_e64 v17, v3, v26, s[0:1]
	v_cndmask_b32_e64 v41, v26, v3, s[0:1]
	ds_bpermute_b32 v2, v140, v12
	ds_bpermute_b32 v3, v140, v23
	v_mul_f32_e32 v6, v47, v4
	v_cndmask_b32_e64 v0, v38, v0, s[0:1]
	v_mul_f32_e32 v42, v15, v1
	v_fmac_f32_e32 v17, v1, v14
	v_mul_f32_e32 v43, v0, v42
	v_fmac_f32_e32 v41, v0, v17
	ds_bpermute_b32 v1, v140, v6
	ds_bpermute_b32 v0, v140, v11
	s_waitcnt lgkmcnt(3)
	v_cndmask_b32_e64 v47, v2, v12, s[0:1]
	s_waitcnt lgkmcnt(2)
	v_cndmask_b32_e64 v44, v3, v23, s[0:1]
	v_cndmask_b32_e64 v2, v12, v2, s[0:1]
	v_cndmask_b32_e64 v45, v23, v3, s[0:1]
	v_mul_f32_e32 v46, v47, v43
	v_fmac_f32_e32 v44, v47, v41
	v_mul_f32_e32 v47, v2, v46
	v_fmac_f32_e32 v45, v2, v44
	s_waitcnt lgkmcnt(1)
	v_cndmask_b32_e64 v2, v1, v6, s[0:1]
	s_waitcnt lgkmcnt(0)
	v_cndmask_b32_e64 v91, v0, v11, s[0:1]
	v_mul_f32_e32 v96, v2, v47
	v_fmac_f32_e32 v91, v2, v45
	s_and_saveexec_b64 s[4:5], s[0:1]
	v_mul_f32_e32 v3, v91, v1
	v_mul_f32_e32 v2, v96, v1
	v_add_f32_e32 v3, v3, v0
	ds_write_b64 v139, v[2:3]
	s_or_b64 exec, exec, s[4:5]
	s_cmp_gt_i32 s62, 0
	s_cselect_b64 s[12:13], -1, 0
	s_cmp_lt_i32 s62, 1
	v_mul_i32_i24_e32 v141, 0xffffff08, v94
	s_waitcnt lgkmcnt(0)
	s_barrier
	s_cbranch_scc1 .LBB0_327
	s_cmp_lt_u32 s62, 8
	s_cbranch_scc1 .LBB0_328
	v_add_u32_e32 v95, v95, v141
	s_and_b32 s4, s62, 0x7ffffff8
	v_mov_b32_e32 v0, 1.0
	v_mov_b32_e32 v3, 0
	s_mov_b32 s5, 0

.LBB0_333:
	s_or_b64 exec, exec, s[6:7]
	s_setprio 1
	ds_read_b128 v[0:3], v148 offset:24576
	ds_read_b128 v[4:7], v148 offset:57344
	s_waitcnt lgkmcnt(1)
	v_mfma_f32_32x32x16_bf16 v[32:47], v[48:51], v[0:3], 0
	s_waitcnt lgkmcnt(0)
	v_mfma_f32_32x32x16_bf16 v[16:31], v[48:51], v[4:7], 0
	ds_read_b128 v[0:3], v150 offset:24576
	ds_read_b128 v[4:7], v150 offset:57344
	s_waitcnt lgkmcnt(1)
	v_mfma_f32_32x32x16_bf16 v[32:47], v[52:55], v[0:3], v[32:47]
	s_waitcnt lgkmcnt(0)
	v_mfma_f32_32x32x16_bf16 v[16:31], v[52:55], v[4:7], v[16:31]
	ds_read_b128 v[0:3], v145 offset:24576
	ds_read_b128 v[4:7], v145 offset:57344
	s_waitcnt lgkmcnt(1)
	v_mfma_f32_32x32x16_bf16 v[32:47], v[56:59], v[0:3], v[32:47]
	s_waitcnt lgkmcnt(0)
	v_mfma_f32_32x32x16_bf16 v[16:31], v[56:59], v[4:7], v[16:31]
	ds_read_b128 v[0:3], v149 offset:24576
	ds_read_b128 v[4:7], v149 offset:57344
	s_waitcnt lgkmcnt(1)
	v_mfma_f32_32x32x16_bf16 v[32:47], v[60:63], v[0:3], v[32:47]
	s_waitcnt lgkmcnt(0)
	v_mfma_f32_32x32x16_bf16 v[16:31], v[60:63], v[4:7], v[16:31]
	ds_read_b128 v[0:3], v144 offset:24576
	ds_read_b128 v[4:7], v144 offset:57344
	s_waitcnt lgkmcnt(1)
	v_mfma_f32_32x32x16_bf16 v[32:47], v[64:67], v[0:3], v[32:47]
	s_waitcnt lgkmcnt(0)
	v_mfma_f32_32x32x16_bf16 v[16:31], v[64:67], v[4:7], v[16:31]
	ds_read_b128 v[0:3], v147 offset:24576
	ds_read_b128 v[4:7], v147 offset:57344
	s_waitcnt lgkmcnt(1)
	v_mfma_f32_32x32x16_bf16 v[32:47], v[68:71], v[0:3], v[32:47]
	s_waitcnt lgkmcnt(0)
	v_mfma_f32_32x32x16_bf16 v[16:31], v[68:71], v[4:7], v[16:31]
	ds_read_b128 v[0:3], v143 offset:24576
	ds_read_b128 v[4:7], v143 offset:57344
	s_waitcnt lgkmcnt(1)
	v_mfma_f32_32x32x16_bf16 v[32:47], v[72:75], v[0:3], v[32:47]
	s_waitcnt lgkmcnt(0)
	v_mfma_f32_32x32x16_bf16 v[16:31], v[72:75], v[4:7], v[16:31]
	ds_read_b128 v[0:3], v146 offset:24576
	ds_read_b128 v[4:7], v146 offset:57344
	s_waitcnt lgkmcnt(1)
	v_mfma_f32_32x32x16_bf16 v[32:47], v[76:79], v[0:3], v[32:47]
	s_waitcnt lgkmcnt(0)
	v_mfma_f32_32x32x16_bf16 v[16:31], v[76:79], v[4:7], v[16:31]
	v_mfma_f32_32x32x16_bf16 v[0:15], v[56:59], v[80:83], 0
	v_mfma_f32_32x32x16_bf16 v[0:15], v[60:63], v[84:87], v[0:15]
	s_setprio 0
	s_waitcnt vmcnt(16)
	ds_read_b32 v251, v167 offset:128
	v_mov_b32_e32 v151, v173
	v_mov_b32_e32 v93, v174
	v_add_f32_e32 v32, v32, v151
	v_add_f32_e32 v34, v34, v151
	v_add_f32_e32 v33, v33, v151
	v_add_f32_e32 v35, v35, v151
	v_mul_f32_e32 v32, 0xbfb8aa3b, v32
	v_mul_f32_e32 v34, 0xbfb8aa3b, v34
	v_add_f32_e32 v16, v16, v93
	v_add_f32_e32 v17, v17, v93
	v_mul_f32_e32 v33, 0xbfb8aa3b, v33
	v_mul_f32_e32 v35, 0xbfb8aa3b, v35
	v_exp_f32_e32 v32, v32
	v_exp_f32_e32 v34, v34
	v_mul_f32_e32 v16, 0xbfb8aa3b, v16
	v_mul_f32_e32 v17, 0xbfb8aa3b, v17
	v_exp_f32_e32 v33, v33
	v_exp_f32_e32 v161, v35
	v_exp_f32_e32 v91, v16
	v_exp_f32_e32 v152, v17
	v_add_f32_e32 v32, 1.0, v32
	v_add_f32_e32 v162, 1.0, v34
	v_add_f32_e32 v33, 1.0, v33
	v_rcp_f32_e32 v163, v32
	v_rcp_f32_e32 v165, v33
	v_add_f32_e32 v91, 1.0, v91
	v_rcp_f32_e32 v164, v91
	v_add_f32_e32 v152, 1.0, v152
	v_rcp_f32_e32 v166, v152
	v_add_f32_e32 v18, v18, v93
	v_mul_f32_e32 v18, 0xbfb8aa3b, v18
	v_exp_f32_e32 v18, v18
	v_add_f32_e32 v20, v20, v93
	v_add_f32_e32 v18, 1.0, v18
	v_mul_f32_e32 v20, 0xbfb8aa3b, v20
	v_exp_f32_e32 v20, v20
	v_add_f32_e32 v19, v19, v93
	v_mul_f32_e32 v19, 0xbfb8aa3b, v19
	v_exp_f32_e32 v19, v19
	v_add_f32_e32 v21, v21, v93
	s_waitcnt lgkmcnt(0)
	v_mov_b32_e32 v33, v251
	v_mul_f32_e32 v16, v163, v33
	v_mul_f32_e32 v16, 0x3fb8aa3b, v16
	v_exp_f32_e32 v32, v16
	v_mul_f32_e32 v17, v165, v33
	v_mul_f32_e32 v17, 0x3fb8aa3b, v17
	v_exp_f32_e32 v34, v17
	v_rcp_f32_e32 v16, v162
	v_rcp_f32_e32 v17, v18
	v_fma_f32 v18, -v32, v32, 1.0
	v_sqrt_f32_e32 v18, v18
	v_mul_f32_e32 v16, v16, v33
	v_mul_f32_e32 v16, 0x3fb8aa3b, v16
	v_add_f32_e32 v19, 1.0, v19
	v_mul_f32_e32 v18, v164, v18
	v_mul_f32_e32 v18, v0, v18
	v_exp_f32_e32 v0, v16
	v_add_f32_e32 v16, 1.0, v161
	v_rcp_f32_e32 v16, v16
	v_rcp_f32_e32 v19, v19
	v_fma_f32 v91, -v0, v0, 1.0
	v_sqrt_f32_e32 v91, v91
	v_mul_f32_e32 v16, v16, v33
	v_mul_f32_e32 v16, 0x3fb8aa3b, v16
	v_exp_f32_e32 v152, v16
	v_add_f32_e32 v16, v36, v151
	v_mul_f32_e32 v16, 0xbfb8aa3b, v16
	v_exp_f32_e32 v16, v16
	v_mul_f32_e32 v91, v17, v91
	v_add_f32_e32 v17, 1.0, v20
	v_fma_f32 v36, -v152, v152, 1.0
	v_add_f32_e32 v16, 1.0, v16
	v_rcp_f32_e32 v16, v16
	v_sqrt_f32_e32 v36, v36
	v_rcp_f32_e32 v17, v17
	v_mul_f32_e32 v21, 0xbfb8aa3b, v21
	v_mul_f32_e32 v16, v16, v33
	v_mul_f32_e32 v16, 0x3fb8aa3b, v16
	v_exp_f32_e32 v20, v16
	v_add_f32_e32 v16, v37, v151
	v_mul_f32_e32 v16, 0xbfb8aa3b, v16
	v_exp_f32_e32 v16, v16
	v_mul_f32_e32 v36, v19, v36
	v_fma_f32 v19, -v20, v20, 1.0
	v_sqrt_f32_e32 v19, v19
	v_add_f32_e32 v16, 1.0, v16
	v_rcp_f32_e32 v16, v16
	v_exp_f32_e32 v21, v21
	v_mul_f32_e32 v17, v17, v19
	v_mul_f32_e32 v19, v4, v17
	v_mul_f32_e32 v16, v16, v33
	v_mul_f32_e32 v16, 0x3fb8aa3b, v16
	v_exp_f32_e32 v37, v16
	v_add_f32_e32 v16, v38, v151
	v_mul_f32_e32 v16, 0xbfb8aa3b, v16
	v_exp_f32_e32 v16, v16
	v_add_f32_e32 v4, 1.0, v21
	v_add_f32_e32 v21, v22, v93
	v_mul_f32_e32 v21, 0xbfb8aa3b, v21
	v_add_f32_e32 v16, 1.0, v16
	v_rcp_f32_e32 v16, v16
	v_fma_f32 v17, -v37, v37, 1.0
	v_exp_f32_e32 v21, v21
	v_rcp_f32_e32 v4, v4
	v_mul_f32_e32 v16, v16, v33
	v_mul_f32_e32 v16, 0x3fb8aa3b, v16
	v_sqrt_f32_e32 v17, v17
	v_exp_f32_e32 v38, v16
	v_add_f32_e32 v16, 1.0, v21
	v_add_f32_e32 v21, v39, v151
	v_mul_f32_e32 v4, v4, v17
	v_fma_f32 v17, -v38, v38, 1.0
	v_mul_f32_e32 v21, 0xbfb8aa3b, v21
	v_rcp_f32_e32 v16, v16
	v_sqrt_f32_e32 v17, v17
	v_exp_f32_e32 v21, v21
	v_add_f32_e32 v22, v23, v93
	v_mul_f32_e32 v22, 0xbfb8aa3b, v22
	v_mul_f32_e32 v23, v16, v17
	v_add_f32_e32 v16, 1.0, v21
	v_rcp_f32_e32 v16, v16
	v_add_f32_e32 v21, v40, v151
	v_mul_f32_e32 v21, 0xbfb8aa3b, v21
	v_exp_f32_e32 v21, v21
	v_mul_f32_e32 v16, v16, v33
	v_mul_f32_e32 v16, 0x3fb8aa3b, v16
	v_exp_f32_e32 v39, v16
	v_add_f32_e32 v16, 1.0, v21
	v_rcp_f32_e32 v16, v16
	v_exp_f32_e32 v22, v22
	v_add_f32_e32 v21, v24, v93
	v_mul_f32_e32 v21, 0xbfb8aa3b, v21
	v_mul_f32_e32 v16, v16, v33
	v_add_f32_e32 v17, 1.0, v22
	v_fma_f32 v22, -v39, v39, 1.0
	v_mul_f32_e32 v16, 0x3fb8aa3b, v16
	v_sqrt_f32_e32 v24, v22
	v_exp_f32_e32 v22, v16
	v_add_f32_e32 v16, v41, v151
	v_mul_f32_e32 v16, 0xbfb8aa3b, v16
	v_exp_f32_e32 v16, v16
	v_exp_f32_e32 v21, v21
	v_fma_f32 v40, -v22, v22, 1.0
	v_rcp_f32_e32 v17, v17
	v_add_f32_e32 v16, 1.0, v16
	v_rcp_f32_e32 v16, v16
	v_add_f32_e32 v21, 1.0, v21
	v_rcp_f32_e32 v21, v21
	v_sqrt_f32_e32 v40, v40
	v_mul_f32_e32 v16, v16, v33
	v_mul_f32_e32 v16, 0x3fb8aa3b, v16
	v_mul_f32_e32 v24, v17, v24
	v_mul_f32_e32 v17, v21, v40
	v_exp_f32_e32 v40, v16
	v_add_f32_e32 v16, v42, v151
	v_add_f32_e32 v25, v25, v93
	v_mul_f32_e32 v16, 0xbfb8aa3b, v16
	v_mul_f32_e32 v25, 0xbfb8aa3b, v25
	v_exp_f32_e32 v16, v16
	v_exp_f32_e32 v25, v25
	v_fma_f32 v35, -v34, v34, 1.0
	v_sqrt_f32_e32 v35, v35
	v_add_f32_e32 v16, 1.0, v16
	v_add_f32_e32 v21, 1.0, v25
	v_rcp_f32_e32 v16, v16
	v_rcp_f32_e32 v25, v21
	v_fma_f32 v21, -v40, v40, 1.0
	v_sqrt_f32_e32 v41, v21
	v_add_f32_e32 v21, v26, v93
	v_mul_f32_e32 v16, v16, v33
	v_mul_f32_e32 v21, 0xbfb8aa3b, v21
	v_mul_f32_e32 v16, 0x3fb8aa3b, v16
	v_exp_f32_e32 v26, v21
	v_mul_f32_e32 v21, v8, v17
	v_mul_f32_e32 v8, v25, v41
	v_exp_f32_e32 v41, v16
	v_add_f32_e32 v16, v43, v151
	v_mul_f32_e32 v16, 0xbfb8aa3b, v16
	v_exp_f32_e32 v16, v16
	v_add_f32_e32 v17, 1.0, v26
	v_fma_f32 v25, -v41, v41, 1.0
	v_add_f32_e32 v26, v27, v93
	v_add_f32_e32 v16, 1.0, v16
	v_rcp_f32_e32 v16, v16
	v_rcp_f32_e32 v17, v17
	v_sqrt_f32_e32 v25, v25
	v_mul_f32_e32 v26, 0xbfb8aa3b, v26
	v_mul_f32_e32 v16, v16, v33
	v_exp_f32_e32 v26, v26
	v_mul_f32_e32 v16, 0x3fb8aa3b, v16
	v_exp_f32_e32 v153, v16
	v_mul_f32_e32 v154, v17, v25
	v_add_f32_e32 v25, v44, v151
	v_add_f32_e32 v16, 1.0, v26
	v_mul_f32_e32 v25, 0xbfb8aa3b, v25
	v_add_f32_e32 v26, v28, v93
	v_fma_f32 v17, -v153, v153, 1.0
	v_exp_f32_e32 v25, v25
	v_mul_f32_e32 v26, 0xbfb8aa3b, v26
	v_rcp_f32_e32 v16, v16
	v_sqrt_f32_e32 v17, v17
	v_exp_f32_e32 v26, v26
	v_add_f32_e32 v25, 1.0, v25
	v_rcp_f32_e32 v25, v25
	v_mul_f32_e32 v155, v16, v17
	v_add_f32_e32 v16, 1.0, v26
	v_add_f32_e32 v26, v29, v93
	v_mul_f32_e32 v26, 0xbfb8aa3b, v26
	v_exp_f32_e32 v26, v26
	v_rcp_f32_e32 v17, v16
	v_mul_f32_e32 v16, v25, v33
	v_add_f32_e32 v25, v45, v151
	v_mul_f32_e32 v25, 0xbfb8aa3b, v25
	v_exp_f32_e32 v25, v25
	v_add_f32_e32 v26, 1.0, v26
	v_rcp_f32_e32 v42, v26
	v_add_f32_e32 v26, v46, v151
	v_mul_f32_e32 v26, 0xbfb8aa3b, v26
	v_exp_f32_e32 v26, v26
	v_add_f32_e32 v25, 1.0, v25
	v_rcp_f32_e32 v25, v25
	v_add_f32_e32 v27, v30, v93
	v_mul_f32_e32 v27, 0xbfb8aa3b, v27
	v_exp_f32_e32 v27, v27
	v_add_f32_e32 v26, 1.0, v26
	v_rcp_f32_e32 v26, v26
	v_mul_f32_e32 v25, v25, v33
	v_mul_f32_e32 v25, 0x3fb8aa3b, v25
	v_exp_f32_e32 v43, v25
	v_add_f32_e32 v25, 1.0, v27
	v_rcp_f32_e32 v44, v25
	v_mul_f32_e32 v25, v26, v33
	v_add_f32_e32 v26, v47, v151
	v_mul_f32_e32 v26, 0xbfb8aa3b, v26
	v_exp_f32_e32 v26, v26
	v_add_f32_e32 v27, v31, v93
	v_mul_f32_e32 v27, 0xbfb8aa3b, v27
	v_exp_f32_e32 v27, v27
	v_add_f32_e32 v26, 1.0, v26
	v_mul_f32_e32 v16, 0x3fb8aa3b, v16
	v_rcp_f32_e32 v26, v26
	v_exp_f32_e32 v16, v16
	v_mul_f32_e32 v25, 0x3fb8aa3b, v25
	v_fmac_f32_e32 v18, 0, v32
	v_mul_f32_e32 v35, v166, v35
	v_exp_f32_e32 v45, v25
	v_add_f32_e32 v25, 1.0, v27
	v_mul_f32_e32 v31, v34, v18
	v_rcp_f32_e32 v46, v25
	v_mul_f32_e32 v25, v26, v33
	v_fmac_f32_e32 v31, v1, v35
	v_mul_f32_e32 v33, v32, v34
	v_fmac_f32_e32 v19, 0, v20
	v_mul_f32_e32 v30, v0, v31
	v_mul_f32_e32 v34, v0, v33
	v_mul_f32_e32 v28, v37, v19
	v_fma_f32 v0, -v16, v16, 1.0
	v_fmac_f32_e32 v28, v5, v4
	v_sqrt_f32_e32 v1, v0
	v_mul_f32_e32 v27, v38, v28
	v_fmac_f32_e32 v30, v2, v91
	v_fmac_f32_e32 v27, v6, v23
	v_fma_f32 v2, -v43, v43, 1.0
	v_mul_f32_e32 v26, v39, v27
	v_mov_b32_e32 v0, v89
	v_sqrt_f32_e32 v2, v2
	v_fmac_f32_e32 v26, v7, v24
	v_pk_mul_f32 v[6:7], v[16:17], v[0:1]
	v_mul_f32_e32 v29, v152, v30
	v_fmac_f32_e32 v6, v12, v7
	v_fmac_f32_e32 v29, v3, v36
	v_mov_b32_e32 v3, v6
	v_mul_f32_e32 v25, 0x3fb8aa3b, v25
	v_pk_mul_f32 v[4:5], v[42:43], v[2:3]
	v_fma_f32 v0, -v45, v45, 1.0
	v_exp_f32_e32 v47, v25
	v_fmac_f32_e32 v5, v13, v4
	v_sqrt_f32_e32 v4, v0
	v_fmac_f32_e32 v21, 0, v22
	v_mul_f32_e32 v25, v40, v21
	v_fmac_f32_e32 v25, v9, v8
	v_pk_mul_f32 v[8:9], v[44:45], v[4:5]
	v_fma_f32 v0, -v47, v47, 1.0
	v_fmac_f32_e32 v9, v14, v8
	v_sqrt_f32_e32 v8, v0
	ds_bpermute_b32 v0, v140, v29
	v_mul_f32_e32 v24, v41, v25
	v_mul_f32_e32 v35, v152, v34
	v_mul_f32_e32 v36, v20, v37
	v_fmac_f32_e32 v24, v10, v154
	v_mul_f32_e32 v37, v38, v36
	v_mul_f32_e32 v23, v153, v24
	ds_bpermute_b32 v13, v140, v35
	v_mul_f32_e32 v38, v39, v37
	v_fmac_f32_e32 v23, v11, v155
	v_pk_mul_f32 v[10:11], v[46:47], v[8:9]
	s_waitcnt lgkmcnt(1)
	v_cndmask_b32_e64 v14, v29, v0, s[0:1]
	v_fmac_f32_e32 v11, v15, v10
	v_cndmask_b32_e64 v10, v0, v29, s[0:1]
	ds_bpermute_b32 v0, v140, v38
	ds_bpermute_b32 v3, v140, v26
	v_mul_f32_e32 v39, v22, v40
	v_mul_f32_e32 v40, v41, v39
	s_waitcnt lgkmcnt(2)
	v_cndmask_b32_e64 v1, v13, v35, s[0:1]
	v_mul_f32_e32 v12, v153, v40
	v_mul_f32_e32 v7, v16, v43
	v_cndmask_b32_e64 v2, v35, v13, s[0:1]
	v_fmac_f32_e32 v10, 0, v1
	v_mul_f32_e32 v4, v45, v7
	v_mul_f32_e32 v15, v35, v13
	v_fmac_f32_e32 v14, v2, v10
	s_waitcnt lgkmcnt(1)
	v_cndmask_b32_e64 v1, v0, v38, s[0:1]
	s_waitcnt lgkmcnt(0)
	v_cndmask_b32_e64 v17, v3, v26, s[0:1]
	v_cndmask_b32_e64 v41, v26, v3, s[0:1]
	ds_bpermute_b32 v2, v140, v12
	ds_bpermute_b32 v3, v140, v23
	v_mul_f32_e32 v8, v47, v4
	v_cndmask_b32_e64 v0, v38, v0, s[0:1]
	v_mul_f32_e32 v42, v15, v1
	v_fmac_f32_e32 v17, v1, v14
	v_mul_f32_e32 v43, v0, v42
	v_fmac_f32_e32 v41, v0, v17
	ds_bpermute_b32 v1, v140, v8
	ds_bpermute_b32 v0, v140, v11
	s_waitcnt lgkmcnt(3)
	v_cndmask_b32_e64 v47, v2, v12, s[0:1]
	s_waitcnt lgkmcnt(2)
	v_cndmask_b32_e64 v44, v3, v23, s[0:1]
	v_cndmask_b32_e64 v2, v12, v2, s[0:1]
	v_cndmask_b32_e64 v45, v23, v3, s[0:1]
	v_mul_f32_e32 v46, v47, v43
	v_fmac_f32_e32 v44, v47, v41
	v_mul_f32_e32 v47, v2, v46
	v_fmac_f32_e32 v45, v2, v44
	s_waitcnt lgkmcnt(1)
	v_cndmask_b32_e64 v2, v1, v8, s[0:1]
	s_waitcnt lgkmcnt(0)
	v_cndmask_b32_e64 v91, v0, v11, s[0:1]
	v_mul_f32_e32 v93, v2, v47
	v_fmac_f32_e32 v91, v2, v45
	s_and_saveexec_b64 s[6:7], s[0:1]
	v_mul_f32_e32 v3, v91, v1
	v_mul_f32_e32 v2, v93, v1
	v_add_f32_e32 v3, v3, v0
	ds_write_b64 v139, v[2:3] offset:2048
	s_or_b64 exec, exec, s[6:7]
	v_cndmask_b32_e64 v0, 0, 1, s[12:13]
	v_cmp_ne_u32_e64 s[6:7], 1, v0
	s_andn2_b64 vcc, exec, s[12:13]
	s_waitcnt lgkmcnt(0)
	s_barrier
	s_cbranch_vccnz .LBB0_340
	s_cmp_lt_u32 s62, 8
	s_cbranch_scc1 .LBB0_341
	s_add_i32 s9, 16, 0x800
	s_and_b32 s8, s62, 0x7ffffff8
	v_add3_u32 v151, v141, v138, s9
	v_mov_b32_e32 v0, 1.0
	v_mov_b32_e32 v3, 0
	s_mov_b32 s9, 0

.LBB0_346:
	s_or_b64 exec, exec, s[8:9]
	s_setprio 1
	ds_read_b128 v[0:3], v148 offset:32768
	ds_read_b128 v[4:7], v150 offset:32768
	v_add_u32_e32 v8, 0x8000, v150
	s_waitcnt lgkmcnt(1)
	v_mfma_f32_32x32x16_bf16 v[16:31], v[48:51], v[0:3], 0
	v_add_u32_e32 v0, 0x8000, v148
	ds_read_b128 v[0:3], v0 offset:32768
	ds_read_b128 v[8:11], v8 offset:32768
	s_waitcnt lgkmcnt(1)
	v_mfma_f32_32x32x16_bf16 v[32:47], v[48:51], v[0:3], 0
	v_mfma_f32_32x32x16_bf16 v[16:31], v[52:55], v[4:7], v[16:31]
	ds_read_b128 v[0:3], v145 offset:32768
	ds_read_b128 v[4:7], v149 offset:32768
	s_waitcnt lgkmcnt(2)
	v_mfma_f32_32x32x16_bf16 v[32:47], v[52:55], v[8:11], v[32:47]
	v_add_u32_e32 v8, 0x8000, v149
	ds_read_b128 v[8:11], v8 offset:32768
	s_waitcnt lgkmcnt(2)
	v_mfma_f32_32x32x16_bf16 v[16:31], v[56:59], v[0:3], v[16:31]
	v_add_u32_e32 v0, 0x8000, v145
	ds_read_b128 v[0:3], v0 offset:32768
	s_waitcnt lgkmcnt(0)
	v_mfma_f32_32x32x16_bf16 v[32:47], v[56:59], v[0:3], v[32:47]
	v_mfma_f32_32x32x16_bf16 v[16:31], v[60:63], v[4:7], v[16:31]
	ds_read_b128 v[0:3], v144 offset:32768
	ds_read_b128 v[4:7], v147 offset:32768
	v_mfma_f32_32x32x16_bf16 v[32:47], v[60:63], v[8:11], v[32:47]
	v_add_u32_e32 v8, 0x8000, v147
	ds_read_b128 v[8:11], v8 offset:32768
	s_waitcnt lgkmcnt(2)
	v_mfma_f32_32x32x16_bf16 v[16:31], v[64:67], v[0:3], v[16:31]
	v_add_u32_e32 v0, 0x8000, v144
	ds_read_b128 v[0:3], v0 offset:32768
	s_waitcnt lgkmcnt(0)
	v_mfma_f32_32x32x16_bf16 v[32:47], v[64:67], v[0:3], v[32:47]
	v_mfma_f32_32x32x16_bf16 v[16:31], v[68:71], v[4:7], v[16:31]
	ds_read_b128 v[0:3], v143 offset:32768
	ds_read_b128 v[4:7], v146 offset:32768
	v_mfma_f32_32x32x16_bf16 v[32:47], v[68:71], v[8:11], v[32:47]
	v_add_u32_e32 v8, 0x8000, v146
	ds_read_b128 v[8:11], v8 offset:32768
	s_waitcnt lgkmcnt(2)
	v_mfma_f32_32x32x16_bf16 v[16:31], v[72:75], v[0:3], v[16:31]
	v_add_u32_e32 v0, 0x8000, v143
	ds_read_b128 v[0:3], v0 offset:32768
	s_waitcnt lgkmcnt(0)
	v_mfma_f32_32x32x16_bf16 v[32:47], v[72:75], v[0:3], v[32:47]
	v_mfma_f32_32x32x16_bf16 v[16:31], v[76:79], v[4:7], v[16:31]
	v_mfma_f32_32x32x16_bf16 v[32:47], v[76:79], v[8:11], v[32:47]
	v_mfma_f32_32x32x16_bf16 v[0:15], v[64:67], v[80:83], 0
	v_mfma_f32_32x32x16_bf16 v[0:15], v[68:71], v[84:87], v[0:15]
	s_setprio 0
	s_waitcnt vmcnt(16)
	ds_read_b32 v251, v167 offset:256
	v_mov_b32_e32 v151, v173
	v_mov_b32_e32 v93, v174
	s_nop 0
	v_add_f32_e32 v18, v18, v151
	v_add_f32_e32 v19, v19, v151
	v_mul_f32_e32 v18, 0xbfb8aa3b, v18
	v_add_f32_e32 v16, v16, v151
	v_add_f32_e32 v32, v32, v93
	v_add_f32_e32 v17, v17, v151
	v_mul_f32_e32 v19, 0xbfb8aa3b, v19
	v_exp_f32_e32 v18, v18
	v_add_f32_e32 v33, v33, v93
	v_mul_f32_e32 v16, 0xbfb8aa3b, v16
	v_mul_f32_e32 v32, 0xbfb8aa3b, v32
	v_mul_f32_e32 v17, 0xbfb8aa3b, v17
	v_exp_f32_e32 v161, v19
	v_mul_f32_e32 v33, 0xbfb8aa3b, v33
	v_exp_f32_e32 v91, v16
	v_exp_f32_e32 v32, v32
	v_exp_f32_e32 v152, v17
	v_exp_f32_e32 v33, v33
	v_add_f32_e32 v162, 1.0, v18
	v_add_f32_e32 v32, 1.0, v32
	v_add_f32_e32 v91, 1.0, v91
	v_add_f32_e32 v33, 1.0, v33
	v_rcp_f32_e32 v164, v32
	v_rcp_f32_e32 v163, v91
	v_rcp_f32_e32 v166, v33
	v_add_f32_e32 v152, 1.0, v152
	v_rcp_f32_e32 v165, v152
	v_add_f32_e32 v34, v34, v93
	v_mul_f32_e32 v34, 0xbfb8aa3b, v34
	v_exp_f32_e32 v34, v34
	v_add_f32_e32 v36, v36, v93
	v_add_f32_e32 v34, 1.0, v34
	v_mul_f32_e32 v36, 0xbfb8aa3b, v36
	v_exp_f32_e32 v36, v36
	s_nop 1
	s_nop 1
	s_waitcnt lgkmcnt(0)
	v_mov_b32_e32 v33, v251
	v_mul_f32_e32 v16, v163, v33
	v_mul_f32_e32 v16, 0x3fb8aa3b, v16
	v_exp_f32_e32 v32, v16
	v_rcp_f32_e32 v16, v162
	v_mul_f32_e32 v17, v165, v33
	v_mul_f32_e32 v17, 0x3fb8aa3b, v17
	v_fma_f32 v18, -v32, v32, 1.0
	v_sqrt_f32_e32 v18, v18
	v_mul_f32_e32 v16, v16, v33
	v_mul_f32_e32 v16, 0x3fb8aa3b, v16
	v_exp_f32_e32 v91, v17
	v_mul_f32_e32 v18, v164, v18
	v_mul_f32_e32 v18, v0, v18
	v_exp_f32_e32 v0, v16
	v_add_f32_e32 v16, 1.0, v161
	v_rcp_f32_e32 v16, v16
	v_fma_f32 v19, -v91, v91, 1.0
	v_sqrt_f32_e32 v19, v19
	v_rcp_f32_e32 v17, v34
	v_mul_f32_e32 v16, v16, v33
	v_mul_f32_e32 v16, 0x3fb8aa3b, v16
	v_exp_f32_e32 v152, v16
	v_add_f32_e32 v16, v20, v151
	v_mul_f32_e32 v16, 0xbfb8aa3b, v16
	v_mul_f32_e32 v34, v166, v19
	v_add_f32_e32 v19, v35, v93
	v_exp_f32_e32 v16, v16
	v_mul_f32_e32 v19, 0xbfb8aa3b, v19
	v_exp_f32_e32 v19, v19
	v_fma_f32 v20, -v152, v152, 1.0
	v_add_f32_e32 v16, 1.0, v16
	v_rcp_f32_e32 v16, v16
	v_add_f32_e32 v19, 1.0, v19
	v_rcp_f32_e32 v19, v19
	v_sqrt_f32_e32 v20, v20
	v_mul_f32_e32 v16, v16, v33
	v_mul_f32_e32 v16, 0x3fb8aa3b, v16
	v_fma_f32 v35, -v0, v0, 1.0
	v_mul_f32_e32 v153, v19, v20
	v_exp_f32_e32 v20, v16
	v_add_f32_e32 v16, v21, v151
	v_mul_f32_e32 v16, 0xbfb8aa3b, v16
	v_exp_f32_e32 v16, v16
	v_sqrt_f32_e32 v35, v35
	v_fma_f32 v19, -v20, v20, 1.0
	v_add_f32_e32 v21, v37, v93
	v_add_f32_e32 v16, 1.0, v16
	v_rcp_f32_e32 v16, v16
	v_mul_f32_e32 v35, v17, v35
	v_add_f32_e32 v17, 1.0, v36
	v_rcp_f32_e32 v17, v17
	v_mul_f32_e32 v16, v16, v33
	v_mul_f32_e32 v16, 0x3fb8aa3b, v16
	v_exp_f32_e32 v36, v16
	v_add_f32_e32 v16, v22, v151
	v_mul_f32_e32 v16, 0xbfb8aa3b, v16
	v_exp_f32_e32 v16, v16
	v_sqrt_f32_e32 v19, v19
	v_mul_f32_e32 v21, 0xbfb8aa3b, v21
	v_exp_f32_e32 v21, v21
	v_add_f32_e32 v16, 1.0, v16
	v_rcp_f32_e32 v16, v16
	v_mul_f32_e32 v17, v17, v19
	v_mul_f32_e32 v19, v4, v17
	v_add_f32_e32 v4, 1.0, v21
	v_add_f32_e32 v21, v38, v93
	v_mul_f32_e32 v21, 0xbfb8aa3b, v21
	v_mul_f32_e32 v16, v16, v33
	v_fma_f32 v17, -v36, v36, 1.0
	v_exp_f32_e32 v21, v21
	v_mul_f32_e32 v16, 0x3fb8aa3b, v16
	v_rcp_f32_e32 v4, v4
	v_sqrt_f32_e32 v17, v17
	v_exp_f32_e32 v37, v16
	v_add_f32_e32 v16, 1.0, v21
	v_add_f32_e32 v21, v23, v151
	v_mul_f32_e32 v4, v4, v17
	v_fma_f32 v17, -v37, v37, 1.0
	v_mul_f32_e32 v21, 0xbfb8aa3b, v21
	v_rcp_f32_e32 v16, v16
	v_sqrt_f32_e32 v17, v17
	v_exp_f32_e32 v21, v21
	v_add_f32_e32 v22, v39, v93
	v_mul_f32_e32 v22, 0xbfb8aa3b, v22
	v_mul_f32_e32 v23, v16, v17
	v_add_f32_e32 v16, 1.0, v21
	v_rcp_f32_e32 v16, v16
	v_add_f32_e32 v21, v24, v151
	v_mul_f32_e32 v21, 0xbfb8aa3b, v21
	v_exp_f32_e32 v21, v21
	v_mul_f32_e32 v16, v16, v33
	v_mul_f32_e32 v16, 0x3fb8aa3b, v16
	v_exp_f32_e32 v24, v16
	v_add_f32_e32 v16, 1.0, v21
	v_rcp_f32_e32 v16, v16
	v_exp_f32_e32 v22, v22
	v_add_f32_e32 v21, v40, v93
	v_mul_f32_e32 v21, 0xbfb8aa3b, v21
	v_mul_f32_e32 v16, v16, v33
	v_add_f32_e32 v17, 1.0, v22
	v_fma_f32 v22, -v24, v24, 1.0
	v_mul_f32_e32 v16, 0x3fb8aa3b, v16
	v_sqrt_f32_e32 v38, v22
	v_exp_f32_e32 v22, v16
	v_add_f32_e32 v16, v25, v151
	v_mul_f32_e32 v16, 0xbfb8aa3b, v16
	v_exp_f32_e32 v16, v16
	v_exp_f32_e32 v21, v21
	v_add_f32_e32 v39, v41, v93
	v_fma_f32 v25, -v22, v22, 1.0
	v_add_f32_e32 v16, 1.0, v16
	v_rcp_f32_e32 v16, v16
	v_add_f32_e32 v21, 1.0, v21
	v_mul_f32_e32 v39, 0xbfb8aa3b, v39
	v_rcp_f32_e32 v17, v17
	v_rcp_f32_e32 v21, v21
	v_sqrt_f32_e32 v25, v25
	v_exp_f32_e32 v39, v39
	v_mul_f32_e32 v16, v16, v33
	v_mul_f32_e32 v16, 0x3fb8aa3b, v16
	v_mul_f32_e32 v38, v17, v38
	v_mul_f32_e32 v17, v21, v25
	v_add_f32_e32 v21, 1.0, v39
	v_exp_f32_e32 v39, v16
	v_add_f32_e32 v16, v26, v151
	v_mul_f32_e32 v16, 0xbfb8aa3b, v16
	v_exp_f32_e32 v16, v16
	v_rcp_f32_e32 v25, v21
	v_fma_f32 v21, -v39, v39, 1.0
	v_sqrt_f32_e32 v26, v21
	v_add_f32_e32 v16, 1.0, v16
	v_add_f32_e32 v21, v42, v93
	v_rcp_f32_e32 v16, v16
	v_mul_f32_e32 v21, 0xbfb8aa3b, v21
	v_exp_f32_e32 v40, v21
	v_mul_f32_e32 v21, v8, v17
	v_mul_f32_e32 v16, v16, v33
	v_mul_f32_e32 v16, 0x3fb8aa3b, v16
	v_add_f32_e32 v17, 1.0, v40
	v_exp_f32_e32 v40, v16
	v_add_f32_e32 v16, v27, v151
	v_mul_f32_e32 v16, 0xbfb8aa3b, v16
	v_exp_f32_e32 v16, v16
	v_mul_f32_e32 v8, v25, v26
	v_fma_f32 v25, -v40, v40, 1.0
	v_add_f32_e32 v26, v43, v93
	v_add_f32_e32 v16, 1.0, v16
	v_rcp_f32_e32 v16, v16
	v_rcp_f32_e32 v17, v17
	v_sqrt_f32_e32 v25, v25
	v_mul_f32_e32 v26, 0xbfb8aa3b, v26
	v_mul_f32_e32 v16, v16, v33
	v_exp_f32_e32 v26, v26
	v_mul_f32_e32 v16, 0x3fb8aa3b, v16
	v_exp_f32_e32 v41, v16
	v_mul_f32_e32 v154, v17, v25
	v_add_f32_e32 v25, v28, v151
	v_add_f32_e32 v16, 1.0, v26
	v_mul_f32_e32 v25, 0xbfb8aa3b, v25
	v_add_f32_e32 v26, v44, v93
	v_fma_f32 v17, -v41, v41, 1.0
	v_exp_f32_e32 v25, v25
	v_mul_f32_e32 v26, 0xbfb8aa3b, v26
	v_rcp_f32_e32 v16, v16
	v_sqrt_f32_e32 v17, v17
	v_exp_f32_e32 v26, v26
	v_add_f32_e32 v25, 1.0, v25
	v_rcp_f32_e32 v25, v25
	v_mul_f32_e32 v155, v16, v17
	v_add_f32_e32 v16, 1.0, v26
	v_add_f32_e32 v26, v45, v93
	v_mul_f32_e32 v26, 0xbfb8aa3b, v26
	v_exp_f32_e32 v26, v26
	v_rcp_f32_e32 v17, v16
	v_mul_f32_e32 v16, v25, v33
	v_add_f32_e32 v25, v29, v151
	v_mul_f32_e32 v25, 0xbfb8aa3b, v25
	v_exp_f32_e32 v25, v25
	v_add_f32_e32 v26, 1.0, v26
	v_rcp_f32_e32 v42, v26
	v_add_f32_e32 v26, v30, v151
	v_mul_f32_e32 v26, 0xbfb8aa3b, v26
	v_exp_f32_e32 v26, v26
	v_add_f32_e32 v25, 1.0, v25
	v_rcp_f32_e32 v25, v25
	v_add_f32_e32 v27, v46, v93
	v_mul_f32_e32 v27, 0xbfb8aa3b, v27
	v_exp_f32_e32 v27, v27
	v_add_f32_e32 v26, 1.0, v26
	v_rcp_f32_e32 v26, v26
	v_mul_f32_e32 v25, v25, v33
	v_mul_f32_e32 v25, 0x3fb8aa3b, v25
	v_exp_f32_e32 v43, v25
	v_add_f32_e32 v25, 1.0, v27
	v_rcp_f32_e32 v44, v25
	v_mul_f32_e32 v25, v26, v33
	v_add_f32_e32 v26, v31, v151
	v_mul_f32_e32 v26, 0xbfb8aa3b, v26
	v_exp_f32_e32 v26, v26
	v_add_f32_e32 v27, v47, v93
	v_mul_f32_e32 v27, 0xbfb8aa3b, v27
	v_exp_f32_e32 v27, v27
	v_add_f32_e32 v26, 1.0, v26
	v_mul_f32_e32 v16, 0x3fb8aa3b, v16
	v_rcp_f32_e32 v26, v26
	v_exp_f32_e32 v16, v16
	v_mul_f32_e32 v25, 0x3fb8aa3b, v25
	v_fmac_f32_e32 v18, 0, v32
	v_exp_f32_e32 v45, v25
	v_add_f32_e32 v25, 1.0, v27
	v_mul_f32_e32 v31, v91, v18
	v_rcp_f32_e32 v46, v25
	v_mul_f32_e32 v25, v26, v33
	v_fmac_f32_e32 v31, v1, v34
	v_mul_f32_e32 v33, v32, v91
	v_fmac_f32_e32 v19, 0, v20
	v_mul_f32_e32 v30, v0, v31
	v_mul_f32_e32 v34, v0, v33
	v_mul_f32_e32 v28, v36, v19
	v_fma_f32 v0, -v16, v16, 1.0
	v_fmac_f32_e32 v28, v5, v4
	v_sqrt_f32_e32 v1, v0
	v_mul_f32_e32 v27, v37, v28
	v_fmac_f32_e32 v30, v2, v35
	v_fmac_f32_e32 v27, v6, v23
	v_fma_f32 v2, -v43, v43, 1.0
	v_mul_f32_e32 v26, v24, v27
	v_mov_b32_e32 v0, v89
	v_sqrt_f32_e32 v2, v2
	v_fmac_f32_e32 v26, v7, v38
	v_pk_mul_f32 v[6:7], v[16:17], v[0:1]
	v_mul_f32_e32 v29, v152, v30
	v_fmac_f32_e32 v6, v12, v7
	v_fmac_f32_e32 v29, v3, v153
	v_mov_b32_e32 v3, v6
	v_mul_f32_e32 v25, 0x3fb8aa3b, v25
	v_pk_mul_f32 v[4:5], v[42:43], v[2:3]
	v_fma_f32 v0, -v45, v45, 1.0
	v_exp_f32_e32 v47, v25
	v_fmac_f32_e32 v5, v13, v4
	v_sqrt_f32_e32 v4, v0
	v_fmac_f32_e32 v21, 0, v22
	v_mul_f32_e32 v25, v39, v21
	v_mul_f32_e32 v36, v20, v36
	v_fmac_f32_e32 v25, v9, v8
	v_pk_mul_f32 v[8:9], v[44:45], v[4:5]
	v_fma_f32 v0, -v47, v47, 1.0
	v_mul_f32_e32 v37, v37, v36
	v_fmac_f32_e32 v9, v14, v8
	v_sqrt_f32_e32 v8, v0
	ds_bpermute_b32 v0, v140, v29
	v_mul_f32_e32 v38, v24, v37
	v_mul_f32_e32 v24, v40, v25
	v_mul_f32_e32 v35, v152, v34
	v_fmac_f32_e32 v24, v10, v154
	v_mul_f32_e32 v23, v41, v24
	ds_bpermute_b32 v13, v140, v35
	v_fmac_f32_e32 v23, v11, v155
	v_pk_mul_f32 v[10:11], v[46:47], v[8:9]
	s_waitcnt lgkmcnt(1)
	v_cndmask_b32_e64 v14, v29, v0, s[0:1]
	v_fmac_f32_e32 v11, v15, v10
	v_cndmask_b32_e64 v10, v0, v29, s[0:1]
	ds_bpermute_b32 v0, v140, v38
	ds_bpermute_b32 v3, v140, v26
	v_mul_f32_e32 v39, v22, v39
	v_mul_f32_e32 v40, v40, v39
	s_waitcnt lgkmcnt(2)
	v_cndmask_b32_e64 v1, v13, v35, s[0:1]
	v_mul_f32_e32 v12, v41, v40
	v_mul_f32_e32 v7, v16, v43
	v_cndmask_b32_e64 v2, v35, v13, s[0:1]
	v_fmac_f32_e32 v10, 0, v1
	v_mul_f32_e32 v4, v45, v7
	v_mul_f32_e32 v15, v35, v13
	v_fmac_f32_e32 v14, v2, v10
	s_waitcnt lgkmcnt(1)
	v_cndmask_b32_e64 v1, v0, v38, s[0:1]
	s_waitcnt lgkmcnt(0)
	v_cndmask_b32_e64 v17, v3, v26, s[0:1]
	v_cndmask_b32_e64 v41, v26, v3, s[0:1]
	ds_bpermute_b32 v2, v140, v12
	ds_bpermute_b32 v3, v140, v23
	v_mul_f32_e32 v8, v47, v4
	v_cndmask_b32_e64 v0, v38, v0, s[0:1]
	v_mul_f32_e32 v42, v15, v1
	v_fmac_f32_e32 v17, v1, v14
	v_mul_f32_e32 v43, v0, v42
	v_fmac_f32_e32 v41, v0, v17
	ds_bpermute_b32 v1, v140, v8
	ds_bpermute_b32 v0, v140, v11
	s_waitcnt lgkmcnt(3)
	v_cndmask_b32_e64 v47, v2, v12, s[0:1]
	s_waitcnt lgkmcnt(2)
	v_cndmask_b32_e64 v44, v3, v23, s[0:1]
	v_cndmask_b32_e64 v2, v12, v2, s[0:1]
	v_cndmask_b32_e64 v45, v23, v3, s[0:1]
	v_mul_f32_e32 v46, v47, v43
	v_fmac_f32_e32 v44, v47, v41
	v_mul_f32_e32 v47, v2, v46
	v_fmac_f32_e32 v45, v2, v44
	s_waitcnt lgkmcnt(1)
	v_cndmask_b32_e64 v2, v1, v8, s[0:1]
	s_waitcnt lgkmcnt(0)
	v_cndmask_b32_e64 v91, v0, v11, s[0:1]
	v_mul_f32_e32 v93, v2, v47
	v_fmac_f32_e32 v91, v2, v45
	s_and_saveexec_b64 s[8:9], s[0:1]
	v_mul_f32_e32 v3, v91, v1
	v_mul_f32_e32 v2, v93, v1
	v_add_f32_e32 v3, v3, v0
	ds_write_b64 v139, v[2:3] offset:4096
	s_or_b64 exec, exec, s[8:9]
	s_and_b64 vcc, exec, s[6:7]
	s_waitcnt lgkmcnt(0)
	s_barrier
	s_cbranch_vccnz .LBB0_353
	s_cmp_lt_u32 s62, 8
	s_cbranch_scc1 .LBB0_354
	s_add_i32 s9, 16, 0x1000
	s_and_b32 s8, s62, 0x7ffffff8
	v_add3_u32 v151, v141, v138, s9
	v_mov_b32_e32 v0, 1.0
	v_mov_b32_e32 v3, 0
	s_mov_b32 s9, 0

.LBB0_359:
	s_or_b64 exec, exec, s[8:9]
	s_setprio 1
	ds_read_b128 v[0:3], v148 offset:40960
	ds_read_b128 v[4:7], v150 offset:40960
	v_add_u32_e32 v8, 0xa000, v150
	s_waitcnt lgkmcnt(1)
	v_mfma_f32_32x32x16_bf16 v[16:31], v[48:51], v[0:3], 0
	v_add_u32_e32 v0, 0xa000, v148
	ds_read_b128 v[0:3], v0 offset:32768
	ds_read_b128 v[8:11], v8 offset:32768
	s_waitcnt lgkmcnt(1)
	v_mfma_f32_32x32x16_bf16 v[32:47], v[48:51], v[0:3], 0
	v_mfma_f32_32x32x16_bf16 v[16:31], v[52:55], v[4:7], v[16:31]
	ds_read_b128 v[0:3], v145 offset:40960
	ds_read_b128 v[4:7], v149 offset:40960
	s_waitcnt lgkmcnt(2)
	v_mfma_f32_32x32x16_bf16 v[32:47], v[52:55], v[8:11], v[32:47]
	v_add_u32_e32 v8, 0xa000, v149
	ds_read_b128 v[8:11], v8 offset:32768
	s_waitcnt lgkmcnt(2)
	v_mfma_f32_32x32x16_bf16 v[16:31], v[56:59], v[0:3], v[16:31]
	v_add_u32_e32 v0, 0xa000, v145
	ds_read_b128 v[0:3], v0 offset:32768
	s_waitcnt lgkmcnt(0)
	v_mfma_f32_32x32x16_bf16 v[32:47], v[56:59], v[0:3], v[32:47]
	v_mfma_f32_32x32x16_bf16 v[16:31], v[60:63], v[4:7], v[16:31]
	ds_read_b128 v[0:3], v144 offset:40960
	ds_read_b128 v[4:7], v147 offset:40960
	v_mfma_f32_32x32x16_bf16 v[32:47], v[60:63], v[8:11], v[32:47]
	v_add_u32_e32 v8, 0xa000, v147
	ds_read_b128 v[8:11], v8 offset:32768
	s_waitcnt lgkmcnt(2)
	v_mfma_f32_32x32x16_bf16 v[16:31], v[64:67], v[0:3], v[16:31]
	v_add_u32_e32 v0, 0xa000, v144
	ds_read_b128 v[0:3], v0 offset:32768
	s_waitcnt lgkmcnt(0)
	v_mfma_f32_32x32x16_bf16 v[32:47], v[64:67], v[0:3], v[32:47]
	v_mfma_f32_32x32x16_bf16 v[16:31], v[68:71], v[4:7], v[16:31]
	ds_read_b128 v[0:3], v143 offset:40960
	ds_read_b128 v[4:7], v146 offset:40960
	v_mfma_f32_32x32x16_bf16 v[32:47], v[68:71], v[8:11], v[32:47]
	v_add_u32_e32 v8, 0xa000, v146
	ds_read_b128 v[8:11], v8 offset:32768
	s_waitcnt lgkmcnt(2)
	v_mfma_f32_32x32x16_bf16 v[16:31], v[72:75], v[0:3], v[16:31]
	v_add_u32_e32 v0, 0xa000, v143
	ds_read_b128 v[0:3], v0 offset:32768
	s_waitcnt lgkmcnt(0)
	v_mfma_f32_32x32x16_bf16 v[32:47], v[72:75], v[0:3], v[32:47]
	v_mfma_f32_32x32x16_bf16 v[16:31], v[76:79], v[4:7], v[16:31]
	v_mfma_f32_32x32x16_bf16 v[32:47], v[76:79], v[8:11], v[32:47]
	v_mfma_f32_32x32x16_bf16 v[0:15], v[72:75], v[80:83], 0
	v_mfma_f32_32x32x16_bf16 v[0:15], v[76:79], v[84:87], v[0:15]
	s_setprio 0
	s_waitcnt vmcnt(16)
	ds_read_b32 v251, v167 offset:384
	v_mov_b32_e32 v49, v173
	v_mov_b32_e32 v48, v174
	s_nop 0
	v_add_f32_e32 v18, v18, v49
	v_add_f32_e32 v19, v19, v49
	v_mul_f32_e32 v18, 0xbfb8aa3b, v18
	v_add_f32_e32 v16, v16, v49
	v_add_f32_e32 v32, v32, v48
	v_add_f32_e32 v17, v17, v49
	v_mul_f32_e32 v19, 0xbfb8aa3b, v19
	v_exp_f32_e32 v18, v18
	v_add_f32_e32 v33, v33, v48
	v_mul_f32_e32 v16, 0xbfb8aa3b, v16
	v_mul_f32_e32 v32, 0xbfb8aa3b, v32
	v_mul_f32_e32 v17, 0xbfb8aa3b, v17
	v_exp_f32_e32 v59, v19
	v_mul_f32_e32 v33, 0xbfb8aa3b, v33
	v_exp_f32_e32 v50, v16
	v_exp_f32_e32 v32, v32
	v_exp_f32_e32 v51, v17
	v_exp_f32_e32 v33, v33
	v_add_f32_e32 v60, 1.0, v18
	v_add_f32_e32 v32, 1.0, v32
	v_add_f32_e32 v50, 1.0, v50
	v_add_f32_e32 v33, 1.0, v33
	v_rcp_f32_e32 v62, v32
	v_rcp_f32_e32 v61, v50
	v_rcp_f32_e32 v64, v33
	v_add_f32_e32 v51, 1.0, v51
	v_rcp_f32_e32 v63, v51
	v_add_f32_e32 v34, v34, v48
	v_mul_f32_e32 v34, 0xbfb8aa3b, v34
	v_exp_f32_e32 v34, v34
	v_add_f32_e32 v36, v36, v48
	v_add_f32_e32 v34, 1.0, v34
	v_mul_f32_e32 v36, 0xbfb8aa3b, v36
	v_exp_f32_e32 v36, v36
	s_nop 1
	s_nop 1
	s_waitcnt lgkmcnt(0)
	v_mov_b32_e32 v33, v251
	v_mul_f32_e32 v16, v61, v33
	v_mul_f32_e32 v16, 0x3fb8aa3b, v16
	v_exp_f32_e32 v32, v16
	v_rcp_f32_e32 v16, v60
	v_mul_f32_e32 v17, v63, v33
	v_mul_f32_e32 v17, 0x3fb8aa3b, v17
	v_fma_f32 v18, -v32, v32, 1.0
	v_sqrt_f32_e32 v18, v18
	v_mul_f32_e32 v16, v16, v33
	v_mul_f32_e32 v16, 0x3fb8aa3b, v16
	v_exp_f32_e32 v50, v17
	v_mul_f32_e32 v18, v62, v18
	v_mul_f32_e32 v18, v0, v18
	v_exp_f32_e32 v0, v16
	v_add_f32_e32 v16, 1.0, v59
	v_rcp_f32_e32 v16, v16
	v_fma_f32 v19, -v50, v50, 1.0
	v_sqrt_f32_e32 v19, v19
	v_rcp_f32_e32 v17, v34
	v_mul_f32_e32 v16, v16, v33
	v_mul_f32_e32 v16, 0x3fb8aa3b, v16
	v_exp_f32_e32 v51, v16
	v_add_f32_e32 v16, v20, v49
	v_mul_f32_e32 v16, 0xbfb8aa3b, v16
	v_mul_f32_e32 v34, v64, v19
	v_add_f32_e32 v19, v35, v48
	v_exp_f32_e32 v16, v16
	v_mul_f32_e32 v19, 0xbfb8aa3b, v19
	v_exp_f32_e32 v19, v19
	v_fma_f32 v20, -v51, v51, 1.0
	v_add_f32_e32 v16, 1.0, v16
	v_rcp_f32_e32 v16, v16
	v_add_f32_e32 v19, 1.0, v19
	v_rcp_f32_e32 v19, v19
	v_sqrt_f32_e32 v20, v20
	v_mul_f32_e32 v16, v16, v33
	v_mul_f32_e32 v16, 0x3fb8aa3b, v16
	v_fma_f32 v35, -v0, v0, 1.0
	v_mul_f32_e32 v52, v19, v20
	v_exp_f32_e32 v20, v16
	v_add_f32_e32 v16, v21, v49
	v_mul_f32_e32 v16, 0xbfb8aa3b, v16
	v_exp_f32_e32 v16, v16
	v_sqrt_f32_e32 v35, v35
	v_fma_f32 v19, -v20, v20, 1.0
	v_add_f32_e32 v21, v37, v48
	v_add_f32_e32 v16, 1.0, v16
	v_rcp_f32_e32 v16, v16
	v_mul_f32_e32 v35, v17, v35
	v_add_f32_e32 v17, 1.0, v36
	v_rcp_f32_e32 v17, v17
	v_mul_f32_e32 v16, v16, v33
	v_mul_f32_e32 v16, 0x3fb8aa3b, v16
	v_exp_f32_e32 v36, v16
	v_add_f32_e32 v16, v22, v49
	v_mul_f32_e32 v16, 0xbfb8aa3b, v16
	v_exp_f32_e32 v16, v16
	v_sqrt_f32_e32 v19, v19
	v_mul_f32_e32 v21, 0xbfb8aa3b, v21
	v_exp_f32_e32 v21, v21
	v_add_f32_e32 v16, 1.0, v16
	v_rcp_f32_e32 v16, v16
	v_mul_f32_e32 v17, v17, v19
	v_mul_f32_e32 v19, v4, v17
	v_add_f32_e32 v4, 1.0, v21
	v_add_f32_e32 v21, v38, v48
	v_mul_f32_e32 v21, 0xbfb8aa3b, v21
	v_mul_f32_e32 v16, v16, v33
	v_fma_f32 v17, -v36, v36, 1.0
	v_exp_f32_e32 v21, v21
	v_mul_f32_e32 v16, 0x3fb8aa3b, v16
	v_rcp_f32_e32 v4, v4
	v_sqrt_f32_e32 v17, v17
	v_exp_f32_e32 v37, v16
	v_add_f32_e32 v16, 1.0, v21
	v_add_f32_e32 v21, v23, v49
	v_mul_f32_e32 v4, v4, v17
	v_fma_f32 v17, -v37, v37, 1.0
	v_mul_f32_e32 v21, 0xbfb8aa3b, v21
	v_rcp_f32_e32 v16, v16
	v_sqrt_f32_e32 v17, v17
	v_exp_f32_e32 v21, v21
	v_add_f32_e32 v22, v39, v48
	v_mul_f32_e32 v22, 0xbfb8aa3b, v22
	v_mul_f32_e32 v23, v16, v17
	v_add_f32_e32 v16, 1.0, v21
	v_rcp_f32_e32 v16, v16
	v_add_f32_e32 v21, v24, v49
	v_mul_f32_e32 v21, 0xbfb8aa3b, v21
	v_exp_f32_e32 v21, v21
	v_mul_f32_e32 v16, v16, v33
	v_mul_f32_e32 v16, 0x3fb8aa3b, v16
	v_exp_f32_e32 v24, v16
	v_add_f32_e32 v16, 1.0, v21
	v_rcp_f32_e32 v16, v16
	v_exp_f32_e32 v22, v22
	v_add_f32_e32 v21, v40, v48
	v_mul_f32_e32 v21, 0xbfb8aa3b, v21
	v_mul_f32_e32 v16, v16, v33
	v_add_f32_e32 v17, 1.0, v22
	v_fma_f32 v22, -v24, v24, 1.0
	v_mul_f32_e32 v16, 0x3fb8aa3b, v16
	v_sqrt_f32_e32 v38, v22
	v_exp_f32_e32 v22, v16
	v_add_f32_e32 v16, v25, v49
	v_mul_f32_e32 v16, 0xbfb8aa3b, v16
	v_exp_f32_e32 v16, v16
	v_exp_f32_e32 v21, v21
	v_add_f32_e32 v39, v41, v48
	v_fma_f32 v25, -v22, v22, 1.0
	v_add_f32_e32 v16, 1.0, v16
	v_rcp_f32_e32 v16, v16
	v_add_f32_e32 v21, 1.0, v21
	v_mul_f32_e32 v39, 0xbfb8aa3b, v39
	v_rcp_f32_e32 v17, v17
	v_rcp_f32_e32 v21, v21
	v_sqrt_f32_e32 v25, v25
	v_exp_f32_e32 v39, v39
	v_mul_f32_e32 v16, v16, v33
	v_mul_f32_e32 v16, 0x3fb8aa3b, v16
	v_mul_f32_e32 v38, v17, v38
	v_mul_f32_e32 v17, v21, v25
	v_add_f32_e32 v21, 1.0, v39
	v_exp_f32_e32 v39, v16
	v_add_f32_e32 v16, v26, v49
	v_mul_f32_e32 v16, 0xbfb8aa3b, v16
	v_exp_f32_e32 v16, v16
	v_rcp_f32_e32 v25, v21
	v_fma_f32 v21, -v39, v39, 1.0
	v_sqrt_f32_e32 v26, v21
	v_add_f32_e32 v16, 1.0, v16
	v_add_f32_e32 v21, v42, v48
	v_rcp_f32_e32 v16, v16
	v_mul_f32_e32 v21, 0xbfb8aa3b, v21
	v_exp_f32_e32 v40, v21
	v_mul_f32_e32 v21, v8, v17
	v_mul_f32_e32 v16, v16, v33
	v_mul_f32_e32 v16, 0x3fb8aa3b, v16
	v_add_f32_e32 v17, 1.0, v40
	v_exp_f32_e32 v40, v16
	v_add_f32_e32 v16, v27, v49
	v_mul_f32_e32 v16, 0xbfb8aa3b, v16
	v_exp_f32_e32 v16, v16
	v_mul_f32_e32 v8, v25, v26
	v_fma_f32 v25, -v40, v40, 1.0
	v_add_f32_e32 v26, v43, v48
	v_add_f32_e32 v16, 1.0, v16
	v_rcp_f32_e32 v16, v16
	v_rcp_f32_e32 v17, v17
	v_sqrt_f32_e32 v25, v25
	v_mul_f32_e32 v26, 0xbfb8aa3b, v26
	v_mul_f32_e32 v16, v16, v33
	v_exp_f32_e32 v26, v26
	v_mul_f32_e32 v16, 0x3fb8aa3b, v16
	v_exp_f32_e32 v41, v16
	v_mul_f32_e32 v53, v17, v25
	v_add_f32_e32 v25, v28, v49
	v_add_f32_e32 v16, 1.0, v26
	v_mul_f32_e32 v25, 0xbfb8aa3b, v25
	v_add_f32_e32 v26, v44, v48
	v_fma_f32 v17, -v41, v41, 1.0
	v_exp_f32_e32 v25, v25
	v_mul_f32_e32 v26, 0xbfb8aa3b, v26
	v_rcp_f32_e32 v16, v16
	v_sqrt_f32_e32 v17, v17
	v_exp_f32_e32 v26, v26
	v_add_f32_e32 v25, 1.0, v25
	v_rcp_f32_e32 v25, v25
	v_mul_f32_e32 v54, v16, v17
	v_add_f32_e32 v16, 1.0, v26
	v_add_f32_e32 v26, v45, v48
	v_mul_f32_e32 v26, 0xbfb8aa3b, v26
	v_exp_f32_e32 v26, v26
	v_rcp_f32_e32 v17, v16
	v_mul_f32_e32 v16, v25, v33
	v_add_f32_e32 v25, v29, v49
	v_mul_f32_e32 v25, 0xbfb8aa3b, v25
	v_exp_f32_e32 v25, v25
	v_add_f32_e32 v26, 1.0, v26
	v_rcp_f32_e32 v42, v26
	v_add_f32_e32 v26, v30, v49
	v_mul_f32_e32 v26, 0xbfb8aa3b, v26
	v_exp_f32_e32 v26, v26
	v_add_f32_e32 v25, 1.0, v25
	v_rcp_f32_e32 v25, v25
	v_add_f32_e32 v27, v46, v48
	v_mul_f32_e32 v27, 0xbfb8aa3b, v27
	v_exp_f32_e32 v27, v27
	v_add_f32_e32 v26, 1.0, v26
	v_rcp_f32_e32 v26, v26
	v_mul_f32_e32 v25, v25, v33
	v_mul_f32_e32 v25, 0x3fb8aa3b, v25
	v_exp_f32_e32 v43, v25
	v_add_f32_e32 v25, 1.0, v27
	v_rcp_f32_e32 v44, v25
	v_mul_f32_e32 v25, v26, v33
	v_add_f32_e32 v26, v31, v49
	v_mul_f32_e32 v26, 0xbfb8aa3b, v26
	v_exp_f32_e32 v26, v26
	v_add_f32_e32 v27, v47, v48
	v_mul_f32_e32 v27, 0xbfb8aa3b, v27
	v_exp_f32_e32 v27, v27
	v_add_f32_e32 v26, 1.0, v26
	v_mul_f32_e32 v16, 0x3fb8aa3b, v16
	v_rcp_f32_e32 v26, v26
	v_exp_f32_e32 v16, v16
	v_mul_f32_e32 v25, 0x3fb8aa3b, v25
	v_fmac_f32_e32 v18, 0, v32
	v_exp_f32_e32 v45, v25
	v_add_f32_e32 v25, 1.0, v27
	v_mul_f32_e32 v31, v50, v18
	v_rcp_f32_e32 v46, v25
	v_mul_f32_e32 v25, v26, v33
	v_fmac_f32_e32 v31, v1, v34
	v_mul_f32_e32 v33, v32, v50
	v_fmac_f32_e32 v19, 0, v20
	v_mul_f32_e32 v30, v0, v31
	v_mul_f32_e32 v34, v0, v33
	v_mul_f32_e32 v28, v36, v19
	v_fma_f32 v0, -v16, v16, 1.0
	v_fmac_f32_e32 v28, v5, v4
	v_sqrt_f32_e32 v1, v0
	v_mul_f32_e32 v27, v37, v28
	v_fmac_f32_e32 v30, v2, v35
	v_fmac_f32_e32 v27, v6, v23
	v_fma_f32 v2, -v43, v43, 1.0
	v_mul_f32_e32 v26, v24, v27
	v_mov_b32_e32 v0, v89
	v_sqrt_f32_e32 v2, v2
	v_fmac_f32_e32 v26, v7, v38
	v_pk_mul_f32 v[6:7], v[16:17], v[0:1]
	v_mul_f32_e32 v29, v51, v30
	v_fmac_f32_e32 v6, v12, v7
	v_fmac_f32_e32 v29, v3, v52
	v_mov_b32_e32 v3, v6
	v_mul_f32_e32 v25, 0x3fb8aa3b, v25
	v_pk_mul_f32 v[4:5], v[42:43], v[2:3]
	v_fma_f32 v0, -v45, v45, 1.0
	v_exp_f32_e32 v47, v25
	v_fmac_f32_e32 v5, v13, v4
	v_sqrt_f32_e32 v4, v0
	v_fmac_f32_e32 v21, 0, v22
	v_mul_f32_e32 v25, v39, v21
	v_mul_f32_e32 v36, v20, v36
	v_fmac_f32_e32 v25, v9, v8
	v_pk_mul_f32 v[8:9], v[44:45], v[4:5]
	v_fma_f32 v0, -v47, v47, 1.0
	v_mul_f32_e32 v37, v37, v36
	v_fmac_f32_e32 v9, v14, v8
	v_sqrt_f32_e32 v8, v0
	ds_bpermute_b32 v0, v140, v29
	v_mul_f32_e32 v38, v24, v37
	v_mul_f32_e32 v24, v40, v25
	v_mul_f32_e32 v35, v51, v34
	v_fmac_f32_e32 v24, v10, v53
	v_mul_f32_e32 v23, v41, v24
	ds_bpermute_b32 v13, v140, v35
	v_fmac_f32_e32 v23, v11, v54
	v_pk_mul_f32 v[10:11], v[46:47], v[8:9]
	s_waitcnt lgkmcnt(1)
	v_cndmask_b32_e64 v14, v29, v0, s[0:1]
	v_fmac_f32_e32 v11, v15, v10
	v_cndmask_b32_e64 v10, v0, v29, s[0:1]
	ds_bpermute_b32 v0, v140, v38
	ds_bpermute_b32 v3, v140, v26
	v_mul_f32_e32 v39, v22, v39
	v_mul_f32_e32 v40, v40, v39
	s_waitcnt lgkmcnt(2)
	v_cndmask_b32_e64 v1, v13, v35, s[0:1]
	v_mul_f32_e32 v12, v41, v40
	v_mul_f32_e32 v7, v16, v43
	v_cndmask_b32_e64 v2, v35, v13, s[0:1]
	v_fmac_f32_e32 v10, 0, v1
	v_mul_f32_e32 v4, v45, v7
	v_mul_f32_e32 v15, v35, v13
	v_fmac_f32_e32 v14, v2, v10
	s_waitcnt lgkmcnt(1)
	v_cndmask_b32_e64 v1, v0, v38, s[0:1]
	s_waitcnt lgkmcnt(0)
	v_cndmask_b32_e64 v17, v3, v26, s[0:1]
	v_cndmask_b32_e64 v41, v26, v3, s[0:1]
	ds_bpermute_b32 v2, v140, v12
	ds_bpermute_b32 v3, v140, v23
	v_mul_f32_e32 v8, v47, v4
	v_cndmask_b32_e64 v0, v38, v0, s[0:1]
	v_mul_f32_e32 v42, v15, v1
	v_fmac_f32_e32 v17, v1, v14
	v_mul_f32_e32 v43, v0, v42
	v_fmac_f32_e32 v41, v0, v17
	ds_bpermute_b32 v1, v140, v8
	ds_bpermute_b32 v0, v140, v11
	s_waitcnt lgkmcnt(3)
	v_cndmask_b32_e64 v47, v2, v12, s[0:1]
	s_waitcnt lgkmcnt(2)
	v_cndmask_b32_e64 v44, v3, v23, s[0:1]
	v_cndmask_b32_e64 v2, v12, v2, s[0:1]
	v_cndmask_b32_e64 v45, v23, v3, s[0:1]
	v_mul_f32_e32 v46, v47, v43
	v_fmac_f32_e32 v44, v47, v41
	v_mul_f32_e32 v47, v2, v46
	v_fmac_f32_e32 v45, v2, v44
	s_waitcnt lgkmcnt(1)
	v_cndmask_b32_e64 v2, v1, v8, s[0:1]
	s_waitcnt lgkmcnt(0)
	v_cndmask_b32_e64 v48, v0, v11, s[0:1]
	v_mul_f32_e32 v49, v2, v47
	v_fmac_f32_e32 v48, v2, v45
	s_and_saveexec_b64 s[8:9], s[0:1]
	v_mul_f32_e32 v3, v48, v1
	v_mul_f32_e32 v2, v49, v1
	v_add_f32_e32 v3, v3, v0
	ds_write_b64 v139, v[2:3] offset:6144
	s_or_b64 exec, exec, s[8:9]
	s_and_b64 vcc, exec, s[6:7]
	s_waitcnt lgkmcnt(0)
	s_barrier
	s_cbranch_vccnz .LBB0_366
	s_cmp_lt_u32 s62, 8
	s_cbranch_scc1 .LBB0_367
	s_and_b32 s6, s62, 0x7ffffff8
	v_add3_u32 v50, v141, v138, s88
	v_mov_b32_e32 v0, 1.0
	v_mov_b32_e32 v3, 0
	s_mov_b32 s7, 0
